# batched EpiQ/EpiKV epilogue loads, GEMM k-loop 2-step DMA lookahead, rows L2 warm-up, 4-deep scan prefetch, attention tile rewrite
# speedup vs baseline: 1.0228x; 1.0228x over previous
; __device__ __forceinline__ int opaque_tid() { int t = threadIdx.x; asm volatile("" : "+v"(t)); return t; }
; template <class Epi>
; __device__ __forceinline__ void gemm_tile(const bf16_t* A, int lda, const bf16_t* Bt, int ldb, int K, int m0, int n0, const Epi& epi, char* smem) {
;     const int tid = opaque_tid(), lane = tid & 63, wid = tid >> 6, wr = wid >> 1, wc = wid & 1, fr = lane & 15, fq = lane >> 4;
;     f32x4 acc[4][4];
; #pragma unroll
;     for (int m = 0; m < 4; ++m)
; #pragma unroll
;         for (int n = 0; n < 4; ++n) acc[m][n] = (f32x4){0.f, 0.f, 0.f, 0.f};
;     const int lr = lane >> 3;
;     const bf16_t* Ag[4]; const bf16_t* Bg[4];
; #pragma unroll
;     for (int i = 0; i < 4; ++i) {
;         const int r = (wid + 4 * i) * 8 + lr, lc = (lane & 7) ^ ((r >> 1) & 7);
;         Ag[i] = A + (size_t)(m0 + r) * lda + lc * 8; Bg[i] = Bt + (size_t)(n0 + r) * ldb + lc * 8;
;     }
;     const unsigned lds0 = (unsigned)(uintptr_t)smem;
;     const int rsw = (fr >> 1) & 7;
;     const int aofs = (wr * 64 + fr) * 128, bofs = 16384 + (wc * 64 + fr) * 128;
;     const int nk = K >> 6;
;     ...
;     G_ISSUE(0, 0)
;     asm volatile("s_waitcnt vmcnt(0)" ::: "memory");
;     __syncthreads();
.LBB0_99:
	s_waitcnt vmcnt(1)
	v_mov_b32_e32 v16, v109
	s_lshl_b32 s43, s35, 7
	v_ashrrev_i32_e32 v17, 6, v16
	v_bfe_u32 v18, v16, 3, 3
	v_lshlrev_b32_e32 v19, 3, v17
	s_waitcnt vmcnt(0)
	v_or_b32_e32 v20, v19, v18
	v_add_u32_e32 v2, s43, v20
	v_mov_b64_e32 v[0:1], s[28:29]
	s_movk_i32 s8, 0x1600
	v_lshrrev_b32_e32 v21, 1, v20
	v_mad_i64_i32 v[2:3], s[0:1], v2, s8, v[0:1]
	s_lshl_b32 s42, s34, 7
	v_xor_b32_e32 v4, v21, v16
	v_readlane_b32 s0, v251, 28
	v_lshlrev_b32_e32 v4, 4, v4
	v_add_u32_e32 v6, s42, v20
	v_readlane_b32 s1, v251, 29
	v_add_u32_e32 v10, 32, v20
	v_add_u32_e32 v14, 64, v20
	v_add_u32_e32 v20, 0x60, v20
	v_and_b32_e32 v104, 0x70, v4
	v_mov_b64_e32 v[4:5], s[0:1]
	v_add_u32_e32 v8, s43, v10
	v_add_u32_e32 v10, s42, v10
	v_add_u32_e32 v12, s43, v14
	v_add_u32_e32 v14, s42, v14
	v_add_u32_e32 v22, s43, v20
	v_add_u32_e32 v20, s42, v20
	v_mad_i64_i32 v[6:7], s[0:1], v6, s8, v[4:5]
	v_mad_i64_i32 v[8:9], s[0:1], v8, s8, v[0:1]
	v_mad_i64_i32 v[10:11], s[0:1], v10, s8, v[4:5]
	v_mad_i64_i32 v[12:13], s[0:1], v12, s8, v[0:1]
	v_mad_i64_i32 v[14:15], s[0:1], v14, s8, v[4:5]
	v_mad_i64_i32 v[0:1], s[0:1], v22, s8, v[0:1]
	v_mad_i64_i32 v[4:5], s[0:1], v20, s8, v[4:5]
	v_lshlrev_b32_e32 v84, 10, v17
	v_lshl_add_u64 v[2:3], v[2:3], 0, v[104:105]
	v_readfirstlane_b32 s0, v84
	s_mov_b32 m0, s0
	v_lshl_add_u64 v[6:7], v[6:7], 0, v[104:105]
	global_load_lds_dwordx4 v[2:3], off
	v_add_u32_e32 v2, 0x4000, v84
	v_lshl_add_u64 v[8:9], v[8:9], 0, v[104:105]
	v_readfirstlane_b32 s0, v2
	v_add_u32_e32 v2, 0x1000, v84
	s_mov_b32 m0, s0
	v_readfirstlane_b32 s0, v2
	v_add_u32_e32 v2, 0x5000, v84
	global_load_lds_dwordx4 v[6:7], off
	s_mov_b32 m0, s0
	v_readfirstlane_b32 s0, v2
	v_add_u32_e32 v2, 0x2000, v84
	v_lshl_add_u64 v[10:11], v[10:11], 0, v[104:105]
	global_load_lds_dwordx4 v[8:9], off
	s_mov_b32 m0, s0
	v_readfirstlane_b32 s0, v2
	v_add_u32_e32 v2, 0x6000, v84
	v_lshl_add_u64 v[12:13], v[12:13], 0, v[104:105]
	global_load_lds_dwordx4 v[10:11], off
	s_mov_b32 m0, s0
	v_readfirstlane_b32 s0, v2
	v_add_u32_e32 v2, 0x3000, v84
	v_lshl_add_u64 v[14:15], v[14:15], 0, v[104:105]
	global_load_lds_dwordx4 v[12:13], off
	s_mov_b32 m0, s0
	v_readfirstlane_b32 s0, v2
	v_lshl_add_u64 v[0:1], v[0:1], 0, v[104:105]
	global_load_lds_dwordx4 v[14:15], off
	s_mov_b32 m0, s0
	v_lshl_add_u64 v[4:5], v[4:5], 0, v[104:105]
	global_load_lds_dwordx4 v[0:1], off
	v_add_u32_e32 v0, 0x7000, v84
	v_and_b32_e32 v83, 15, v16
	v_readfirstlane_b32 s0, v0
	s_mov_b32 m0, s0
	v_bfe_u32 v81, v16, 4, 2
	global_load_lds_dwordx4 v[4:5], off
	v_lshrrev_b32_e32 v1, 1, v16
	v_bfe_u32 v2, v16, 1, 3
	v_ashrrev_i32_e32 v82, 7, v16
	v_and_b32_e32 v80, 1, v17
	v_lshlrev_b32_e32 v0, 7, v83
	v_bitop3_b32 v1, v81, v1, 7 bitop3:0x78
	v_bitop3_b32 v2, v81, v2, 4 bitop3:0x36
	v_lshl_or_b32 v3, v80, 13, v0
	v_lshl_or_b32 v0, v82, 13, v0
	v_lshlrev_b32_e32 v1, 4, v1
	v_lshlrev_b32_e32 v2, 4, v2
	v_or_b32_e32 v88, v0, v1
	v_or_b32_e32 v86, v0, v2
	v_or_b32_e32 v0, s43, v18
	v_or_b32_e32 v85, v3, v2
	v_add_u32_e32 v0, v0, v19
	v_bitop3_b32 v2, v21, 7, v16 bitop3:0x48
	v_or_b32_e32 v87, v3, v1
	v_mad_i64_i32 v[0:1], s[0:1], v0, s8, 0
	v_lshlrev_b32_e32 v2, 4, v2
	v_readlane_b32 s4, v252, 51
	v_or_b32_e32 v0, v0, v2
	v_readlane_b32 s5, v252, 52
	v_readlane_b32 s6, v252, 53
	v_readlane_b32 s7, v252, 54
	v_lshl_add_u64 v[64:65], s[4:5], 0, v[0:1]
	v_or_b32_e32 v0, s42, v18
	v_add_u32_e32 v0, v0, v19
	v_mad_i64_i32 v[0:1], s[0:1], v0, s8, 0
	v_or_b32_e32 v0, v0, v2
	v_or_b32_e32 v3, 32, v18
	v_lshl_add_u64 v[66:67], s[6:7], 0, v[0:1]
	v_or_b32_e32 v0, s43, v3
	v_add_u32_e32 v0, v0, v19
	v_mad_i64_i32 v[0:1], s[0:1], v0, s8, 0
	v_or_b32_e32 v0, v0, v2
	v_lshl_add_u64 v[68:69], s[4:5], 0, v[0:1]
	v_or_b32_e32 v0, s42, v3
	v_add_u32_e32 v0, v0, v19
	v_mad_i64_i32 v[0:1], s[0:1], v0, s8, 0
	v_or_b32_e32 v0, v0, v2
	v_or_b32_e32 v3, 64, v18
	v_lshl_add_u64 v[70:71], s[6:7], 0, v[0:1]
	v_or_b32_e32 v0, s43, v3
	v_add_u32_e32 v0, v0, v19
	v_mad_i64_i32 v[0:1], s[0:1], v0, s8, 0
	v_or_b32_e32 v0, v0, v2
	v_lshl_add_u64 v[72:73], s[4:5], 0, v[0:1]
	v_or_b32_e32 v0, s42, v3
	v_add_u32_e32 v0, v0, v19
	v_mad_i64_i32 v[0:1], s[0:1], v0, s8, 0
	v_or_b32_e32 v0, v0, v2
	v_or_b32_e32 v3, 0x60, v18
	v_lshl_add_u64 v[74:75], s[6:7], 0, v[0:1]
	v_or_b32_e32 v0, s43, v3
	v_add_u32_e32 v0, v0, v19
	v_mad_i64_i32 v[0:1], s[0:1], v0, s8, 0
	v_or_b32_e32 v0, v0, v2
	v_lshl_add_u64 v[76:77], s[4:5], 0, v[0:1]
	v_or_b32_e32 v0, s42, v3
	v_add_u32_e32 v0, v0, v19
	v_mad_i64_i32 v[0:1], s[0:1], v0, s8, 0
	s_waitcnt vmcnt(0)
; template <class Epi>
; __device__ __forceinline__ void gemm_tile(const bf16_t* A, int lda, const bf16_t* Bt, int ldb, int K, int m0, int n0, const Epi& epi, char* smem) {
;     ...
;     f32x4 acc[4][4];
; #pragma unroll
;     for (int m = 0; m < 4; ++m)
; #pragma unroll
;         for (int n = 0; n < 4; ++n) acc[m][n] = (f32x4){0.f, 0.f, 0.f, 0.f};
;     const int lr = lane >> 3;
;     const bf16_t* Ag[4]; const bf16_t* Bg[4];
; #pragma unroll
;     for (int i = 0; i < 4; ++i) {
;         const int r = (wid + 4 * i) * 8 + lr, lc = (lane & 7) ^ ((r >> 1) & 7);
;         Ag[i] = A + (size_t)(m0 + r) * lda + lc * 8; Bg[i] = Bt + (size_t)(n0 + r) * ldb + lc * 8;
;     }
;     const unsigned lds0 = (unsigned)(uintptr_t)smem;
;     const int rsw = (fr >> 1) & 7;
;     const int aofs = (wr * 64 + fr) * 128, bofs = 16384 + (wc * 64 + fr) * 128;
;     const int nk = K >> 6;
;     ...
;     G_ISSUE(0, 0)
;     asm volatile("s_waitcnt vmcnt(0)" ::: "memory");
;     __syncthreads();
;     for (int kt = 0; kt < nk; ++kt) {
;         const int st = (kt & 1) * 32768;
;         if (kt + 1 < nk) G_ISSUE(((kt + 1) & 1) * 32768, (kt + 1) * 64)
;         {
;             bf16x8 a0[4], b0[4], a1[4], b1[4];
;             const int ch0 = ((0 + fq) ^ rsw) << 4, ch1 = ((4 + fq) ^ rsw) << 4;
; #pragma unroll
;             for (int m = 0; m < 4; ++m) a0[m] = *(const bf16x8*)(smem + st + aofs + m * 2048 + ch0);
; #pragma unroll
;             for (int n = 0; n < 4; ++n) b0[n] = *(const bf16x8*)(smem + st + bofs + n * 2048 + ch0);
;             __builtin_amdgcn_sched_barrier(0);
; #pragma unroll
;             for (int m = 0; m < 4; ++m) a1[m] = *(const bf16x8*)(smem + st + aofs + m * 2048 + ch1);
; #pragma unroll
;             for (int n = 0; n < 4; ++n) b1[n] = *(const bf16x8*)(smem + st + bofs + n * 2048 + ch1);
;             __builtin_amdgcn_sched_barrier(0);
;             __builtin_amdgcn_s_setprio(1);
; #pragma unroll
;             for (int m = 0; m < 4; ++m)
; #pragma unroll
;                 for (int n = 0; n < 4; ++n) acc[m][n] = __builtin_amdgcn_mfma_f32_16x16x32_bf16(b0[n], a0[m], acc[m][n], 0, 0, 0);
;             __builtin_amdgcn_sched_barrier(0);
; #pragma unroll
;             for (int m = 0; m < 4; ++m)
; #pragma unroll
;                 for (int n = 0; n < 4; ++n) acc[m][n] = __builtin_amdgcn_mfma_f32_16x16x32_bf16(b1[n], a1[m], acc[m][n], 0, 0, 0);
	v_or_b32_e32 v0, v0, v2
	v_lshl_add_u64 v[78:79], s[6:7], 0, v[0:1]
	v_mov_b32_e32 v0, 0
	s_mov_b64 s[0:1], 0
	s_mov_b32 s44, 0x8000
	v_mov_b32_e32 v1, v0
	v_mov_b32_e32 v2, v0
	v_mov_b32_e32 v3, v0
	v_mov_b32_e32 v4, v0
	v_mov_b32_e32 v5, v0
	v_mov_b32_e32 v6, v0
	v_mov_b32_e32 v7, v0
	v_mov_b32_e32 v8, v0
	v_mov_b32_e32 v9, v0
	v_mov_b32_e32 v10, v0
	v_mov_b32_e32 v11, v0
	v_mov_b32_e32 v12, v0
	v_mov_b32_e32 v13, v0
	v_mov_b32_e32 v14, v0
	v_mov_b32_e32 v15, v0
	v_mov_b32_e32 v16, v0
	v_mov_b32_e32 v17, v0
	v_mov_b32_e32 v18, v0
	v_mov_b32_e32 v19, v0
	v_mov_b32_e32 v20, v0
	v_mov_b32_e32 v21, v0
	v_mov_b32_e32 v22, v0
	v_mov_b32_e32 v23, v0
	v_mov_b32_e32 v24, v0
	v_mov_b32_e32 v25, v0
	v_mov_b32_e32 v26, v0
	v_mov_b32_e32 v27, v0
	v_mov_b32_e32 v36, v0
	v_mov_b32_e32 v37, v0
	v_mov_b32_e32 v38, v0
	v_mov_b32_e32 v39, v0
	v_mov_b32_e32 v28, v0
	v_mov_b32_e32 v29, v0
	v_mov_b32_e32 v30, v0
	v_mov_b32_e32 v31, v0
	v_mov_b32_e32 v32, v0
	v_mov_b32_e32 v33, v0
	v_mov_b32_e32 v34, v0
	v_mov_b32_e32 v35, v0
	v_mov_b32_e32 v40, v0
	v_mov_b32_e32 v41, v0
	v_mov_b32_e32 v42, v0
	v_mov_b32_e32 v43, v0
	v_mov_b32_e32 v44, v0
	v_mov_b32_e32 v45, v0
	v_mov_b32_e32 v46, v0
	v_mov_b32_e32 v47, v0
	v_mov_b32_e32 v48, v0
	v_mov_b32_e32 v49, v0
	v_mov_b32_e32 v50, v0
	v_mov_b32_e32 v51, v0
	v_mov_b32_e32 v52, v0
	v_mov_b32_e32 v53, v0
	v_mov_b32_e32 v54, v0
	v_mov_b32_e32 v55, v0
	v_mov_b32_e32 v56, v0
	v_mov_b32_e32 v57, v0
	v_mov_b32_e32 v58, v0
	v_mov_b32_e32 v59, v0
	v_mov_b32_e32 v60, v0
	v_mov_b32_e32 v61, v0
	v_mov_b32_e32 v62, v0
	v_mov_b32_e32 v63, v0
	v_readfirstlane_b32 s98, v84
	s_mov_b64 s[100:101], 0
	s_nop 3
	s_add_u32 s99, s98, 0x8000
	s_mov_b32 m0, s99
	v_lshl_add_u64 v[166:167], v[64:65], 0, s[100:101]
	global_load_lds_dwordx4 v[166:167], off
	s_add_u32 m0, s99, 0x4000
	v_lshl_add_u64 v[166:167], v[66:67], 0, s[100:101]
	global_load_lds_dwordx4 v[166:167], off
	s_add_u32 m0, s99, 0x1000
	v_lshl_add_u64 v[166:167], v[68:69], 0, s[100:101]
	global_load_lds_dwordx4 v[166:167], off
	s_add_u32 m0, s99, 0x5000
	v_lshl_add_u64 v[166:167], v[70:71], 0, s[100:101]
	global_load_lds_dwordx4 v[166:167], off
	s_add_u32 m0, s99, 0x2000
	v_lshl_add_u64 v[166:167], v[72:73], 0, s[100:101]
	global_load_lds_dwordx4 v[166:167], off
	s_add_u32 m0, s99, 0x6000
	v_lshl_add_u64 v[166:167], v[74:75], 0, s[100:101]
	global_load_lds_dwordx4 v[166:167], off
	s_add_u32 m0, s99, 0x3000
	v_lshl_add_u64 v[166:167], v[76:77], 0, s[100:101]
	global_load_lds_dwordx4 v[166:167], off
	s_add_u32 m0, s99, 0x7000
	v_lshl_add_u64 v[166:167], v[78:79], 0, s[100:101]
	global_load_lds_dwordx4 v[166:167], off
	s_waitcnt vmcnt(8) lgkmcnt(0)
	s_barrier
.LBB0_100:
	s_add_i32 s45, s44, 0xffff8000
	s_and_b32 s45, s45, 0x8000
	v_add_u32_e32 v89, s45, v88
	ds_read_b128 v[90:93], v89
	ds_read_b128 v[94:97], v89 offset:2048
	ds_read_b128 v[98:101], v89 offset:4096
	ds_read_b128 v[114:117], v89 offset:6144
	v_or_b32_e32 v89, s45, v87
	ds_read_b128 v[118:121], v89 offset:16384
	ds_read_b128 v[122:125], v89 offset:18432
	ds_read_b128 v[126:129], v89 offset:20480
	ds_read_b128 v[130:133], v89 offset:22528
	v_add_u32_e32 v89, s45, v86
	ds_read_b128 v[134:137], v89
	ds_read_b128 v[138:141], v89 offset:2048
	ds_read_b128 v[142:145], v89 offset:4096
	ds_read_b128 v[146:149], v89 offset:6144
	v_or_b32_e32 v89, s45, v85
	ds_read_b128 v[150:153], v89 offset:16384
	ds_read_b128 v[154:157], v89 offset:18432
	ds_read_b128 v[158:161], v89 offset:20480
	ds_read_b128 v[162:165], v89 offset:22528
	s_waitcnt lgkmcnt(0)
	s_barrier
	s_cmpk_eq_i32 s0, 0x1500
	s_cbranch_scc1 .Lnodma_g100
	s_add_u32 s100, s0, 0x80
	s_addc_u32 s101, s1, 0
	s_add_u32 s99, s98, s45
	s_setprio 1
	v_mfma_f32_16x16x32_bf16 v[36:39], v[118:121], v[90:93], v[36:39]
	v_mfma_f32_16x16x32_bf16 v[24:27], v[122:125], v[90:93], v[24:27]
	v_mfma_f32_16x16x32_bf16 v[20:23], v[126:129], v[90:93], v[20:23]
	v_mfma_f32_16x16x32_bf16 v[16:19], v[130:133], v[90:93], v[16:19]
	s_mov_b32 m0, s99
	v_lshl_add_u64 v[166:167], v[64:65], 0, s[100:101]
	global_load_lds_dwordx4 v[166:167], off
	v_mfma_f32_16x16x32_bf16 v[12:15], v[118:121], v[94:97], v[12:15]
	v_mfma_f32_16x16x32_bf16 v[8:11], v[122:125], v[94:97], v[8:11]
	v_mfma_f32_16x16x32_bf16 v[4:7], v[126:129], v[94:97], v[4:7]
	v_mfma_f32_16x16x32_bf16 v[0:3], v[130:133], v[94:97], v[0:3]
	s_add_u32 m0, s99, 0x4000
	v_lshl_add_u64 v[166:167], v[66:67], 0, s[100:101]
	global_load_lds_dwordx4 v[166:167], off
	v_mfma_f32_16x16x32_bf16 v[28:31], v[118:121], v[98:101], v[28:31]
	v_mfma_f32_16x16x32_bf16 v[32:35], v[122:125], v[98:101], v[32:35]
	v_mfma_f32_16x16x32_bf16 v[40:43], v[126:129], v[98:101], v[40:43]
	v_mfma_f32_16x16x32_bf16 v[44:47], v[130:133], v[98:101], v[44:47]
	s_add_u32 m0, s99, 0x1000
	v_lshl_add_u64 v[166:167], v[68:69], 0, s[100:101]
	global_load_lds_dwordx4 v[166:167], off
	v_mfma_f32_16x16x32_bf16 v[48:51], v[118:121], v[114:117], v[48:51]
	v_mfma_f32_16x16x32_bf16 v[52:55], v[122:125], v[114:117], v[52:55]
	v_mfma_f32_16x16x32_bf16 v[56:59], v[126:129], v[114:117], v[56:59]
	v_mfma_f32_16x16x32_bf16 v[60:63], v[130:133], v[114:117], v[60:63]
	s_add_u32 m0, s99, 0x5000
	v_lshl_add_u64 v[166:167], v[70:71], 0, s[100:101]
	global_load_lds_dwordx4 v[166:167], off
	v_mfma_f32_16x16x32_bf16 v[36:39], v[150:153], v[134:137], v[36:39]
	v_mfma_f32_16x16x32_bf16 v[24:27], v[154:157], v[134:137], v[24:27]
	v_mfma_f32_16x16x32_bf16 v[20:23], v[158:161], v[134:137], v[20:23]
	v_mfma_f32_16x16x32_bf16 v[16:19], v[162:165], v[134:137], v[16:19]
	s_add_u32 m0, s99, 0x2000
	v_lshl_add_u64 v[166:167], v[72:73], 0, s[100:101]
	global_load_lds_dwordx4 v[166:167], off
	v_mfma_f32_16x16x32_bf16 v[12:15], v[150:153], v[138:141], v[12:15]
	v_mfma_f32_16x16x32_bf16 v[8:11], v[154:157], v[138:141], v[8:11]
	v_mfma_f32_16x16x32_bf16 v[4:7], v[158:161], v[138:141], v[4:7]
	v_mfma_f32_16x16x32_bf16 v[0:3], v[162:165], v[138:141], v[0:3]
	s_add_u32 m0, s99, 0x6000
	v_lshl_add_u64 v[166:167], v[74:75], 0, s[100:101]
	global_load_lds_dwordx4 v[166:167], off
	v_mfma_f32_16x16x32_bf16 v[28:31], v[150:153], v[142:145], v[28:31]
	v_mfma_f32_16x16x32_bf16 v[32:35], v[154:157], v[142:145], v[32:35]
	v_mfma_f32_16x16x32_bf16 v[40:43], v[158:161], v[142:145], v[40:43]
	v_mfma_f32_16x16x32_bf16 v[44:47], v[162:165], v[142:145], v[44:47]
	s_add_u32 m0, s99, 0x3000
	v_lshl_add_u64 v[166:167], v[76:77], 0, s[100:101]
	global_load_lds_dwordx4 v[166:167], off
	v_mfma_f32_16x16x32_bf16 v[48:51], v[150:153], v[146:149], v[48:51]
	v_mfma_f32_16x16x32_bf16 v[52:55], v[154:157], v[146:149], v[52:55]
	v_mfma_f32_16x16x32_bf16 v[56:59], v[158:161], v[146:149], v[56:59]
	v_mfma_f32_16x16x32_bf16 v[60:63], v[162:165], v[146:149], v[60:63]
	s_add_u32 m0, s99, 0x7000
	v_lshl_add_u64 v[166:167], v[78:79], 0, s[100:101]
	global_load_lds_dwordx4 v[166:167], off
	s_setprio 0
	s_branch .Ljoin_g100
; template <class Epi>
; __device__ __forceinline__ void gemm_tile(const bf16_t* A, int lda, const bf16_t* Bt, int ldb, int K, int m0, int n0, const Epi& epi, char* smem) {
;     ...
;     for (int kt = 0; kt < nk; ++kt) {
;         const int st = (kt & 1) * 32768;
;         if (kt + 1 < nk) G_ISSUE(((kt + 1) & 1) * 32768, (kt + 1) * 64)
;         {
;             bf16x8 a0[4], b0[4], a1[4], b1[4];
;             const int ch0 = ((0 + fq) ^ rsw) << 4, ch1 = ((4 + fq) ^ rsw) << 4;
; #pragma unroll
;             for (int m = 0; m < 4; ++m) a0[m] = *(const bf16x8*)(smem + st + aofs + m * 2048 + ch0);
; #pragma unroll
;             for (int n = 0; n < 4; ++n) b0[n] = *(const bf16x8*)(smem + st + bofs + n * 2048 + ch0);
;             __builtin_amdgcn_sched_barrier(0);
; #pragma unroll
;             for (int m = 0; m < 4; ++m) a1[m] = *(const bf16x8*)(smem + st + aofs + m * 2048 + ch1);
; #pragma unroll
;             for (int n = 0; n < 4; ++n) b1[n] = *(const bf16x8*)(smem + st + bofs + n * 2048 + ch1);
;             __builtin_amdgcn_sched_barrier(0);
;             __builtin_amdgcn_s_setprio(1);
; #pragma unroll
;             for (int m = 0; m < 4; ++m)
; #pragma unroll
;                 for (int n = 0; n < 4; ++n) acc[m][n] = __builtin_amdgcn_mfma_f32_16x16x32_bf16(b0[n], a0[m], acc[m][n], 0, 0, 0);
;             __builtin_amdgcn_sched_barrier(0);
; #pragma unroll
;             for (int m = 0; m < 4; ++m)
; #pragma unroll
;                 for (int n = 0; n < 4; ++n) acc[m][n] = __builtin_amdgcn_mfma_f32_16x16x32_bf16(b1[n], a1[m], acc[m][n], 0, 0, 0);
;             __builtin_amdgcn_s_setprio(0);
;             __builtin_amdgcn_sched_barrier(0);
;         }
;         asm volatile("s_waitcnt vmcnt(0)" ::: "memory");
;         __syncthreads();
;     }
;     __device__ __forceinline__ void operator()(const f32x4 (&acc)[4][4], int m0, int n0, int wr, int wc, int fr, int fq, char*) const {
; #pragma unroll
;         for (int m = 0; m < 4; ++m) {
;             const int row = m0 + wr * 64 + m * 16 + fr;
;             const float* xi = from_input ? xin_row(*p, row) : xcur_row(*p, row);
;             float* xo = shadow ? (float*)(p->ws + OFF_Q) + (size_t)row * 1024 : xcur_row(*p, row);
;             const float* gt = gate + (size_t)mod_index(row) * 6144;
.Lnodma_g100:
	s_waitcnt vmcnt(0)
	s_setprio 1
	v_mfma_f32_16x16x32_bf16 v[36:39], v[118:121], v[90:93], v[36:39]
	v_mfma_f32_16x16x32_bf16 v[24:27], v[122:125], v[90:93], v[24:27]
	v_mfma_f32_16x16x32_bf16 v[20:23], v[126:129], v[90:93], v[20:23]
	v_mfma_f32_16x16x32_bf16 v[16:19], v[130:133], v[90:93], v[16:19]
	v_mfma_f32_16x16x32_bf16 v[12:15], v[118:121], v[94:97], v[12:15]
	v_mfma_f32_16x16x32_bf16 v[8:11], v[122:125], v[94:97], v[8:11]
	v_mfma_f32_16x16x32_bf16 v[4:7], v[126:129], v[94:97], v[4:7]
	v_mfma_f32_16x16x32_bf16 v[0:3], v[130:133], v[94:97], v[0:3]
	v_mfma_f32_16x16x32_bf16 v[28:31], v[118:121], v[98:101], v[28:31]
	v_mfma_f32_16x16x32_bf16 v[32:35], v[122:125], v[98:101], v[32:35]
	v_mfma_f32_16x16x32_bf16 v[40:43], v[126:129], v[98:101], v[40:43]
	v_mfma_f32_16x16x32_bf16 v[44:47], v[130:133], v[98:101], v[44:47]
	v_mfma_f32_16x16x32_bf16 v[48:51], v[118:121], v[114:117], v[48:51]
	v_mfma_f32_16x16x32_bf16 v[52:55], v[122:125], v[114:117], v[52:55]
	v_mfma_f32_16x16x32_bf16 v[56:59], v[126:129], v[114:117], v[56:59]
	v_mfma_f32_16x16x32_bf16 v[60:63], v[130:133], v[114:117], v[60:63]
	v_mfma_f32_16x16x32_bf16 v[36:39], v[150:153], v[134:137], v[36:39]
	v_mfma_f32_16x16x32_bf16 v[24:27], v[154:157], v[134:137], v[24:27]
	v_mfma_f32_16x16x32_bf16 v[20:23], v[158:161], v[134:137], v[20:23]
	v_mfma_f32_16x16x32_bf16 v[16:19], v[162:165], v[134:137], v[16:19]
	v_mfma_f32_16x16x32_bf16 v[12:15], v[150:153], v[138:141], v[12:15]
	v_mfma_f32_16x16x32_bf16 v[8:11], v[154:157], v[138:141], v[8:11]
	v_mfma_f32_16x16x32_bf16 v[4:7], v[158:161], v[138:141], v[4:7]
	v_mfma_f32_16x16x32_bf16 v[0:3], v[162:165], v[138:141], v[0:3]
	v_mfma_f32_16x16x32_bf16 v[28:31], v[150:153], v[142:145], v[28:31]
	v_mfma_f32_16x16x32_bf16 v[32:35], v[154:157], v[142:145], v[32:35]
	v_mfma_f32_16x16x32_bf16 v[40:43], v[158:161], v[142:145], v[40:43]
	v_mfma_f32_16x16x32_bf16 v[44:47], v[162:165], v[142:145], v[44:47]
	v_mfma_f32_16x16x32_bf16 v[48:51], v[150:153], v[146:149], v[48:51]
	v_mfma_f32_16x16x32_bf16 v[52:55], v[154:157], v[146:149], v[52:55]
	v_mfma_f32_16x16x32_bf16 v[56:59], v[158:161], v[146:149], v[56:59]
	v_mfma_f32_16x16x32_bf16 v[60:63], v[162:165], v[146:149], v[60:63]
	s_setprio 0
.Ljoin_g100:
	s_add_u32 s0, s0, 0x80
	s_addc_u32 s1, s1, 0
	s_add_i32 s44, s44, 0x8000
	s_cmpk_eq_i32 s0, 0x1580
	s_waitcnt vmcnt(8)
	s_barrier
	s_cbranch_scc0 .LBB0_100
	ds_read_b128 v[64:67], v88 offset:32768
	ds_read_b128 v[68:71], v88 offset:34816
	ds_read_b128 v[72:75], v88 offset:36864
	ds_read_b128 v[76:79], v88 offset:38912
	ds_read_b128 v[88:91], v87 offset:49152
	ds_read_b128 v[92:95], v87 offset:51200
	ds_read_b128 v[96:99], v87 offset:53248
	ds_read_b128 v[100:103], v87 offset:55296
	ds_read_b128 v[114:117], v86 offset:32768
	ds_read_b128 v[118:121], v86 offset:34816
	ds_read_b128 v[122:125], v86 offset:36864
	ds_read_b128 v[126:129], v86 offset:38912
	ds_read_b128 v[130:133], v85 offset:49152
	ds_read_b128 v[134:137], v85 offset:51200
	ds_read_b128 v[138:141], v85 offset:53248
	ds_read_b128 v[84:87], v85 offset:55296
	s_setprio 1
	s_waitcnt lgkmcnt(11)
	v_mfma_f32_16x16x32_bf16 v[36:39], v[88:91], v[64:67], v[36:39]
	s_waitcnt lgkmcnt(10)
	v_mfma_f32_16x16x32_bf16 v[24:27], v[92:95], v[64:67], v[24:27]
	s_waitcnt lgkmcnt(9)
	v_mfma_f32_16x16x32_bf16 v[20:23], v[96:99], v[64:67], v[20:23]
	s_waitcnt lgkmcnt(8)
	v_mfma_f32_16x16x32_bf16 v[16:19], v[100:103], v[64:67], v[16:19]
	v_mfma_f32_16x16x32_bf16 v[12:15], v[88:91], v[68:71], v[12:15]
	v_mfma_f32_16x16x32_bf16 v[8:11], v[92:95], v[68:71], v[8:11]
	v_mfma_f32_16x16x32_bf16 v[4:7], v[96:99], v[68:71], v[4:7]
	v_mfma_f32_16x16x32_bf16 v[0:3], v[100:103], v[68:71], v[0:3]
	v_mfma_f32_16x16x32_bf16 v[28:31], v[88:91], v[72:75], v[28:31]
	v_mfma_f32_16x16x32_bf16 v[64:67], v[92:95], v[72:75], v[32:35]
	v_mfma_f32_16x16x32_bf16 v[68:71], v[96:99], v[72:75], v[40:43]
	v_mfma_f32_16x16x32_bf16 v[88:91], v[88:91], v[76:79], v[48:51]
	v_mfma_f32_16x16x32_bf16 v[92:95], v[92:95], v[76:79], v[52:55]
	v_mfma_f32_16x16x32_bf16 v[96:99], v[96:99], v[76:79], v[56:59]
	v_mfma_f32_16x16x32_bf16 v[76:79], v[100:103], v[76:79], v[60:63]
	v_mfma_f32_16x16x32_bf16 v[72:75], v[100:103], v[72:75], v[44:47]
	s_waitcnt lgkmcnt(3)
	v_mfma_f32_16x16x32_bf16 v[60:63], v[130:133], v[114:117], v[36:39]
	s_waitcnt lgkmcnt(2)
	v_mfma_f32_16x16x32_bf16 v[56:59], v[134:137], v[114:117], v[24:27]
	s_waitcnt lgkmcnt(1)
	v_mfma_f32_16x16x32_bf16 v[52:55], v[138:141], v[114:117], v[20:23]
	s_waitcnt lgkmcnt(0)
	v_mfma_f32_16x16x32_bf16 v[48:51], v[84:87], v[114:117], v[16:19]
	v_mfma_f32_16x16x32_bf16 v[44:47], v[130:133], v[118:121], v[12:15]
	v_mfma_f32_16x16x32_bf16 v[40:43], v[134:137], v[118:121], v[8:11]
	v_mfma_f32_16x16x32_bf16 v[36:39], v[138:141], v[118:121], v[4:7]
	v_mfma_f32_16x16x32_bf16 v[32:35], v[84:87], v[118:121], v[0:3]
	v_mfma_f32_16x16x32_bf16 v[28:31], v[130:133], v[122:125], v[28:31]
	v_mfma_f32_16x16x32_bf16 v[24:27], v[134:137], v[122:125], v[64:67]
	v_mfma_f32_16x16x32_bf16 v[20:23], v[138:141], v[122:125], v[68:71]
	v_mfma_f32_16x16x32_bf16 v[16:19], v[84:87], v[122:125], v[72:75]
	v_mfma_f32_16x16x32_bf16 v[12:15], v[130:133], v[126:129], v[88:91]
	v_mfma_f32_16x16x32_bf16 v[8:11], v[134:137], v[126:129], v[92:95]
	v_mfma_f32_16x16x32_bf16 v[4:7], v[138:141], v[126:129], v[96:99]
	v_mfma_f32_16x16x32_bf16 v[0:3], v[84:87], v[126:129], v[76:79]
	s_setprio 0
	v_or_b32_e32 v64, s43, v83
	s_nop 0
	v_lshl_add_u32 v76, v82, 6, v64
	v_mul_hi_i32 v64, v76, s36
	v_lshrrev_b32_e32 v65, 31, v64
	v_ashrrev_i32_e32 v64, 11, v64
	s_waitcnt vmcnt(0)
	v_add_u32_e32 v70, v64, v65
	s_movk_i32 s0, 0xef00
	v_mad_i32_i24 v68, v70, s0, v76
	v_cmp_lt_i32_e32 vcc, s2, v68
	v_ashrrev_i32_e32 v71, 31, v70
	v_add_u32_e32 v104, 0xffffff00, v68
	s_barrier
	s_and_saveexec_b64 s[0:1], vcc
	s_xor_b64 s[0:1], exec, s[0:1]
	v_lshlrev_b64 v[64:65], 24, v[70:71]
	v_lshl_add_u64 v[64:65], s[24:25], 0, v[64:65]
	v_mov_b64_e32 v[66:67], v[104:105]
	s_or_saveexec_b64 s[0:1], s[0:1]
	v_lshl_add_u32 v68, v70, 8, v68
	v_ashrrev_i32_e32 v69, 31, v68
	s_xor_b64 exec, exec, s[0:1]
	s_cbranch_execz .LBB0_105
	v_readlane_b32 s4, v251, 30
	v_readlane_b32 s5, v251, 31
	v_mov_b64_e32 v[66:67], v[68:69]
	s_nop 0
	v_mov_b64_e32 v[64:65], s[4:5]

; __device__ __forceinline__ int opaque_tid() { int t = threadIdx.x; asm volatile("" : "+v"(t)); return t; }
; template <class Epi>
; __device__ __forceinline__ void gemm_tile(const bf16_t* A, int lda, const bf16_t* Bt, int ldb, int K, int m0, int n0, const Epi& epi, char* smem) {
;     const int tid = opaque_tid(), lane = tid & 63, wid = tid >> 6, wr = wid >> 1, wc = wid & 1, fr = lane & 15, fq = lane >> 4;
;     f32x4 acc[4][4];
; #pragma unroll
;     for (int m = 0; m < 4; ++m)
; #pragma unroll
;         for (int n = 0; n < 4; ++n) acc[m][n] = (f32x4){0.f, 0.f, 0.f, 0.f};
;     const int lr = lane >> 3;
;     const bf16_t* Ag[4]; const bf16_t* Bg[4];
; #pragma unroll
;     for (int i = 0; i < 4; ++i) {
;         const int r = (wid + 4 * i) * 8 + lr, lc = (lane & 7) ^ ((r >> 1) & 7);
;         Ag[i] = A + (size_t)(m0 + r) * lda + lc * 8; Bg[i] = Bt + (size_t)(n0 + r) * ldb + lc * 8;
;     }
;     const unsigned lds0 = (unsigned)(uintptr_t)smem;
;     const int rsw = (fr >> 1) & 7;
;     const int aofs = (wr * 64 + fr) * 128, bofs = 16384 + (wc * 64 + fr) * 128;
;     const int nk = K >> 6;
;     ...
;     G_ISSUE(0, 0)
;     asm volatile("s_waitcnt vmcnt(0)" ::: "memory");
;     __syncthreads();
; __device__ __forceinline__ bool gemm_unit(int it, int NT, int m_lo, int& mt, int& nt) {
;     const int xcd = blockIdx.x & 7, j = blockIdx.x >> 3, nb = gridDim.x >> 3;
;     const int L = it * nb + j, MX = 34 - m_lo;
;     if (L >= MX * NT) return false;
;     const int grp = L / (8 * NT), r = L - grp * 8 * NT, gsz = min(8, MX - grp * 8);
;     nt = r / gsz; mt = xcd * 34 + m_lo + grp * 8 + (r - nt * gsz);
;     return true;
.LBB0_152:
	s_mul_hi_u32 s1, s0, 0xba2e8ba3
	s_lshr_b32 s1, s1, 8
	s_lshl_b32 s35, s1, 3
	s_sub_i32 s34, s81, s35
	s_min_u32 s42, s34, 8
	s_waitcnt vmcnt(1)
	v_cvt_f32_ubyte0_e32 v0, s42
	v_rcp_iflag_f32_e32 v0, v0
	s_sub_i32 s45, 0, s42
	s_mul_i32 s34, s1, 0xfffffea0
	s_add_i32 s43, s34, s0
	v_mul_f32_e32 v0, 0x4f7ffffe, v0
	v_cvt_u32_f32_e32 v0, v0
	s_abs_i32 s34, s43
	s_ashr_i32 s44, s43, 31
	v_mov_b32_e32 v16, v109
	v_readfirstlane_b32 s46, v0
	s_mul_i32 s45, s45, s46
	s_mul_hi_u32 s45, s46, s45
	s_add_i32 s46, s46, s45
	s_mul_hi_u32 s45, s34, s46
	s_mul_i32 s46, s45, s42
	s_sub_i32 s34, s34, s46
	s_add_i32 s47, s45, 1
	s_sub_i32 s46, s34, s42
	s_cmp_ge_u32 s34, s42
	s_cselect_b32 s45, s47, s45
	s_cselect_b32 s34, s46, s34
	s_add_i32 s46, s45, 1
	s_cmp_ge_u32 s34, s42
	s_cselect_b32 s34, s46, s45
	s_xor_b32 s45, s34, s44
	s_sub_i32 s34, s45, s44
	s_add_i32 s35, s93, s35
	s_mul_i32 s42, s42, s34
	s_add_i32 s35, s35, s43
	s_sub_i32 s35, s35, s42
	v_ashrrev_i32_e32 v17, 6, v16
	v_bfe_u32 v18, v16, 3, 3
	v_lshlrev_b32_e32 v19, 3, v17
	s_lshl_b32 s35, s35, 7
	v_or_b32_e32 v12, v19, v18
	s_waitcnt vmcnt(0)
	v_lshrrev_b32_e32 v20, 1, v12
	v_add_u32_e32 v0, s35, v12
	v_xor_b32_e32 v2, v20, v16
	v_ashrrev_i32_e32 v1, 31, v0
	s_lshl_b32 s43, s34, 7
	v_lshlrev_b64 v[0:1], 11, v[0:1]
	v_lshlrev_b32_e32 v2, 4, v2
	v_add_u32_e32 v6, 32, v12
	v_add_u32_e32 v10, 64, v12
	v_add_u32_e32 v14, 0x60, v12
	v_lshlrev_b32_e32 v84, 10, v17
	v_lshl_add_u64 v[0:1], s[40:41], 0, v[0:1]
	v_and_b32_e32 v104, 0x70, v2
	v_add_u32_e32 v2, s43, v12
	v_add_u32_e32 v4, s35, v6
	v_add_u32_e32 v6, s43, v6
	v_add_u32_e32 v8, s35, v10
	v_add_u32_e32 v10, s43, v10
	v_add_u32_e32 v12, s35, v14
	v_add_u32_e32 v14, s43, v14
	v_readfirstlane_b32 s43, v84
	v_lshl_add_u64 v[0:1], v[0:1], 0, v[104:105]
	v_ashrrev_i32_e32 v3, 31, v2
	v_readlane_b32 s4, v251, 32
	s_mov_b32 m0, s43
	v_lshlrev_b64 v[2:3], 11, v[2:3]
	v_readlane_b32 s5, v251, 33
	v_ashrrev_i32_e32 v5, 31, v4
	global_load_lds_dwordx4 v[0:1], off
	v_add_u32_e32 v0, 0x4000, v84
	v_lshl_add_u64 v[2:3], s[4:5], 0, v[2:3]
	v_lshlrev_b64 v[4:5], 11, v[4:5]
	v_ashrrev_i32_e32 v7, 31, v6
	v_readfirstlane_b32 s43, v0
	v_add_u32_e32 v0, 0x1000, v84
	v_lshl_add_u64 v[2:3], v[2:3], 0, v[104:105]
	v_lshl_add_u64 v[4:5], s[40:41], 0, v[4:5]
	v_lshlrev_b64 v[6:7], 11, v[6:7]
	v_ashrrev_i32_e32 v9, 31, v8
	s_mov_b32 m0, s43
	v_readfirstlane_b32 s43, v0
	v_add_u32_e32 v0, 0x5000, v84
	v_lshl_add_u64 v[4:5], v[4:5], 0, v[104:105]
	v_lshl_add_u64 v[6:7], s[4:5], 0, v[6:7]
	v_lshlrev_b64 v[8:9], 11, v[8:9]
	v_ashrrev_i32_e32 v11, 31, v10
	global_load_lds_dwordx4 v[2:3], off
	s_mov_b32 m0, s43
	v_readfirstlane_b32 s43, v0
	v_add_u32_e32 v0, 0x2000, v84
	v_lshl_add_u64 v[6:7], v[6:7], 0, v[104:105]
	v_lshl_add_u64 v[8:9], s[40:41], 0, v[8:9]
	v_lshlrev_b64 v[10:11], 11, v[10:11]
	v_ashrrev_i32_e32 v13, 31, v12
	global_load_lds_dwordx4 v[4:5], off
	s_mov_b32 m0, s43
	v_readfirstlane_b32 s43, v0
	v_add_u32_e32 v0, 0x6000, v84
	v_lshl_add_u64 v[8:9], v[8:9], 0, v[104:105]
	v_lshl_add_u64 v[10:11], s[4:5], 0, v[10:11]
	v_lshlrev_b64 v[12:13], 11, v[12:13]
	v_ashrrev_i32_e32 v15, 31, v14
	global_load_lds_dwordx4 v[6:7], off
	s_mov_b32 m0, s43
	v_readfirstlane_b32 s43, v0
	v_add_u32_e32 v0, 0x3000, v84
	v_lshl_add_u64 v[10:11], v[10:11], 0, v[104:105]
	v_lshl_add_u64 v[12:13], s[40:41], 0, v[12:13]
	v_lshlrev_b64 v[14:15], 11, v[14:15]
	global_load_lds_dwordx4 v[8:9], off
	s_mov_b32 m0, s43
	v_readfirstlane_b32 s43, v0
	v_add_u32_e32 v0, 0x7000, v84
	v_lshl_add_u64 v[12:13], v[12:13], 0, v[104:105]
	v_lshl_add_u64 v[14:15], s[4:5], 0, v[14:15]
	global_load_lds_dwordx4 v[10:11], off
	s_mov_b32 m0, s43
	v_readfirstlane_b32 s43, v0
	v_lshl_add_u64 v[14:15], v[14:15], 0, v[104:105]
	global_load_lds_dwordx4 v[12:13], off
	s_mov_b32 m0, s43
	s_add_i32 s0, s93, s0
	global_load_lds_dwordx4 v[14:15], off
	v_and_b32_e32 v82, 15, v16
	v_lshrrev_b32_e32 v21, 1, v16
	v_bfe_u32 v83, v16, 4, 2
	s_sub_i32 s0, s0, s42
	s_mulk_i32 s1, 0x158
	v_ashrrev_i32_e32 v80, 7, v16
	v_and_b32_e32 v81, 1, v17
	v_lshlrev_b32_e32 v23, 7, v82
	v_bitop3_b32 v0, v83, v21, 7 bitop3:0x78
	s_sub_i32 s0, s0, s1
	v_bfe_u32 v22, v16, 1, 3
	v_lshlrev_b32_e32 v0, 4, v0
	v_lshl_or_b32 v2, v80, 13, v23
	v_lshl_or_b32 v3, v81, 13, v23
	s_lshl_b32 s0, s0, 7
	v_bitop3_b32 v1, v83, v22, 4 bitop3:0x36
	v_or_b32_e32 v87, v2, v0
	v_or_b32_e32 v88, v3, v0
	v_or_b32_e32 v0, s0, v18
	v_lshlrev_b32_e32 v1, 4, v1
	v_add_u32_e32 v0, v0, v19
	v_or_b32_e32 v86, v2, v1
	v_or_b32_e32 v85, v3, v1
	v_ashrrev_i32_e32 v1, 31, v0
	v_bitop3_b32 v2, v20, 7, v16 bitop3:0x48
	v_lshlrev_b64 v[0:1], 11, v[0:1]
	v_lshlrev_b32_e32 v2, 4, v2
	v_readlane_b32 s4, v252, 55
	v_or_b32_e32 v0, v0, v2
	v_readlane_b32 s5, v252, 56
	s_lshl_b32 s1, s45, 7
	s_lshl_b32 s42, s44, 7
	v_lshl_add_u64 v[64:65], s[4:5], 0, v[0:1]
	v_or_b32_e32 v0, s1, v18
	v_add_u32_e32 v0, v0, v19
	v_subrev_u32_e32 v0, s42, v0
	v_ashrrev_i32_e32 v1, 31, v0
	v_lshlrev_b64 v[0:1], 11, v[0:1]
	v_readlane_b32 s6, v252, 57
	v_or_b32_e32 v0, v0, v2
	v_readlane_b32 s7, v252, 58
	v_or_b32_e32 v3, 32, v18
	s_waitcnt vmcnt(0)
	s_waitcnt vmcnt(0) lgkmcnt(0)
; template <class Epi>
; __device__ __forceinline__ void gemm_tile(const bf16_t* A, int lda, const bf16_t* Bt, int ldb, int K, int m0, int n0, const Epi& epi, char* smem) {
;     ...
;     f32x4 acc[4][4];
; #pragma unroll
;     for (int m = 0; m < 4; ++m)
; #pragma unroll
;         for (int n = 0; n < 4; ++n) acc[m][n] = (f32x4){0.f, 0.f, 0.f, 0.f};
;     const int lr = lane >> 3;
;     const bf16_t* Ag[4]; const bf16_t* Bg[4];
; #pragma unroll
;     for (int i = 0; i < 4; ++i) {
;         const int r = (wid + 4 * i) * 8 + lr, lc = (lane & 7) ^ ((r >> 1) & 7);
;         Ag[i] = A + (size_t)(m0 + r) * lda + lc * 8; Bg[i] = Bt + (size_t)(n0 + r) * ldb + lc * 8;
;     }
;     const unsigned lds0 = (unsigned)(uintptr_t)smem;
;     const int rsw = (fr >> 1) & 7;
;     const int aofs = (wr * 64 + fr) * 128, bofs = 16384 + (wc * 64 + fr) * 128;
;     const int nk = K >> 6;
;     ...
;     G_ISSUE(0, 0)
;     asm volatile("s_waitcnt vmcnt(0)" ::: "memory");
;     __syncthreads();
;     for (int kt = 0; kt < nk; ++kt) {
;         const int st = (kt & 1) * 32768;
;         if (kt + 1 < nk) G_ISSUE(((kt + 1) & 1) * 32768, (kt + 1) * 64)
	v_lshl_add_u64 v[66:67], s[6:7], 0, v[0:1]
	v_or_b32_e32 v0, s0, v3
	v_add_u32_e32 v0, v0, v19
	v_ashrrev_i32_e32 v1, 31, v0
	v_lshlrev_b64 v[0:1], 11, v[0:1]
	v_or_b32_e32 v0, v0, v2
	v_lshl_add_u64 v[68:69], s[4:5], 0, v[0:1]
	v_or_b32_e32 v0, s1, v3
	v_add_u32_e32 v0, v0, v19
	v_subrev_u32_e32 v0, s42, v0
	v_ashrrev_i32_e32 v1, 31, v0
	v_lshlrev_b64 v[0:1], 11, v[0:1]
	v_or_b32_e32 v0, v0, v2
	v_or_b32_e32 v3, 64, v18
	v_lshl_add_u64 v[70:71], s[6:7], 0, v[0:1]
	v_or_b32_e32 v0, s0, v3
	v_add_u32_e32 v0, v0, v19
	v_ashrrev_i32_e32 v1, 31, v0
	v_lshlrev_b64 v[0:1], 11, v[0:1]
	v_or_b32_e32 v0, v0, v2
	v_lshl_add_u64 v[72:73], s[4:5], 0, v[0:1]
	v_or_b32_e32 v0, s1, v3
	v_add_u32_e32 v0, v0, v19
	v_subrev_u32_e32 v0, s42, v0
	v_ashrrev_i32_e32 v1, 31, v0
	v_lshlrev_b64 v[0:1], 11, v[0:1]
	v_or_b32_e32 v0, v0, v2
	v_or_b32_e32 v3, 0x60, v18
	v_lshl_add_u64 v[74:75], s[6:7], 0, v[0:1]
	v_or_b32_e32 v0, s0, v3
	v_add_u32_e32 v0, v0, v19
	v_ashrrev_i32_e32 v1, 31, v0
	v_lshlrev_b64 v[0:1], 11, v[0:1]
	v_or_b32_e32 v0, v0, v2
	v_lshl_add_u64 v[76:77], s[4:5], 0, v[0:1]
	v_or_b32_e32 v0, s1, v3
	v_add_u32_e32 v0, v0, v19
	v_subrev_u32_e32 v0, s42, v0
	v_ashrrev_i32_e32 v1, 31, v0
	v_lshlrev_b64 v[0:1], 11, v[0:1]
	v_or_b32_e32 v0, v0, v2
	v_lshl_add_u64 v[78:79], s[6:7], 0, v[0:1]
	v_mov_b32_e32 v0, 0
	s_mov_b64 s[0:1], 0
	s_mov_b32 s42, 0x8000
	v_mov_b32_e32 v1, v0
	v_mov_b32_e32 v2, v0
	v_mov_b32_e32 v3, v0
	v_mov_b32_e32 v4, v0
	v_mov_b32_e32 v5, v0
	v_mov_b32_e32 v6, v0
	v_mov_b32_e32 v7, v0
	v_mov_b32_e32 v8, v0
	v_mov_b32_e32 v9, v0
	v_mov_b32_e32 v10, v0
	v_mov_b32_e32 v11, v0
	v_mov_b32_e32 v12, v0
	v_mov_b32_e32 v13, v0
	v_mov_b32_e32 v14, v0
	v_mov_b32_e32 v15, v0
	v_mov_b32_e32 v16, v0
	v_mov_b32_e32 v17, v0
	v_mov_b32_e32 v18, v0
	v_mov_b32_e32 v19, v0
	v_mov_b32_e32 v20, v0
	v_mov_b32_e32 v21, v0
	v_mov_b32_e32 v22, v0
	v_mov_b32_e32 v23, v0
	v_mov_b32_e32 v24, v0
	v_mov_b32_e32 v25, v0
	v_mov_b32_e32 v26, v0
	v_mov_b32_e32 v27, v0
	v_mov_b32_e32 v36, v0
	v_mov_b32_e32 v37, v0
	v_mov_b32_e32 v38, v0
	v_mov_b32_e32 v39, v0
	v_mov_b32_e32 v28, v0
	v_mov_b32_e32 v29, v0
	v_mov_b32_e32 v30, v0
	v_mov_b32_e32 v31, v0
	v_mov_b32_e32 v32, v0
	v_mov_b32_e32 v33, v0
	v_mov_b32_e32 v34, v0
	v_mov_b32_e32 v35, v0
	v_mov_b32_e32 v40, v0
	v_mov_b32_e32 v41, v0
	v_mov_b32_e32 v42, v0
	v_mov_b32_e32 v43, v0
	v_mov_b32_e32 v44, v0
	v_mov_b32_e32 v45, v0
	v_mov_b32_e32 v46, v0
	v_mov_b32_e32 v47, v0
	v_mov_b32_e32 v48, v0
	v_mov_b32_e32 v49, v0
	v_mov_b32_e32 v50, v0
	v_mov_b32_e32 v51, v0
	v_mov_b32_e32 v52, v0
	v_mov_b32_e32 v53, v0
	v_mov_b32_e32 v54, v0
	v_mov_b32_e32 v55, v0
	v_mov_b32_e32 v56, v0
	v_mov_b32_e32 v57, v0
	v_mov_b32_e32 v58, v0
	v_mov_b32_e32 v59, v0
	v_mov_b32_e32 v60, v0
	v_mov_b32_e32 v61, v0
	v_mov_b32_e32 v62, v0
	v_mov_b32_e32 v63, v0
	v_readfirstlane_b32 s98, v84
	s_mov_b64 s[100:101], 0
	s_nop 3
	s_add_u32 s99, s98, 0x8000
	s_mov_b32 m0, s99
	v_lshl_add_u64 v[166:167], v[64:65], 0, s[100:101]
	global_load_lds_dwordx4 v[166:167], off
	s_add_u32 m0, s99, 0x4000
	v_lshl_add_u64 v[166:167], v[66:67], 0, s[100:101]
	global_load_lds_dwordx4 v[166:167], off
	s_add_u32 m0, s99, 0x1000
	v_lshl_add_u64 v[166:167], v[68:69], 0, s[100:101]
	global_load_lds_dwordx4 v[166:167], off
	s_add_u32 m0, s99, 0x5000
	v_lshl_add_u64 v[166:167], v[70:71], 0, s[100:101]
	global_load_lds_dwordx4 v[166:167], off
	s_add_u32 m0, s99, 0x2000
	v_lshl_add_u64 v[166:167], v[72:73], 0, s[100:101]
	global_load_lds_dwordx4 v[166:167], off
	s_add_u32 m0, s99, 0x6000
	v_lshl_add_u64 v[166:167], v[74:75], 0, s[100:101]
	global_load_lds_dwordx4 v[166:167], off
	s_add_u32 m0, s99, 0x3000
	v_lshl_add_u64 v[166:167], v[76:77], 0, s[100:101]
	global_load_lds_dwordx4 v[166:167], off
	s_add_u32 m0, s99, 0x7000
	v_lshl_add_u64 v[166:167], v[78:79], 0, s[100:101]
	global_load_lds_dwordx4 v[166:167], off
	s_waitcnt vmcnt(8) lgkmcnt(0)
	s_barrier
; template <class Epi>
; __device__ __forceinline__ void gemm_tile(const bf16_t* A, int lda, const bf16_t* Bt, int ldb, int K, int m0, int n0, const Epi& epi, char* smem) {
;     ...
;     for (int kt = 0; kt < nk; ++kt) {
;         const int st = (kt & 1) * 32768;
;         if (kt + 1 < nk) G_ISSUE(((kt + 1) & 1) * 32768, (kt + 1) * 64)
;         {
;             bf16x8 a0[4], b0[4], a1[4], b1[4];
;             const int ch0 = ((0 + fq) ^ rsw) << 4, ch1 = ((4 + fq) ^ rsw) << 4;
; #pragma unroll
;             for (int m = 0; m < 4; ++m) a0[m] = *(const bf16x8*)(smem + st + aofs + m * 2048 + ch0);
; #pragma unroll
;             for (int n = 0; n < 4; ++n) b0[n] = *(const bf16x8*)(smem + st + bofs + n * 2048 + ch0);
;             __builtin_amdgcn_sched_barrier(0);
; #pragma unroll
;             for (int m = 0; m < 4; ++m) a1[m] = *(const bf16x8*)(smem + st + aofs + m * 2048 + ch1);
; #pragma unroll
;             for (int n = 0; n < 4; ++n) b1[n] = *(const bf16x8*)(smem + st + bofs + n * 2048 + ch1);
;             __builtin_amdgcn_sched_barrier(0);
;             __builtin_amdgcn_s_setprio(1);
; #pragma unroll
;             for (int m = 0; m < 4; ++m)
; #pragma unroll
;                 for (int n = 0; n < 4; ++n) acc[m][n] = __builtin_amdgcn_mfma_f32_16x16x32_bf16(b0[n], a0[m], acc[m][n], 0, 0, 0);
;             __builtin_amdgcn_sched_barrier(0);
; #pragma unroll
;             for (int m = 0; m < 4; ++m)
; #pragma unroll
;                 for (int n = 0; n < 4; ++n) acc[m][n] = __builtin_amdgcn_mfma_f32_16x16x32_bf16(b1[n], a1[m], acc[m][n], 0, 0, 0);
;             __builtin_amdgcn_s_setprio(0);
.LBB0_153:
	s_add_i32 s43, s42, 0xffff8000
	s_and_b32 s43, s43, 0x8000
	v_add_u32_e32 v89, s43, v87
	ds_read_b128 v[90:93], v89
	ds_read_b128 v[94:97], v89 offset:2048
	ds_read_b128 v[98:101], v89 offset:4096
	ds_read_b128 v[114:117], v89 offset:6144
	v_or_b32_e32 v89, s43, v88
	ds_read_b128 v[118:121], v89 offset:16384
	ds_read_b128 v[122:125], v89 offset:18432
	ds_read_b128 v[126:129], v89 offset:20480
	ds_read_b128 v[130:133], v89 offset:22528
	v_add_u32_e32 v89, s43, v86
	ds_read_b128 v[134:137], v89
	ds_read_b128 v[138:141], v89 offset:2048
	ds_read_b128 v[142:145], v89 offset:4096
	ds_read_b128 v[146:149], v89 offset:6144
	v_or_b32_e32 v89, s43, v85
	ds_read_b128 v[150:153], v89 offset:16384
	ds_read_b128 v[154:157], v89 offset:18432
	ds_read_b128 v[158:161], v89 offset:20480
	ds_read_b128 v[162:165], v89 offset:22528
	s_waitcnt lgkmcnt(0)
	s_barrier
	s_cmpk_eq_i32 s0, 0x700
	s_cbranch_scc1 .Lnodma_g153
	s_add_u32 s100, s0, 0x80
	s_addc_u32 s101, s1, 0
	s_add_u32 s99, s98, s43
	s_setprio 1
	v_mfma_f32_16x16x32_bf16 v[36:39], v[118:121], v[90:93], v[36:39]
	v_mfma_f32_16x16x32_bf16 v[24:27], v[122:125], v[90:93], v[24:27]
	v_mfma_f32_16x16x32_bf16 v[20:23], v[126:129], v[90:93], v[20:23]
	v_mfma_f32_16x16x32_bf16 v[16:19], v[130:133], v[90:93], v[16:19]
	s_mov_b32 m0, s99
	v_lshl_add_u64 v[166:167], v[64:65], 0, s[100:101]
	global_load_lds_dwordx4 v[166:167], off
	v_mfma_f32_16x16x32_bf16 v[12:15], v[118:121], v[94:97], v[12:15]
	v_mfma_f32_16x16x32_bf16 v[8:11], v[122:125], v[94:97], v[8:11]
	v_mfma_f32_16x16x32_bf16 v[4:7], v[126:129], v[94:97], v[4:7]
	v_mfma_f32_16x16x32_bf16 v[0:3], v[130:133], v[94:97], v[0:3]
	s_add_u32 m0, s99, 0x4000
	v_lshl_add_u64 v[166:167], v[66:67], 0, s[100:101]
	global_load_lds_dwordx4 v[166:167], off
	v_mfma_f32_16x16x32_bf16 v[28:31], v[118:121], v[98:101], v[28:31]
	v_mfma_f32_16x16x32_bf16 v[32:35], v[122:125], v[98:101], v[32:35]
	v_mfma_f32_16x16x32_bf16 v[40:43], v[126:129], v[98:101], v[40:43]
	v_mfma_f32_16x16x32_bf16 v[44:47], v[130:133], v[98:101], v[44:47]
	s_add_u32 m0, s99, 0x1000
	v_lshl_add_u64 v[166:167], v[68:69], 0, s[100:101]
	global_load_lds_dwordx4 v[166:167], off
	v_mfma_f32_16x16x32_bf16 v[48:51], v[118:121], v[114:117], v[48:51]
	v_mfma_f32_16x16x32_bf16 v[52:55], v[122:125], v[114:117], v[52:55]
	v_mfma_f32_16x16x32_bf16 v[56:59], v[126:129], v[114:117], v[56:59]
	v_mfma_f32_16x16x32_bf16 v[60:63], v[130:133], v[114:117], v[60:63]
	s_add_u32 m0, s99, 0x5000
	v_lshl_add_u64 v[166:167], v[70:71], 0, s[100:101]
	global_load_lds_dwordx4 v[166:167], off
	v_mfma_f32_16x16x32_bf16 v[36:39], v[150:153], v[134:137], v[36:39]
	v_mfma_f32_16x16x32_bf16 v[24:27], v[154:157], v[134:137], v[24:27]
	v_mfma_f32_16x16x32_bf16 v[20:23], v[158:161], v[134:137], v[20:23]
	v_mfma_f32_16x16x32_bf16 v[16:19], v[162:165], v[134:137], v[16:19]
	s_add_u32 m0, s99, 0x2000
	v_lshl_add_u64 v[166:167], v[72:73], 0, s[100:101]
	global_load_lds_dwordx4 v[166:167], off
	v_mfma_f32_16x16x32_bf16 v[12:15], v[150:153], v[138:141], v[12:15]
	v_mfma_f32_16x16x32_bf16 v[8:11], v[154:157], v[138:141], v[8:11]
	v_mfma_f32_16x16x32_bf16 v[4:7], v[158:161], v[138:141], v[4:7]
	v_mfma_f32_16x16x32_bf16 v[0:3], v[162:165], v[138:141], v[0:3]
	s_add_u32 m0, s99, 0x6000
	v_lshl_add_u64 v[166:167], v[74:75], 0, s[100:101]
	global_load_lds_dwordx4 v[166:167], off
	v_mfma_f32_16x16x32_bf16 v[28:31], v[150:153], v[142:145], v[28:31]
	v_mfma_f32_16x16x32_bf16 v[32:35], v[154:157], v[142:145], v[32:35]
	v_mfma_f32_16x16x32_bf16 v[40:43], v[158:161], v[142:145], v[40:43]
	v_mfma_f32_16x16x32_bf16 v[44:47], v[162:165], v[142:145], v[44:47]
	s_add_u32 m0, s99, 0x3000
	v_lshl_add_u64 v[166:167], v[76:77], 0, s[100:101]
	global_load_lds_dwordx4 v[166:167], off
	v_mfma_f32_16x16x32_bf16 v[48:51], v[150:153], v[146:149], v[48:51]
	v_mfma_f32_16x16x32_bf16 v[52:55], v[154:157], v[146:149], v[52:55]
	v_mfma_f32_16x16x32_bf16 v[56:59], v[158:161], v[146:149], v[56:59]
	v_mfma_f32_16x16x32_bf16 v[60:63], v[162:165], v[146:149], v[60:63]
	s_add_u32 m0, s99, 0x7000
	v_lshl_add_u64 v[166:167], v[78:79], 0, s[100:101]
	global_load_lds_dwordx4 v[166:167], off
	s_setprio 0
	s_branch .Ljoin_g153

; __device__ __forceinline__ unsigned pack2bf(float a, float b) { const f32x2 v = {a, b}; return __builtin_bit_cast(unsigned, __builtin_convertvector(v, bf2_t)); }
; template <class Epi>
; __device__ __forceinline__ void gemm_tile(const bf16_t* A, int lda, const bf16_t* Bt, int ldb, int K, int m0, int n0, const Epi& epi, char* smem) {
;     ...
;             __builtin_amdgcn_sched_barrier(0);
;         }
;         asm volatile("s_waitcnt vmcnt(0)" ::: "memory");
;         __syncthreads();
;     }
;     __device__ __forceinline__ void operator()(const f32x4 (&acc)[4][4], int m0, int n0, int wr, int wc, int fr, int fq, char*) const {
; #pragma unroll
;         for (int m = 0; m < 4; ++m) {
;             const int row = m0 + wr * 64 + m * 16 + fr;
;             const int col = (n0 >> 1) + wc * 32 + fq * 8;
;             float o[8];
; #pragma unroll
;             for (int pp = 0; pp < 2; ++pp)
; #pragma unroll
;                 for (int j = 0; j < 4; ++j) { const float g = acc[m][2 * pp][j], u = acc[m][2 * pp + 1][j]; o[pp * 4 + j] = g / (1.f + __expf(-g)) * u; }
;             uint4 w; w.x = pack2bf(o[0], o[1]); w.y = pack2bf(o[2], o[3]); w.z = pack2bf(o[4], o[5]); w.w = pack2bf(o[6], o[7]);
;             *(uint4*)(act + (size_t)row * FFH + col) = w;
.Ljoin_g153:
	s_add_u32 s0, s0, 0x80
	s_addc_u32 s1, s1, 0
	s_add_i32 s42, s42, 0x8000
	s_cmpk_eq_i32 s0, 0x780
	s_waitcnt vmcnt(8)
	s_barrier
	s_cbranch_scc0 .LBB0_153
	ds_read_b128 v[64:67], v88 offset:55296
	ds_read_b128 v[68:71], v88 offset:53248
	ds_read_b128 v[72:75], v88 offset:51200
	ds_read_b128 v[76:79], v88 offset:49152
	ds_read_b128 v[88:91], v87 offset:38912
	ds_read_b128 v[92:95], v87 offset:36864
	ds_read_b128 v[96:99], v87 offset:34816
	ds_read_b128 v[100:103], v87 offset:32768
	ds_read_b128 v[114:117], v86 offset:32768
	ds_read_b128 v[118:121], v86 offset:34816
	ds_read_b128 v[122:125], v86 offset:36864
	ds_read_b128 v[126:129], v86 offset:38912
	ds_read_b128 v[130:133], v85 offset:49152
	ds_read_b128 v[134:137], v85 offset:51200
	ds_read_b128 v[138:141], v85 offset:53248
	ds_read_b128 v[84:87], v85 offset:55296
	s_setprio 1
	s_waitcnt lgkmcnt(8)
	v_mfma_f32_16x16x32_bf16 v[36:39], v[76:79], v[100:103], v[36:39]
	v_mfma_f32_16x16x32_bf16 v[24:27], v[72:75], v[100:103], v[24:27]
	v_mfma_f32_16x16x32_bf16 v[20:23], v[68:71], v[100:103], v[20:23]
	v_mfma_f32_16x16x32_bf16 v[16:19], v[64:67], v[100:103], v[16:19]
	v_mfma_f32_16x16x32_bf16 v[12:15], v[76:79], v[96:99], v[12:15]
	v_mfma_f32_16x16x32_bf16 v[8:11], v[72:75], v[96:99], v[8:11]
	v_mfma_f32_16x16x32_bf16 v[4:7], v[68:71], v[96:99], v[4:7]
	v_mfma_f32_16x16x32_bf16 v[0:3], v[64:67], v[96:99], v[0:3]
	v_mfma_f32_16x16x32_bf16 v[28:31], v[76:79], v[92:95], v[28:31]
	v_mfma_f32_16x16x32_bf16 v[96:99], v[72:75], v[92:95], v[32:35]
	v_mfma_f32_16x16x32_bf16 v[100:103], v[68:71], v[92:95], v[40:43]
	v_mfma_f32_16x16x32_bf16 v[92:95], v[64:67], v[92:95], v[44:47]
	v_mfma_f32_16x16x32_bf16 v[76:79], v[76:79], v[88:91], v[48:51]
	v_mfma_f32_16x16x32_bf16 v[72:75], v[72:75], v[88:91], v[52:55]
	v_mfma_f32_16x16x32_bf16 v[56:59], v[68:71], v[88:91], v[56:59]
	v_mfma_f32_16x16x32_bf16 v[60:63], v[64:67], v[88:91], v[60:63]
	s_waitcnt lgkmcnt(3)
	v_mfma_f32_16x16x32_bf16 v[64:67], v[130:133], v[114:117], v[36:39]
	s_waitcnt lgkmcnt(2)
	v_mfma_f32_16x16x32_bf16 v[68:71], v[134:137], v[114:117], v[24:27]
	s_waitcnt lgkmcnt(1)
	v_mfma_f32_16x16x32_bf16 v[52:55], v[138:141], v[114:117], v[20:23]
	s_waitcnt lgkmcnt(0)
	v_mfma_f32_16x16x32_bf16 v[48:51], v[84:87], v[114:117], v[16:19]
	v_mfma_f32_16x16x32_bf16 v[40:43], v[130:133], v[118:121], v[12:15]
	v_mfma_f32_16x16x32_bf16 v[44:47], v[134:137], v[118:121], v[8:11]
	v_mfma_f32_16x16x32_bf16 v[36:39], v[138:141], v[118:121], v[4:7]
	v_mfma_f32_16x16x32_bf16 v[32:35], v[84:87], v[118:121], v[0:3]
	v_mfma_f32_16x16x32_bf16 v[24:27], v[130:133], v[122:125], v[28:31]
	v_mfma_f32_16x16x32_bf16 v[28:31], v[134:137], v[122:125], v[96:99]
	v_mfma_f32_16x16x32_bf16 v[20:23], v[138:141], v[122:125], v[100:103]
	v_mfma_f32_16x16x32_bf16 v[16:19], v[84:87], v[122:125], v[92:95]
	v_mfma_f32_16x16x32_bf16 v[8:11], v[130:133], v[126:129], v[76:79]
	v_mfma_f32_16x16x32_bf16 v[12:15], v[134:137], v[126:129], v[72:75]
	v_mfma_f32_16x16x32_bf16 v[4:7], v[138:141], v[126:129], v[56:59]
	v_mfma_f32_16x16x32_bf16 v[0:3], v[84:87], v[126:129], v[60:63]
	s_setprio 0
	s_nop 0
	v_mul_f32_e32 v58, 0xbfb8aa3b, v64
	v_mul_f32_e32 v59, 0xbfb8aa3b, v65
	v_exp_f32_e32 v58, v58
	v_exp_f32_e32 v59, v59
	v_or_b32_e32 v56, s35, v82
	v_lshl_add_u32 v60, v80, 6, v56
	s_lshl_b32 s0, s34, 6
	v_lshlrev_b32_e32 v56, 5, v81
	v_lshlrev_b32_e32 v57, 3, v83
	v_pk_add_f32 v[58:59], v[58:59], 1.0 op_sel_hi:[1,0]
	v_or3_b32 v56, v56, s0, v57
	v_div_scale_f32 v61, s[0:1], v59, v59, v65
	v_rcp_f32_e32 v62, v61
	v_ashrrev_i32_e32 v57, 31, v56
	s_movk_i32 s4, 0x1600
	s_waitcnt vmcnt(0)
	v_fma_f32 v63, -v61, v62, 1.0
	v_fmac_f32_e32 v62, v63, v62
	v_div_scale_f32 v63, vcc, v65, v59, v65
	v_mul_f32_e32 v72, v63, v62
	v_fma_f32 v73, -v61, v72, v63
	v_fmac_f32_e32 v72, v73, v62
	v_fma_f32 v61, -v61, v72, v63
	v_div_fmas_f32 v61, v61, v62, v72
	v_div_fixup_f32 v59, v61, v59, v65
	v_div_scale_f32 v61, s[0:1], v58, v58, v64
	v_rcp_f32_e32 v62, v61
	s_barrier
	v_fma_f32 v63, -v61, v62, 1.0
	v_fmac_f32_e32 v62, v63, v62
	v_div_scale_f32 v63, vcc, v64, v58, v64
	v_mul_f32_e32 v65, v63, v62
	v_fma_f32 v72, -v61, v65, v63
	v_fmac_f32_e32 v65, v72, v62
	v_fma_f32 v61, -v61, v65, v63
	v_div_fmas_f32 v61, v61, v62, v65
	v_div_fixup_f32 v58, v61, v58, v64
	v_mul_f32_e32 v61, 0xbfb8aa3b, v66
	v_exp_f32_e32 v62, v61
	v_mul_f32_e32 v61, 0xbfb8aa3b, v67
	v_exp_f32_e32 v63, v61
	v_pk_mul_f32 v[58:59], v[68:69], v[58:59]
	s_add_i32 s30, s30, 1
	v_pk_add_f32 v[62:63], v[62:63], 1.0 op_sel_hi:[1,0]
	s_nop 0
	v_div_scale_f32 v61, s[0:1], v63, v63, v67
	v_rcp_f32_e32 v64, v61
	s_nop 0
	v_fma_f32 v65, -v61, v64, 1.0
	v_fmac_f32_e32 v64, v65, v64
	v_div_scale_f32 v65, vcc, v67, v63, v67
	v_mul_f32_e32 v68, v65, v64
	v_fma_f32 v69, -v61, v68, v65
	v_fmac_f32_e32 v68, v69, v64
	v_fma_f32 v61, -v61, v68, v65
	v_div_fmas_f32 v61, v61, v64, v68
	v_div_fixup_f32 v63, v61, v63, v67
	v_div_scale_f32 v61, s[0:1], v62, v62, v66
	v_rcp_f32_e32 v64, v61
	s_nop 0
	v_fma_f32 v65, -v61, v64, 1.0
	v_fmac_f32_e32 v64, v65, v64
	v_div_scale_f32 v65, vcc, v66, v62, v66
	v_mul_f32_e32 v67, v65, v64
	v_fma_f32 v68, -v61, v67, v65
	v_fmac_f32_e32 v67, v68, v64
	v_fma_f32 v61, -v61, v67, v65
	v_div_fmas_f32 v61, v61, v64, v67
	v_div_fixup_f32 v62, v61, v62, v66
	v_mul_f32_e32 v61, 0xbfb8aa3b, v52
	v_exp_f32_e32 v64, v61
	v_mul_f32_e32 v61, 0xbfb8aa3b, v53
	v_exp_f32_e32 v65, v61
	v_pk_mul_f32 v[62:63], v[70:71], v[62:63]
	v_pk_add_f32 v[64:65], v[64:65], 1.0 op_sel_hi:[1,0]
	s_nop 0
	v_div_scale_f32 v61, s[0:1], v65, v65, v53
	v_rcp_f32_e32 v66, v61
	s_nop 0
	v_fma_f32 v67, -v61, v66, 1.0
	v_fmac_f32_e32 v66, v67, v66
; __device__ __forceinline__ unsigned pack2bf(float a, float b) { const f32x2 v = {a, b}; return __builtin_bit_cast(unsigned, __builtin_convertvector(v, bf2_t)); }
;     __device__ __forceinline__ void operator()(const f32x4 (&acc)[4][4], int m0, int n0, int wr, int wc, int fr, int fq, char*) const {
;     ...
;         for (int m = 0; m < 4; ++m) {
;             const int row = m0 + wr * 64 + m * 16 + fr;
;             const int col = (n0 >> 1) + wc * 32 + fq * 8;
;             float o[8];
; #pragma unroll
;             for (int pp = 0; pp < 2; ++pp)
; #pragma unroll
;                 for (int j = 0; j < 4; ++j) { const float g = acc[m][2 * pp][j], u = acc[m][2 * pp + 1][j]; o[pp * 4 + j] = g / (1.f + __expf(-g)) * u; }
;             uint4 w; w.x = pack2bf(o[0], o[1]); w.y = pack2bf(o[2], o[3]); w.z = pack2bf(o[4], o[5]); w.w = pack2bf(o[6], o[7]);
;             *(uint4*)(act + (size_t)row * FFH + col) = w;
	v_div_scale_f32 v67, vcc, v53, v65, v53
	v_mul_f32_e32 v68, v67, v66
	v_fma_f32 v69, -v61, v68, v67
	v_fmac_f32_e32 v68, v69, v66
	v_fma_f32 v61, -v61, v68, v67
	v_div_fmas_f32 v61, v61, v66, v68
	v_div_fixup_f32 v53, v61, v65, v53
	v_div_scale_f32 v61, s[0:1], v64, v64, v52
	v_rcp_f32_e32 v65, v61
	s_nop 0
	v_fma_f32 v66, -v61, v65, 1.0
	v_fmac_f32_e32 v65, v66, v65
	v_div_scale_f32 v66, vcc, v52, v64, v52
	v_mul_f32_e32 v67, v66, v65
	v_fma_f32 v68, -v61, v67, v66
	v_fmac_f32_e32 v67, v68, v65
	v_fma_f32 v61, -v61, v67, v66
	v_div_fmas_f32 v61, v61, v65, v67
	v_div_fixup_f32 v52, v61, v64, v52
	v_pk_mul_f32 v[48:49], v[48:49], v[52:53]
	v_mul_f32_e32 v52, 0xbfb8aa3b, v54
	v_mul_f32_e32 v53, 0xbfb8aa3b, v55
	v_exp_f32_e32 v52, v52
	v_exp_f32_e32 v53, v53
	s_nop 0
	v_pk_add_f32 v[52:53], v[52:53], 1.0 op_sel_hi:[1,0]
	s_nop 0
	v_div_scale_f32 v61, s[0:1], v53, v53, v55
	v_rcp_f32_e32 v64, v61
	s_nop 0
	v_fma_f32 v65, -v61, v64, 1.0
	v_fmac_f32_e32 v64, v65, v64
	v_div_scale_f32 v65, vcc, v55, v53, v55
	v_mul_f32_e32 v66, v65, v64
	v_fma_f32 v67, -v61, v66, v65
	v_fmac_f32_e32 v66, v67, v64
	v_fma_f32 v61, -v61, v66, v65
	v_div_fmas_f32 v61, v61, v64, v66
	v_div_fixup_f32 v53, v61, v53, v55
	v_div_scale_f32 v55, s[0:1], v52, v52, v54
	v_rcp_f32_e32 v61, v55
	s_nop 0
	v_fma_f32 v64, -v55, v61, 1.0
	v_fmac_f32_e32 v61, v64, v61
	v_div_scale_f32 v64, vcc, v54, v52, v54
	v_mul_f32_e32 v65, v64, v61
	v_fma_f32 v66, -v55, v65, v64
	v_fmac_f32_e32 v65, v66, v61
	v_fma_f32 v55, -v55, v65, v64
	v_div_fmas_f32 v55, v55, v61, v65
	v_div_fixup_f32 v52, v55, v52, v54
	v_pk_mul_f32 v[50:51], v[50:51], v[52:53]
	v_cvt_pk_bf16_f32 v54, v48, v49
	v_mov_b64_e32 v[48:49], s[28:29]
	v_cvt_pk_bf16_f32 v52, v58, v59
	v_cvt_pk_bf16_f32 v55, v50, v51
	v_mad_i64_i32 v[58:59], s[0:1], v60, s4, v[48:49]
	v_lshlrev_b64 v[50:51], 1, v[56:57]
	v_cvt_pk_bf16_f32 v53, v62, v63
	v_lshl_add_u64 v[56:57], v[58:59], 0, v[50:51]
	global_store_dwordx4 v[56:57], v[52:55], off
	s_nop 1
	v_mul_f32_e32 v52, 0xbfb8aa3b, v40
	v_mul_f32_e32 v53, 0xbfb8aa3b, v41
	v_exp_f32_e32 v52, v52
	v_exp_f32_e32 v53, v53
	s_nop 0
	v_pk_add_f32 v[52:53], v[52:53], 1.0 op_sel_hi:[1,0]
	s_nop 0
	v_div_scale_f32 v54, s[0:1], v53, v53, v41
	v_rcp_f32_e32 v55, v54
	s_nop 0
	v_fma_f32 v56, -v54, v55, 1.0
	v_fmac_f32_e32 v55, v56, v55
	v_div_scale_f32 v56, vcc, v41, v53, v41
	v_mul_f32_e32 v57, v56, v55
	v_fma_f32 v58, -v54, v57, v56
	v_fmac_f32_e32 v57, v58, v55
	v_fma_f32 v54, -v54, v57, v56
	v_div_fmas_f32 v54, v54, v55, v57
	v_div_fixup_f32 v41, v54, v53, v41
	v_div_scale_f32 v53, s[0:1], v52, v52, v40
	v_rcp_f32_e32 v54, v53
	s_nop 0
	v_fma_f32 v55, -v53, v54, 1.0
	v_fmac_f32_e32 v54, v55, v54
	v_div_scale_f32 v55, vcc, v40, v52, v40
	v_mul_f32_e32 v56, v55, v54
	v_fma_f32 v57, -v53, v56, v55
	v_fmac_f32_e32 v56, v57, v54
	v_fma_f32 v53, -v53, v56, v55
	v_div_fmas_f32 v53, v53, v54, v56
	v_div_fixup_f32 v40, v53, v52, v40
	v_pk_mul_f32 v[40:41], v[44:45], v[40:41]
	v_mul_f32_e32 v44, 0xbfb8aa3b, v42
	v_mul_f32_e32 v45, 0xbfb8aa3b, v43
	v_exp_f32_e32 v44, v44
	v_exp_f32_e32 v45, v45
	s_nop 0
	v_pk_add_f32 v[44:45], v[44:45], 1.0 op_sel_hi:[1,0]
	s_nop 0
	v_div_scale_f32 v52, s[0:1], v45, v45, v43
	v_rcp_f32_e32 v53, v52
	s_nop 0
	v_fma_f32 v54, -v52, v53, 1.0
	v_fmac_f32_e32 v53, v54, v53
	v_div_scale_f32 v54, vcc, v43, v45, v43
	v_mul_f32_e32 v55, v54, v53
	v_fma_f32 v56, -v52, v55, v54
	v_fmac_f32_e32 v55, v56, v53
	v_fma_f32 v52, -v52, v55, v54
	v_div_fmas_f32 v52, v52, v53, v55
	v_div_fixup_f32 v43, v52, v45, v43
	v_div_scale_f32 v45, s[0:1], v44, v44, v42
	v_rcp_f32_e32 v52, v45
	s_nop 0
	v_fma_f32 v53, -v45, v52, 1.0
	v_fmac_f32_e32 v52, v53, v52
	v_div_scale_f32 v53, vcc, v42, v44, v42
	v_mul_f32_e32 v54, v53, v52
	v_fma_f32 v55, -v45, v54, v53
	v_fmac_f32_e32 v54, v55, v52
	v_fma_f32 v45, -v45, v54, v53
	v_div_fmas_f32 v45, v45, v52, v54
	v_div_fixup_f32 v42, v45, v44, v42
	v_mul_f32_e32 v44, 0xbfb8aa3b, v36
	v_mul_f32_e32 v45, 0xbfb8aa3b, v37
	v_exp_f32_e32 v44, v44
	v_exp_f32_e32 v45, v45
	v_pk_mul_f32 v[42:43], v[46:47], v[42:43]
	v_pk_add_f32 v[44:45], v[44:45], 1.0 op_sel_hi:[1,0]
	s_nop 0
	v_div_scale_f32 v46, s[0:1], v45, v45, v37
	v_rcp_f32_e32 v47, v46
	s_nop 0
	v_fma_f32 v52, -v46, v47, 1.0
	v_fmac_f32_e32 v47, v52, v47
	v_div_scale_f32 v52, vcc, v37, v45, v37
	v_mul_f32_e32 v53, v52, v47
	v_fma_f32 v54, -v46, v53, v52
	v_fmac_f32_e32 v53, v54, v47
	v_fma_f32 v46, -v46, v53, v52
	v_div_fmas_f32 v46, v46, v47, v53
	v_div_fixup_f32 v37, v46, v45, v37
	v_div_scale_f32 v45, s[0:1], v44, v44, v36
	v_rcp_f32_e32 v46, v45
	s_nop 0
	v_fma_f32 v47, -v45, v46, 1.0
	v_fmac_f32_e32 v46, v47, v46
	v_div_scale_f32 v47, vcc, v36, v44, v36
	v_mul_f32_e32 v52, v47, v46
	v_fma_f32 v53, -v45, v52, v47
	v_fmac_f32_e32 v52, v53, v46
	v_fma_f32 v45, -v45, v52, v47
	v_div_fmas_f32 v45, v45, v46, v52
	v_div_fixup_f32 v36, v45, v44, v36
	v_pk_mul_f32 v[36:37], v[32:33], v[36:37]
	v_mul_f32_e32 v32, 0xbfb8aa3b, v38
	v_mul_f32_e32 v33, 0xbfb8aa3b, v39
	v_exp_f32_e32 v32, v32
	v_exp_f32_e32 v33, v33
	s_nop 0
	v_pk_add_f32 v[32:33], v[32:33], 1.0 op_sel_hi:[1,0]
	s_nop 0
	v_div_scale_f32 v44, s[0:1], v33, v33, v39
	v_rcp_f32_e32 v45, v44
	s_nop 0
	v_fma_f32 v46, -v44, v45, 1.0
	v_fmac_f32_e32 v45, v46, v45
	v_div_scale_f32 v46, vcc, v39, v33, v39
	v_mul_f32_e32 v47, v46, v45
	v_fma_f32 v52, -v44, v47, v46
	v_fmac_f32_e32 v47, v52, v45
	v_fma_f32 v44, -v44, v47, v46
	v_div_fmas_f32 v44, v44, v45, v47
	v_div_fixup_f32 v33, v44, v33, v39
	v_div_scale_f32 v39, s[0:1], v32, v32, v38
	v_rcp_f32_e32 v44, v39
	s_nop 0
	v_fma_f32 v45, -v39, v44, 1.0
	v_fmac_f32_e32 v44, v45, v44
	v_div_scale_f32 v45, vcc, v38, v32, v38
; __device__ __forceinline__ unsigned pack2bf(float a, float b) { const f32x2 v = {a, b}; return __builtin_bit_cast(unsigned, __builtin_convertvector(v, bf2_t)); }
;     __device__ __forceinline__ void operator()(const f32x4 (&acc)[4][4], int m0, int n0, int wr, int wc, int fr, int fq, char*) const {
;     ...
;         for (int m = 0; m < 4; ++m) {
;             const int row = m0 + wr * 64 + m * 16 + fr;
;             const int col = (n0 >> 1) + wc * 32 + fq * 8;
;             float o[8];
; #pragma unroll
;             for (int pp = 0; pp < 2; ++pp)
; #pragma unroll
;                 for (int j = 0; j < 4; ++j) { const float g = acc[m][2 * pp][j], u = acc[m][2 * pp + 1][j]; o[pp * 4 + j] = g / (1.f + __expf(-g)) * u; }
;             uint4 w; w.x = pack2bf(o[0], o[1]); w.y = pack2bf(o[2], o[3]); w.z = pack2bf(o[4], o[5]); w.w = pack2bf(o[6], o[7]);
;             *(uint4*)(act + (size_t)row * FFH + col) = w;
	v_mul_f32_e32 v46, v45, v44
	v_fma_f32 v47, -v39, v46, v45
	v_fmac_f32_e32 v46, v47, v44
	v_fma_f32 v39, -v39, v46, v45
	v_div_fmas_f32 v39, v39, v44, v46
	v_div_fixup_f32 v32, v39, v32, v38
	v_or_b32_e32 v44, 16, v60
	v_pk_mul_f32 v[38:39], v[34:35], v[32:33]
	v_cvt_pk_bf16_f32 v34, v36, v37
	v_mad_i64_i32 v[36:37], s[0:1], v44, s4, v[48:49]
	v_cvt_pk_bf16_f32 v32, v40, v41
	v_cvt_pk_bf16_f32 v33, v42, v43
	v_cvt_pk_bf16_f32 v35, v38, v39
	v_lshl_add_u64 v[36:37], v[36:37], 0, v[50:51]
	global_store_dwordx4 v[36:37], v[32:35], off
	s_nop 1
	v_mul_f32_e32 v32, 0xbfb8aa3b, v24
	v_mul_f32_e32 v33, 0xbfb8aa3b, v25
	v_exp_f32_e32 v32, v32
	v_exp_f32_e32 v33, v33
	s_nop 0
	v_pk_add_f32 v[32:33], v[32:33], 1.0 op_sel_hi:[1,0]
	s_nop 0
	v_div_scale_f32 v34, s[0:1], v33, v33, v25
	v_rcp_f32_e32 v35, v34
	s_nop 0
	v_fma_f32 v36, -v34, v35, 1.0
	v_fmac_f32_e32 v35, v36, v35
	v_div_scale_f32 v36, vcc, v25, v33, v25
	v_mul_f32_e32 v37, v36, v35
	v_fma_f32 v38, -v34, v37, v36
	v_fmac_f32_e32 v37, v38, v35
	v_fma_f32 v34, -v34, v37, v36
	v_div_fmas_f32 v34, v34, v35, v37
	v_div_fixup_f32 v25, v34, v33, v25
	v_div_scale_f32 v33, s[0:1], v32, v32, v24
	v_rcp_f32_e32 v34, v33
	s_nop 0
	v_fma_f32 v35, -v33, v34, 1.0
	v_fmac_f32_e32 v34, v35, v34
	v_div_scale_f32 v35, vcc, v24, v32, v24
	v_mul_f32_e32 v36, v35, v34
	v_fma_f32 v37, -v33, v36, v35
	v_fmac_f32_e32 v36, v37, v34
	v_fma_f32 v33, -v33, v36, v35
	v_div_fmas_f32 v33, v33, v34, v36
	v_div_fixup_f32 v24, v33, v32, v24
	v_pk_mul_f32 v[24:25], v[28:29], v[24:25]
	v_mul_f32_e32 v28, 0xbfb8aa3b, v26
	v_mul_f32_e32 v29, 0xbfb8aa3b, v27
	v_exp_f32_e32 v28, v28
	v_exp_f32_e32 v29, v29
	s_nop 0
	v_pk_add_f32 v[28:29], v[28:29], 1.0 op_sel_hi:[1,0]
	s_nop 0
	v_div_scale_f32 v32, s[0:1], v29, v29, v27
	v_rcp_f32_e32 v33, v32
	s_nop 0
	v_fma_f32 v34, -v32, v33, 1.0
	v_fmac_f32_e32 v33, v34, v33
	v_div_scale_f32 v34, vcc, v27, v29, v27
	v_mul_f32_e32 v35, v34, v33
	v_fma_f32 v36, -v32, v35, v34
	v_fmac_f32_e32 v35, v36, v33
	v_fma_f32 v32, -v32, v35, v34
	v_div_fmas_f32 v32, v32, v33, v35
	v_div_fixup_f32 v27, v32, v29, v27
	v_div_scale_f32 v29, s[0:1], v28, v28, v26
	v_rcp_f32_e32 v32, v29
	s_nop 0
	v_fma_f32 v33, -v29, v32, 1.0
	v_fmac_f32_e32 v32, v33, v32
	v_div_scale_f32 v33, vcc, v26, v28, v26
	v_mul_f32_e32 v34, v33, v32
	v_fma_f32 v35, -v29, v34, v33
	v_fmac_f32_e32 v34, v35, v32
	v_fma_f32 v29, -v29, v34, v33
	v_div_fmas_f32 v29, v29, v32, v34
	v_div_fixup_f32 v26, v29, v28, v26
	v_mul_f32_e32 v28, 0xbfb8aa3b, v20
	v_mul_f32_e32 v29, 0xbfb8aa3b, v21
	v_exp_f32_e32 v28, v28
	v_exp_f32_e32 v29, v29
	v_pk_mul_f32 v[26:27], v[30:31], v[26:27]
	v_pk_add_f32 v[28:29], v[28:29], 1.0 op_sel_hi:[1,0]
	s_nop 0
	v_div_scale_f32 v30, s[0:1], v29, v29, v21
	v_rcp_f32_e32 v31, v30
	s_nop 0
	v_fma_f32 v32, -v30, v31, 1.0
	v_fmac_f32_e32 v31, v32, v31
	v_div_scale_f32 v32, vcc, v21, v29, v21
	v_mul_f32_e32 v33, v32, v31
	v_fma_f32 v34, -v30, v33, v32
	v_fmac_f32_e32 v33, v34, v31
	v_fma_f32 v30, -v30, v33, v32
	v_div_fmas_f32 v30, v30, v31, v33
	v_div_fixup_f32 v21, v30, v29, v21
	v_div_scale_f32 v29, s[0:1], v28, v28, v20
	v_rcp_f32_e32 v30, v29
	s_nop 0
	v_fma_f32 v31, -v29, v30, 1.0
	v_fmac_f32_e32 v30, v31, v30
	v_div_scale_f32 v31, vcc, v20, v28, v20
	v_mul_f32_e32 v32, v31, v30
	v_fma_f32 v33, -v29, v32, v31
	v_fmac_f32_e32 v32, v33, v30
	v_fma_f32 v29, -v29, v32, v31
	v_div_fmas_f32 v29, v29, v30, v32
	v_div_fixup_f32 v20, v29, v28, v20
	v_pk_mul_f32 v[20:21], v[16:17], v[20:21]
	v_mul_f32_e32 v16, 0xbfb8aa3b, v22
	v_mul_f32_e32 v17, 0xbfb8aa3b, v23
	v_exp_f32_e32 v16, v16
	v_exp_f32_e32 v17, v17
	s_nop 0
	v_pk_add_f32 v[16:17], v[16:17], 1.0 op_sel_hi:[1,0]
	s_nop 0
	v_div_scale_f32 v28, s[0:1], v17, v17, v23
	v_rcp_f32_e32 v29, v28
	s_nop 0
	v_fma_f32 v30, -v28, v29, 1.0
	v_fmac_f32_e32 v29, v30, v29
	v_div_scale_f32 v30, vcc, v23, v17, v23
	v_mul_f32_e32 v31, v30, v29
	v_fma_f32 v32, -v28, v31, v30
	v_fmac_f32_e32 v31, v32, v29
	v_fma_f32 v28, -v28, v31, v30
	v_div_fmas_f32 v28, v28, v29, v31
	v_div_fixup_f32 v17, v28, v17, v23
	v_div_scale_f32 v23, s[0:1], v16, v16, v22
	v_rcp_f32_e32 v28, v23
	s_nop 0
	v_fma_f32 v29, -v23, v28, 1.0
	v_fmac_f32_e32 v28, v29, v28
	v_div_scale_f32 v29, vcc, v22, v16, v22
	v_mul_f32_e32 v30, v29, v28
	v_fma_f32 v31, -v23, v30, v29
	v_fmac_f32_e32 v30, v31, v28
	v_fma_f32 v23, -v23, v30, v29
	v_div_fmas_f32 v23, v23, v28, v30
	v_div_fixup_f32 v16, v23, v16, v22
	v_or_b32_e32 v28, 32, v60
	v_pk_mul_f32 v[22:23], v[18:19], v[16:17]
; __device__ __forceinline__ unsigned pack2bf(float a, float b) { const f32x2 v = {a, b}; return __builtin_bit_cast(unsigned, __builtin_convertvector(v, bf2_t)); }
;     __device__ __forceinline__ void operator()(const f32x4 (&acc)[4][4], int m0, int n0, int wr, int wc, int fr, int fq, char*) const {
;     ...
;         for (int m = 0; m < 4; ++m) {
;             const int row = m0 + wr * 64 + m * 16 + fr;
;             const int col = (n0 >> 1) + wc * 32 + fq * 8;
;             float o[8];
; #pragma unroll
;             for (int pp = 0; pp < 2; ++pp)
; #pragma unroll
;                 for (int j = 0; j < 4; ++j) { const float g = acc[m][2 * pp][j], u = acc[m][2 * pp + 1][j]; o[pp * 4 + j] = g / (1.f + __expf(-g)) * u; }
;             uint4 w; w.x = pack2bf(o[0], o[1]); w.y = pack2bf(o[2], o[3]); w.z = pack2bf(o[4], o[5]); w.w = pack2bf(o[6], o[7]);
;             *(uint4*)(act + (size_t)row * FFH + col) = w;
; __device__ __forceinline__ void phase_ffn_in(const Params& p, int layer, char* smem) {
;     ...
;     int mt, nt;
;     for (int it = 0; gemm_unit(it, 44, last ? 2 : 0, mt, nt); ++it) gemm_tile(A, 1024, Bt, 1024, 1024, mt * 128, nt * 128, epi, smem);
	v_cvt_pk_bf16_f32 v18, v20, v21
	v_mad_i64_i32 v[20:21], s[0:1], v28, s4, v[48:49]
	v_cvt_pk_bf16_f32 v16, v24, v25
	v_cvt_pk_bf16_f32 v17, v26, v27
	v_cvt_pk_bf16_f32 v19, v22, v23
	v_lshl_add_u64 v[20:21], v[20:21], 0, v[50:51]
	global_store_dwordx4 v[20:21], v[16:19], off
	s_nop 1
	v_mul_f32_e32 v16, 0xbfb8aa3b, v8
	v_mul_f32_e32 v17, 0xbfb8aa3b, v9
	v_exp_f32_e32 v16, v16
	v_exp_f32_e32 v17, v17
	s_nop 0
	v_pk_add_f32 v[16:17], v[16:17], 1.0 op_sel_hi:[1,0]
	s_nop 0
	v_div_scale_f32 v18, s[0:1], v17, v17, v9
	v_rcp_f32_e32 v19, v18
	s_nop 0
	v_fma_f32 v20, -v18, v19, 1.0
	v_fmac_f32_e32 v19, v20, v19
	v_div_scale_f32 v20, vcc, v9, v17, v9
	v_mul_f32_e32 v21, v20, v19
	v_fma_f32 v22, -v18, v21, v20
	v_fmac_f32_e32 v21, v22, v19
	v_fma_f32 v18, -v18, v21, v20
	v_div_fmas_f32 v18, v18, v19, v21
	v_div_fixup_f32 v9, v18, v17, v9
	v_div_scale_f32 v17, s[0:1], v16, v16, v8
	v_rcp_f32_e32 v18, v17
	s_nop 0
	v_fma_f32 v19, -v17, v18, 1.0
	v_fmac_f32_e32 v18, v19, v18
	v_div_scale_f32 v19, vcc, v8, v16, v8
	v_mul_f32_e32 v20, v19, v18
	v_fma_f32 v21, -v17, v20, v19
	v_fmac_f32_e32 v20, v21, v18
	v_fma_f32 v17, -v17, v20, v19
	v_div_fmas_f32 v17, v17, v18, v20
	v_div_fixup_f32 v8, v17, v16, v8
	v_pk_mul_f32 v[8:9], v[12:13], v[8:9]
	v_mul_f32_e32 v12, 0xbfb8aa3b, v10
	v_mul_f32_e32 v13, 0xbfb8aa3b, v11
	v_exp_f32_e32 v12, v12
	v_exp_f32_e32 v13, v13
	s_nop 0
	v_pk_add_f32 v[12:13], v[12:13], 1.0 op_sel_hi:[1,0]
	s_nop 0
	v_div_scale_f32 v16, s[0:1], v13, v13, v11
	v_rcp_f32_e32 v17, v16
	s_nop 0
	v_fma_f32 v18, -v16, v17, 1.0
	v_fmac_f32_e32 v17, v18, v17
	v_div_scale_f32 v18, vcc, v11, v13, v11
	v_mul_f32_e32 v19, v18, v17
	v_fma_f32 v20, -v16, v19, v18
	v_fmac_f32_e32 v19, v20, v17
	v_fma_f32 v16, -v16, v19, v18
	v_div_fmas_f32 v16, v16, v17, v19
	v_div_fixup_f32 v11, v16, v13, v11
	v_div_scale_f32 v13, s[0:1], v12, v12, v10
	v_rcp_f32_e32 v16, v13
	s_nop 0
	v_fma_f32 v17, -v13, v16, 1.0
	v_fmac_f32_e32 v16, v17, v16
	v_div_scale_f32 v17, vcc, v10, v12, v10
	v_mul_f32_e32 v18, v17, v16
	v_fma_f32 v19, -v13, v18, v17
	v_fmac_f32_e32 v18, v19, v16
	v_fma_f32 v13, -v13, v18, v17
	v_div_fmas_f32 v13, v13, v16, v18
	v_div_fixup_f32 v10, v13, v12, v10
	v_mul_f32_e32 v12, 0xbfb8aa3b, v4
	v_mul_f32_e32 v13, 0xbfb8aa3b, v5
	v_exp_f32_e32 v12, v12
	v_exp_f32_e32 v13, v13
	v_pk_mul_f32 v[10:11], v[14:15], v[10:11]
	v_pk_add_f32 v[12:13], v[12:13], 1.0 op_sel_hi:[1,0]
	s_nop 0
	v_div_scale_f32 v14, s[0:1], v13, v13, v5
	v_rcp_f32_e32 v15, v14
	s_nop 0
	v_fma_f32 v16, -v14, v15, 1.0
	v_fmac_f32_e32 v15, v16, v15
	v_div_scale_f32 v16, vcc, v5, v13, v5
	v_mul_f32_e32 v17, v16, v15
	v_fma_f32 v18, -v14, v17, v16
	v_fmac_f32_e32 v17, v18, v15
	v_fma_f32 v14, -v14, v17, v16
	v_div_fmas_f32 v14, v14, v15, v17
	v_div_fixup_f32 v5, v14, v13, v5
	v_div_scale_f32 v13, s[0:1], v12, v12, v4
	v_rcp_f32_e32 v14, v13
	s_nop 0
	v_fma_f32 v15, -v13, v14, 1.0
	v_fmac_f32_e32 v14, v15, v14
	v_div_scale_f32 v15, vcc, v4, v12, v4
	v_mul_f32_e32 v16, v15, v14
	v_fma_f32 v17, -v13, v16, v15
	v_fmac_f32_e32 v16, v17, v14
	v_fma_f32 v13, -v13, v16, v15
	v_div_fmas_f32 v13, v13, v14, v16
	v_div_fixup_f32 v4, v13, v12, v4
	v_pk_mul_f32 v[4:5], v[0:1], v[4:5]
	v_mul_f32_e32 v0, 0xbfb8aa3b, v6
	v_mul_f32_e32 v1, 0xbfb8aa3b, v7
	v_exp_f32_e32 v0, v0
	v_exp_f32_e32 v1, v1
	s_nop 0
	v_pk_add_f32 v[0:1], v[0:1], 1.0 op_sel_hi:[1,0]
	s_nop 0
	v_div_scale_f32 v12, s[0:1], v1, v1, v7
	v_rcp_f32_e32 v13, v12
	s_nop 0
	v_fma_f32 v14, -v12, v13, 1.0
	v_fmac_f32_e32 v13, v14, v13
	v_div_scale_f32 v14, vcc, v7, v1, v7
	v_mul_f32_e32 v15, v14, v13
	v_fma_f32 v16, -v12, v15, v14
	v_fmac_f32_e32 v15, v16, v13
	v_fma_f32 v12, -v12, v15, v14
	v_div_fmas_f32 v12, v12, v13, v15
	v_div_fixup_f32 v1, v12, v1, v7
	v_div_scale_f32 v7, s[0:1], v0, v0, v6
	v_rcp_f32_e32 v12, v7
	s_nop 0
	v_fma_f32 v13, -v7, v12, 1.0
	v_fmac_f32_e32 v12, v13, v12
	v_div_scale_f32 v13, vcc, v6, v0, v6
	v_mul_f32_e32 v14, v13, v12
	v_fma_f32 v15, -v7, v14, v13
	v_fmac_f32_e32 v14, v15, v12
	v_fma_f32 v7, -v7, v14, v13
	v_div_fmas_f32 v7, v7, v12, v14
	v_div_fixup_f32 v0, v7, v0, v6
	v_or_b32_e32 v12, 48, v60
	v_pk_mul_f32 v[6:7], v[2:3], v[0:1]
	v_cvt_pk_bf16_f32 v2, v4, v5
	v_mad_i64_i32 v[4:5], s[0:1], v12, s4, v[48:49]
	s_mul_i32 s0, s30, s31
	s_add_i32 s0, s0, s91
	v_cvt_pk_bf16_f32 v0, v8, v9
	v_cvt_pk_bf16_f32 v1, v10, v11
	v_cvt_pk_bf16_f32 v3, v6, v7
	v_lshl_add_u64 v[4:5], v[4:5], 0, v[50:51]
	s_cmp_ge_u32 s0, s83
	global_store_dwordx4 v[4:5], v[0:3], off
	s_cbranch_scc0 .LBB0_152

; __device__ __forceinline__ int opaque_tid() { int t = threadIdx.x; asm volatile("" : "+v"(t)); return t; }
; template <class Epi>
; __device__ __forceinline__ void gemm_tile(const bf16_t* A, int lda, const bf16_t* Bt, int ldb, int K, int m0, int n0, const Epi& epi, char* smem) {
;     const int tid = opaque_tid(), lane = tid & 63, wid = tid >> 6, wr = wid >> 1, wc = wid & 1, fr = lane & 15, fq = lane >> 4;
;     f32x4 acc[4][4];
; #pragma unroll
;     for (int m = 0; m < 4; ++m)
; #pragma unroll
;         for (int n = 0; n < 4; ++n) acc[m][n] = (f32x4){0.f, 0.f, 0.f, 0.f};
;     const int lr = lane >> 3;
;     const bf16_t* Ag[4]; const bf16_t* Bg[4];
; #pragma unroll
;     for (int i = 0; i < 4; ++i) {
;         const int r = (wid + 4 * i) * 8 + lr, lc = (lane & 7) ^ ((r >> 1) & 7);
;         Ag[i] = A + (size_t)(m0 + r) * lda + lc * 8; Bg[i] = Bt + (size_t)(n0 + r) * ldb + lc * 8;
;     }
;     const unsigned lds0 = (unsigned)(uintptr_t)smem;
;     const int rsw = (fr >> 1) & 7;
;     const int aofs = (wr * 64 + fr) * 128, bofs = 16384 + (wc * 64 + fr) * 128;
;     const int nk = K >> 6;
;     ...
;     G_ISSUE(0, 0)
;     asm volatile("s_waitcnt vmcnt(0)" ::: "memory");
;     __syncthreads();
.LBB0_181:
	s_waitcnt vmcnt(1)
	v_mov_b32_e32 v16, v109
	s_lshl_b32 s42, s35, 7
	v_ashrrev_i32_e32 v17, 6, v16
	v_bfe_u32 v18, v16, 3, 3
	v_lshlrev_b32_e32 v19, 3, v17
	s_waitcnt vmcnt(2)
	v_or_b32_e32 v12, v19, v18
	s_waitcnt vmcnt(0)
	v_lshrrev_b32_e32 v20, 1, v12
	s_waitcnt vmcnt(1)
	v_xor_b32_e32 v2, v20, v16
	s_lshl_b32 s44, s34, 7
	v_lshlrev_b32_e32 v2, 4, v2
	s_waitcnt vmcnt(0)
	v_add_u32_e32 v6, 32, v12
	v_add_u32_e32 v10, 64, v12
	v_add_u32_e32 v14, 0x60, v12
	v_add_u32_e32 v0, s42, v12
	v_and_b32_e32 v104, 0x70, v2
	v_add_u32_e32 v2, s44, v12
	v_add_u32_e32 v4, s42, v6
	v_add_u32_e32 v6, s44, v6
	v_add_u32_e32 v8, s42, v10
	v_add_u32_e32 v10, s44, v10
	v_add_u32_e32 v12, s42, v14
	v_add_u32_e32 v14, s44, v14
	v_ashrrev_i32_e32 v1, 31, v0
	v_ashrrev_i32_e32 v3, 31, v2
	v_readlane_b32 s0, v251, 36
	v_ashrrev_i32_e32 v7, 31, v6
	v_ashrrev_i32_e32 v11, 31, v10
	v_ashrrev_i32_e32 v15, 31, v14
	v_lshlrev_b64 v[0:1], 11, v[0:1]
	v_lshlrev_b64 v[2:3], 11, v[2:3]
	v_readlane_b32 s1, v251, 37
	v_lshlrev_b64 v[6:7], 11, v[6:7]
	v_lshlrev_b64 v[10:11], 11, v[10:11]
	v_lshlrev_b64 v[14:15], 11, v[14:15]
	v_lshlrev_b32_e32 v84, 10, v17
	v_lshl_add_u64 v[0:1], s[40:41], 0, v[0:1]
	v_lshl_add_u64 v[2:3], s[0:1], 0, v[2:3]
	v_lshl_add_u64 v[6:7], s[0:1], 0, v[6:7]
	v_lshl_add_u64 v[10:11], s[0:1], 0, v[10:11]
	v_lshl_add_u64 v[14:15], s[0:1], 0, v[14:15]
	v_readfirstlane_b32 s0, v84
	v_lshl_add_u64 v[0:1], v[0:1], 0, v[104:105]
	s_mov_b32 m0, s0
	v_ashrrev_i32_e32 v5, 31, v4
	global_load_lds_dwordx4 v[0:1], off
	v_add_u32_e32 v0, 0x4000, v84
	v_lshlrev_b64 v[4:5], 11, v[4:5]
	v_readfirstlane_b32 s0, v0
	v_add_u32_e32 v0, 0x1000, v84
	v_lshl_add_u64 v[2:3], v[2:3], 0, v[104:105]
	v_lshl_add_u64 v[4:5], s[40:41], 0, v[4:5]
	v_ashrrev_i32_e32 v9, 31, v8
	s_mov_b32 m0, s0
	v_readfirstlane_b32 s0, v0
	v_add_u32_e32 v0, 0x5000, v84
	v_lshl_add_u64 v[4:5], v[4:5], 0, v[104:105]
	v_lshlrev_b64 v[8:9], 11, v[8:9]
	global_load_lds_dwordx4 v[2:3], off
	s_mov_b32 m0, s0
	v_readfirstlane_b32 s0, v0
	v_add_u32_e32 v0, 0x2000, v84
	v_lshl_add_u64 v[6:7], v[6:7], 0, v[104:105]
	v_lshl_add_u64 v[8:9], s[40:41], 0, v[8:9]
	v_ashrrev_i32_e32 v13, 31, v12
	global_load_lds_dwordx4 v[4:5], off
	s_mov_b32 m0, s0
	v_readfirstlane_b32 s0, v0
	v_add_u32_e32 v0, 0x6000, v84
	v_lshl_add_u64 v[8:9], v[8:9], 0, v[104:105]
	v_lshlrev_b64 v[12:13], 11, v[12:13]
	global_load_lds_dwordx4 v[6:7], off
	s_mov_b32 m0, s0
	v_readfirstlane_b32 s0, v0
	v_add_u32_e32 v0, 0x3000, v84
	v_lshl_add_u64 v[10:11], v[10:11], 0, v[104:105]
	v_lshl_add_u64 v[12:13], s[40:41], 0, v[12:13]
	global_load_lds_dwordx4 v[8:9], off
	s_mov_b32 m0, s0
	v_readfirstlane_b32 s0, v0
	v_add_u32_e32 v0, 0x7000, v84
	v_lshl_add_u64 v[12:13], v[12:13], 0, v[104:105]
	global_load_lds_dwordx4 v[10:11], off
	s_mov_b32 m0, s0
	v_readfirstlane_b32 s0, v0
	v_lshl_add_u64 v[14:15], v[14:15], 0, v[104:105]
	global_load_lds_dwordx4 v[12:13], off
	s_mov_b32 m0, s0
	v_and_b32_e32 v83, 15, v16
	global_load_lds_dwordx4 v[14:15], off
	v_bfe_u32 v81, v16, 4, 2
	v_lshrrev_b32_e32 v1, 1, v16
	v_bfe_u32 v2, v16, 1, 3
	v_ashrrev_i32_e32 v82, 7, v16
	v_and_b32_e32 v80, 1, v17
	v_lshlrev_b32_e32 v0, 7, v83
	v_bitop3_b32 v1, v81, v1, 7 bitop3:0x78
	v_bitop3_b32 v2, v81, v2, 4 bitop3:0x36
	v_lshl_or_b32 v3, v80, 13, v0
	v_lshl_or_b32 v0, v82, 13, v0
	v_lshlrev_b32_e32 v1, 4, v1
	v_lshlrev_b32_e32 v2, 4, v2
	v_or_b32_e32 v88, v0, v1
	v_or_b32_e32 v86, v0, v2
	v_or_b32_e32 v0, s42, v18
	v_add_u32_e32 v0, v0, v19
	v_or_b32_e32 v87, v3, v1
	v_or_b32_e32 v85, v3, v2
	v_ashrrev_i32_e32 v1, 31, v0
	v_bitop3_b32 v2, v20, 7, v16 bitop3:0x48
	v_lshlrev_b64 v[0:1], 11, v[0:1]
	v_lshlrev_b32_e32 v2, 4, v2
	v_readlane_b32 s0, v252, 55
	v_or_b32_e32 v0, v0, v2
	v_readlane_b32 s1, v252, 56
	v_readlane_b32 s4, v252, 59
	v_readlane_b32 s5, v252, 60
	v_lshl_add_u64 v[64:65], s[0:1], 0, v[0:1]
	v_or_b32_e32 v0, s44, v18
	v_add_u32_e32 v0, v0, v19
	v_ashrrev_i32_e32 v1, 31, v0
	v_lshlrev_b64 v[0:1], 11, v[0:1]
	v_or_b32_e32 v0, v0, v2
	v_or_b32_e32 v3, 32, v18
	v_lshl_add_u64 v[66:67], s[4:5], 0, v[0:1]
	v_or_b32_e32 v0, s42, v3
	v_add_u32_e32 v0, v0, v19
	v_ashrrev_i32_e32 v1, 31, v0
	v_lshlrev_b64 v[0:1], 11, v[0:1]
	v_or_b32_e32 v0, v0, v2
	v_lshl_add_u64 v[68:69], s[0:1], 0, v[0:1]
	v_or_b32_e32 v0, s44, v3
	v_add_u32_e32 v0, v0, v19
	v_ashrrev_i32_e32 v1, 31, v0
	v_lshlrev_b64 v[0:1], 11, v[0:1]
	v_or_b32_e32 v0, v0, v2
	v_or_b32_e32 v3, 64, v18
	v_lshl_add_u64 v[70:71], s[4:5], 0, v[0:1]
	v_or_b32_e32 v0, s42, v3
	v_add_u32_e32 v0, v0, v19
	v_ashrrev_i32_e32 v1, 31, v0
	v_lshlrev_b64 v[0:1], 11, v[0:1]
	v_or_b32_e32 v0, v0, v2
	v_lshl_add_u64 v[72:73], s[0:1], 0, v[0:1]
	v_or_b32_e32 v0, s44, v3
	v_add_u32_e32 v0, v0, v19
	v_ashrrev_i32_e32 v1, 31, v0
	v_lshlrev_b64 v[0:1], 11, v[0:1]
	v_or_b32_e32 v0, v0, v2
	v_or_b32_e32 v3, 0x60, v18
	v_lshl_add_u64 v[74:75], s[4:5], 0, v[0:1]
	v_or_b32_e32 v0, s42, v3
	v_add_u32_e32 v0, v0, v19
	v_ashrrev_i32_e32 v1, 31, v0
	v_lshlrev_b64 v[0:1], 11, v[0:1]
	v_or_b32_e32 v0, v0, v2
	v_lshl_add_u64 v[76:77], s[0:1], 0, v[0:1]
	v_or_b32_e32 v0, s44, v3
	v_add_u32_e32 v0, v0, v19
	v_ashrrev_i32_e32 v1, 31, v0
	v_lshlrev_b64 v[0:1], 11, v[0:1]
	s_waitcnt vmcnt(0)
; template <class Epi>
; __device__ __forceinline__ void gemm_tile(const bf16_t* A, int lda, const bf16_t* Bt, int ldb, int K, int m0, int n0, const Epi& epi, char* smem) {
;     ...
;     f32x4 acc[4][4];
; #pragma unroll
;     for (int m = 0; m < 4; ++m)
; #pragma unroll
;         for (int n = 0; n < 4; ++n) acc[m][n] = (f32x4){0.f, 0.f, 0.f, 0.f};
;     const int lr = lane >> 3;
;     const bf16_t* Ag[4]; const bf16_t* Bg[4];
; #pragma unroll
;     for (int i = 0; i < 4; ++i) {
;         const int r = (wid + 4 * i) * 8 + lr, lc = (lane & 7) ^ ((r >> 1) & 7);
;         Ag[i] = A + (size_t)(m0 + r) * lda + lc * 8; Bg[i] = Bt + (size_t)(n0 + r) * ldb + lc * 8;
;     }
;     const unsigned lds0 = (unsigned)(uintptr_t)smem;
;     const int rsw = (fr >> 1) & 7;
;     const int aofs = (wr * 64 + fr) * 128, bofs = 16384 + (wc * 64 + fr) * 128;
;     const int nk = K >> 6;
;     ...
;     G_ISSUE(0, 0)
;     asm volatile("s_waitcnt vmcnt(0)" ::: "memory");
;     __syncthreads();
;     for (int kt = 0; kt < nk; ++kt) {
;         const int st = (kt & 1) * 32768;
;         if (kt + 1 < nk) G_ISSUE(((kt + 1) & 1) * 32768, (kt + 1) * 64)
;         {
;             bf16x8 a0[4], b0[4], a1[4], b1[4];
;             const int ch0 = ((0 + fq) ^ rsw) << 4, ch1 = ((4 + fq) ^ rsw) << 4;
; #pragma unroll
;             for (int m = 0; m < 4; ++m) a0[m] = *(const bf16x8*)(smem + st + aofs + m * 2048 + ch0);
; #pragma unroll
;             for (int n = 0; n < 4; ++n) b0[n] = *(const bf16x8*)(smem + st + bofs + n * 2048 + ch0);
;             __builtin_amdgcn_sched_barrier(0);
; #pragma unroll
;             for (int m = 0; m < 4; ++m) a1[m] = *(const bf16x8*)(smem + st + aofs + m * 2048 + ch1);
; #pragma unroll
;             for (int n = 0; n < 4; ++n) b1[n] = *(const bf16x8*)(smem + st + bofs + n * 2048 + ch1);
;             __builtin_amdgcn_sched_barrier(0);
;             __builtin_amdgcn_s_setprio(1);
; #pragma unroll
;             for (int m = 0; m < 4; ++m)
; #pragma unroll
;                 for (int n = 0; n < 4; ++n) acc[m][n] = __builtin_amdgcn_mfma_f32_16x16x32_bf16(b0[n], a0[m], acc[m][n], 0, 0, 0);
;             __builtin_amdgcn_sched_barrier(0);
; #pragma unroll
;             for (int m = 0; m < 4; ++m)
; #pragma unroll
;                 for (int n = 0; n < 4; ++n) acc[m][n] = __builtin_amdgcn_mfma_f32_16x16x32_bf16(b1[n], a1[m], acc[m][n], 0, 0, 0);
	v_or_b32_e32 v0, v0, v2
	v_lshl_add_u64 v[78:79], s[4:5], 0, v[0:1]
	v_mov_b32_e32 v0, 0
	s_mov_b64 s[0:1], 0
	s_mov_b32 s43, 0x8000
	v_mov_b32_e32 v1, v0
	v_mov_b32_e32 v2, v0
	v_mov_b32_e32 v3, v0
	v_mov_b32_e32 v4, v0
	v_mov_b32_e32 v5, v0
	v_mov_b32_e32 v6, v0
	v_mov_b32_e32 v7, v0
	v_mov_b32_e32 v8, v0
	v_mov_b32_e32 v9, v0
	v_mov_b32_e32 v10, v0
	v_mov_b32_e32 v11, v0
	v_mov_b32_e32 v12, v0
	v_mov_b32_e32 v13, v0
	v_mov_b32_e32 v14, v0
	v_mov_b32_e32 v15, v0
	v_mov_b32_e32 v16, v0
	v_mov_b32_e32 v17, v0
	v_mov_b32_e32 v18, v0
	v_mov_b32_e32 v19, v0
	v_mov_b32_e32 v20, v0
	v_mov_b32_e32 v21, v0
	v_mov_b32_e32 v22, v0
	v_mov_b32_e32 v23, v0
	v_mov_b32_e32 v24, v0
	v_mov_b32_e32 v25, v0
	v_mov_b32_e32 v26, v0
	v_mov_b32_e32 v27, v0
	v_mov_b32_e32 v36, v0
	v_mov_b32_e32 v37, v0
	v_mov_b32_e32 v38, v0
	v_mov_b32_e32 v39, v0
	v_mov_b32_e32 v28, v0
	v_mov_b32_e32 v29, v0
	v_mov_b32_e32 v30, v0
	v_mov_b32_e32 v31, v0
	v_mov_b32_e32 v32, v0
	v_mov_b32_e32 v33, v0
	v_mov_b32_e32 v34, v0
	v_mov_b32_e32 v35, v0
	v_mov_b32_e32 v40, v0
	v_mov_b32_e32 v41, v0
	v_mov_b32_e32 v42, v0
	v_mov_b32_e32 v43, v0
	v_mov_b32_e32 v44, v0
	v_mov_b32_e32 v45, v0
	v_mov_b32_e32 v46, v0
	v_mov_b32_e32 v47, v0
	v_mov_b32_e32 v48, v0
	v_mov_b32_e32 v49, v0
	v_mov_b32_e32 v50, v0
	v_mov_b32_e32 v51, v0
	v_mov_b32_e32 v52, v0
	v_mov_b32_e32 v53, v0
	v_mov_b32_e32 v54, v0
	v_mov_b32_e32 v55, v0
	v_mov_b32_e32 v56, v0
	v_mov_b32_e32 v57, v0
	v_mov_b32_e32 v58, v0
	v_mov_b32_e32 v59, v0
	v_mov_b32_e32 v60, v0
	v_mov_b32_e32 v61, v0
	v_mov_b32_e32 v62, v0
	v_mov_b32_e32 v63, v0
	v_readfirstlane_b32 s98, v84
	s_mov_b64 s[100:101], 0
	s_nop 3
	s_add_u32 s99, s98, 0x8000
	s_mov_b32 m0, s99
	v_lshl_add_u64 v[166:167], v[64:65], 0, s[100:101]
	global_load_lds_dwordx4 v[166:167], off
	s_add_u32 m0, s99, 0x4000
	v_lshl_add_u64 v[166:167], v[66:67], 0, s[100:101]
	global_load_lds_dwordx4 v[166:167], off
	s_add_u32 m0, s99, 0x1000
	v_lshl_add_u64 v[166:167], v[68:69], 0, s[100:101]
	global_load_lds_dwordx4 v[166:167], off
	s_add_u32 m0, s99, 0x5000
	v_lshl_add_u64 v[166:167], v[70:71], 0, s[100:101]
	global_load_lds_dwordx4 v[166:167], off
	s_add_u32 m0, s99, 0x2000
	v_lshl_add_u64 v[166:167], v[72:73], 0, s[100:101]
	global_load_lds_dwordx4 v[166:167], off
	s_add_u32 m0, s99, 0x6000
	v_lshl_add_u64 v[166:167], v[74:75], 0, s[100:101]
	global_load_lds_dwordx4 v[166:167], off
	s_add_u32 m0, s99, 0x3000
	v_lshl_add_u64 v[166:167], v[76:77], 0, s[100:101]
	global_load_lds_dwordx4 v[166:167], off
	s_add_u32 m0, s99, 0x7000
	v_lshl_add_u64 v[166:167], v[78:79], 0, s[100:101]
	global_load_lds_dwordx4 v[166:167], off
	s_waitcnt vmcnt(8) lgkmcnt(0)
	s_barrier
.LBB0_182:
	s_add_i32 s45, s43, 0xffff8000
	s_and_b32 s45, s45, 0x8000
	v_add_u32_e32 v89, s45, v88
	ds_read_b128 v[90:93], v89
	ds_read_b128 v[94:97], v89 offset:2048
	ds_read_b128 v[98:101], v89 offset:4096
	ds_read_b128 v[114:117], v89 offset:6144
	v_or_b32_e32 v89, s45, v87
	ds_read_b128 v[118:121], v89 offset:16384
	ds_read_b128 v[122:125], v89 offset:18432
	ds_read_b128 v[126:129], v89 offset:20480
	ds_read_b128 v[130:133], v89 offset:22528
	v_add_u32_e32 v89, s45, v86
	ds_read_b128 v[134:137], v89
	ds_read_b128 v[138:141], v89 offset:2048
	ds_read_b128 v[142:145], v89 offset:4096
	ds_read_b128 v[146:149], v89 offset:6144
	v_or_b32_e32 v89, s45, v85
	ds_read_b128 v[150:153], v89 offset:16384
	ds_read_b128 v[154:157], v89 offset:18432
	ds_read_b128 v[158:161], v89 offset:20480
	ds_read_b128 v[162:165], v89 offset:22528
	s_waitcnt lgkmcnt(0)
	s_barrier
	s_cmpk_eq_i32 s0, 0x700
	s_cbranch_scc1 .Lnodma_g182
	s_add_u32 s100, s0, 0x80
	s_addc_u32 s101, s1, 0
	s_add_u32 s99, s98, s45
	s_setprio 1
	v_mfma_f32_16x16x32_bf16 v[36:39], v[118:121], v[90:93], v[36:39]
	v_mfma_f32_16x16x32_bf16 v[24:27], v[122:125], v[90:93], v[24:27]
	v_mfma_f32_16x16x32_bf16 v[20:23], v[126:129], v[90:93], v[20:23]
	v_mfma_f32_16x16x32_bf16 v[16:19], v[130:133], v[90:93], v[16:19]
	s_mov_b32 m0, s99
	v_lshl_add_u64 v[166:167], v[64:65], 0, s[100:101]
	global_load_lds_dwordx4 v[166:167], off
	v_mfma_f32_16x16x32_bf16 v[12:15], v[118:121], v[94:97], v[12:15]
	v_mfma_f32_16x16x32_bf16 v[8:11], v[122:125], v[94:97], v[8:11]
	v_mfma_f32_16x16x32_bf16 v[4:7], v[126:129], v[94:97], v[4:7]
	v_mfma_f32_16x16x32_bf16 v[0:3], v[130:133], v[94:97], v[0:3]
	s_add_u32 m0, s99, 0x4000
	v_lshl_add_u64 v[166:167], v[66:67], 0, s[100:101]
	global_load_lds_dwordx4 v[166:167], off
	v_mfma_f32_16x16x32_bf16 v[28:31], v[118:121], v[98:101], v[28:31]
	v_mfma_f32_16x16x32_bf16 v[32:35], v[122:125], v[98:101], v[32:35]
	v_mfma_f32_16x16x32_bf16 v[40:43], v[126:129], v[98:101], v[40:43]
	v_mfma_f32_16x16x32_bf16 v[44:47], v[130:133], v[98:101], v[44:47]
	s_add_u32 m0, s99, 0x1000
	v_lshl_add_u64 v[166:167], v[68:69], 0, s[100:101]
	global_load_lds_dwordx4 v[166:167], off
	v_mfma_f32_16x16x32_bf16 v[48:51], v[118:121], v[114:117], v[48:51]
	v_mfma_f32_16x16x32_bf16 v[52:55], v[122:125], v[114:117], v[52:55]
	v_mfma_f32_16x16x32_bf16 v[56:59], v[126:129], v[114:117], v[56:59]
	v_mfma_f32_16x16x32_bf16 v[60:63], v[130:133], v[114:117], v[60:63]
	s_add_u32 m0, s99, 0x5000
	v_lshl_add_u64 v[166:167], v[70:71], 0, s[100:101]
	global_load_lds_dwordx4 v[166:167], off
	v_mfma_f32_16x16x32_bf16 v[36:39], v[150:153], v[134:137], v[36:39]
	v_mfma_f32_16x16x32_bf16 v[24:27], v[154:157], v[134:137], v[24:27]
	v_mfma_f32_16x16x32_bf16 v[20:23], v[158:161], v[134:137], v[20:23]
	v_mfma_f32_16x16x32_bf16 v[16:19], v[162:165], v[134:137], v[16:19]
	s_add_u32 m0, s99, 0x2000
	v_lshl_add_u64 v[166:167], v[72:73], 0, s[100:101]
	global_load_lds_dwordx4 v[166:167], off
	v_mfma_f32_16x16x32_bf16 v[12:15], v[150:153], v[138:141], v[12:15]
	v_mfma_f32_16x16x32_bf16 v[8:11], v[154:157], v[138:141], v[8:11]
	v_mfma_f32_16x16x32_bf16 v[4:7], v[158:161], v[138:141], v[4:7]
	v_mfma_f32_16x16x32_bf16 v[0:3], v[162:165], v[138:141], v[0:3]
	s_add_u32 m0, s99, 0x6000
	v_lshl_add_u64 v[166:167], v[74:75], 0, s[100:101]
	global_load_lds_dwordx4 v[166:167], off
	v_mfma_f32_16x16x32_bf16 v[28:31], v[150:153], v[142:145], v[28:31]
	v_mfma_f32_16x16x32_bf16 v[32:35], v[154:157], v[142:145], v[32:35]
	v_mfma_f32_16x16x32_bf16 v[40:43], v[158:161], v[142:145], v[40:43]
	v_mfma_f32_16x16x32_bf16 v[44:47], v[162:165], v[142:145], v[44:47]
	s_add_u32 m0, s99, 0x3000
	v_lshl_add_u64 v[166:167], v[76:77], 0, s[100:101]
	global_load_lds_dwordx4 v[166:167], off
	v_mfma_f32_16x16x32_bf16 v[48:51], v[150:153], v[146:149], v[48:51]
	v_mfma_f32_16x16x32_bf16 v[52:55], v[154:157], v[146:149], v[52:55]
	v_mfma_f32_16x16x32_bf16 v[56:59], v[158:161], v[146:149], v[56:59]
	v_mfma_f32_16x16x32_bf16 v[60:63], v[162:165], v[146:149], v[60:63]
	s_add_u32 m0, s99, 0x7000
	v_lshl_add_u64 v[166:167], v[78:79], 0, s[100:101]
	global_load_lds_dwordx4 v[166:167], off
	s_setprio 0
	s_branch .Ljoin_g182

; template <class Epi>
; __device__ __forceinline__ void gemm_tile(const bf16_t* A, int lda, const bf16_t* Bt, int ldb, int K, int m0, int n0, const Epi& epi, char* smem) {
;     ...
;             __builtin_amdgcn_sched_barrier(0);
;         }
;         asm volatile("s_waitcnt vmcnt(0)" ::: "memory");
;         __syncthreads();
;     }
;     __device__ __forceinline__ void operator()(const f32x4 (&acc)[4][4], int m0, int n0, int wr, int wc, int fr, int fq, char*) const {
; #pragma unroll
;         for (int m = 0; m < 4; ++m) {
;             const int row = m0 + wr * 64 + m * 16 + fr;
;             const float* xi = from_input ? xin_row(*p, row) : xcur_row(*p, row);
;             float* xo = shadow ? (float*)(p->ws + OFF_Q) + (size_t)row * 1024 : xcur_row(*p, row);
;             const float* gt = gate + (size_t)mod_index(row) * 6144;
.Ljoin_g182:
	s_add_u32 s0, s0, 0x80
	s_addc_u32 s1, s1, 0
	s_add_i32 s43, s43, 0x8000
	s_cmpk_eq_i32 s0, 0x780
	s_waitcnt vmcnt(8)
	s_barrier
	s_cbranch_scc0 .LBB0_182
	ds_read_b128 v[64:67], v88 offset:32768
	ds_read_b128 v[68:71], v88 offset:34816
	ds_read_b128 v[72:75], v88 offset:36864
	ds_read_b128 v[76:79], v88 offset:38912
	ds_read_b128 v[88:91], v87 offset:49152
	ds_read_b128 v[92:95], v87 offset:51200
	ds_read_b128 v[96:99], v87 offset:53248
	ds_read_b128 v[100:103], v87 offset:55296
	ds_read_b128 v[114:117], v86 offset:32768
	ds_read_b128 v[118:121], v86 offset:34816
	ds_read_b128 v[122:125], v86 offset:36864
	ds_read_b128 v[126:129], v86 offset:38912
	ds_read_b128 v[130:133], v85 offset:49152
	ds_read_b128 v[134:137], v85 offset:51200
	ds_read_b128 v[138:141], v85 offset:53248
	ds_read_b128 v[84:87], v85 offset:55296
	s_setprio 1
	s_waitcnt lgkmcnt(11)
	v_mfma_f32_16x16x32_bf16 v[36:39], v[88:91], v[64:67], v[36:39]
	s_waitcnt lgkmcnt(10)
	v_mfma_f32_16x16x32_bf16 v[24:27], v[92:95], v[64:67], v[24:27]
	s_waitcnt lgkmcnt(9)
	v_mfma_f32_16x16x32_bf16 v[20:23], v[96:99], v[64:67], v[20:23]
	s_waitcnt lgkmcnt(8)
	v_mfma_f32_16x16x32_bf16 v[16:19], v[100:103], v[64:67], v[16:19]
	v_mfma_f32_16x16x32_bf16 v[12:15], v[88:91], v[68:71], v[12:15]
	v_mfma_f32_16x16x32_bf16 v[8:11], v[92:95], v[68:71], v[8:11]
	v_mfma_f32_16x16x32_bf16 v[4:7], v[96:99], v[68:71], v[4:7]
	v_mfma_f32_16x16x32_bf16 v[0:3], v[100:103], v[68:71], v[0:3]
	v_mfma_f32_16x16x32_bf16 v[28:31], v[88:91], v[72:75], v[28:31]
	v_mfma_f32_16x16x32_bf16 v[64:67], v[92:95], v[72:75], v[32:35]
	v_mfma_f32_16x16x32_bf16 v[68:71], v[96:99], v[72:75], v[40:43]
	v_mfma_f32_16x16x32_bf16 v[88:91], v[88:91], v[76:79], v[48:51]
	v_mfma_f32_16x16x32_bf16 v[92:95], v[92:95], v[76:79], v[52:55]
	v_mfma_f32_16x16x32_bf16 v[96:99], v[96:99], v[76:79], v[56:59]
	v_mfma_f32_16x16x32_bf16 v[76:79], v[100:103], v[76:79], v[60:63]
	v_mfma_f32_16x16x32_bf16 v[72:75], v[100:103], v[72:75], v[44:47]
	s_waitcnt lgkmcnt(3)
	v_mfma_f32_16x16x32_bf16 v[60:63], v[130:133], v[114:117], v[36:39]
	s_waitcnt lgkmcnt(2)
	v_mfma_f32_16x16x32_bf16 v[56:59], v[134:137], v[114:117], v[24:27]
	s_waitcnt lgkmcnt(1)
	v_mfma_f32_16x16x32_bf16 v[52:55], v[138:141], v[114:117], v[20:23]
	s_waitcnt lgkmcnt(0)
	v_mfma_f32_16x16x32_bf16 v[48:51], v[84:87], v[114:117], v[16:19]
	v_mfma_f32_16x16x32_bf16 v[44:47], v[130:133], v[118:121], v[12:15]
	v_mfma_f32_16x16x32_bf16 v[40:43], v[134:137], v[118:121], v[8:11]
	v_mfma_f32_16x16x32_bf16 v[36:39], v[138:141], v[118:121], v[4:7]
	v_mfma_f32_16x16x32_bf16 v[32:35], v[84:87], v[118:121], v[0:3]
	v_mfma_f32_16x16x32_bf16 v[28:31], v[130:133], v[122:125], v[28:31]
	v_mfma_f32_16x16x32_bf16 v[24:27], v[134:137], v[122:125], v[64:67]
	v_mfma_f32_16x16x32_bf16 v[20:23], v[138:141], v[122:125], v[68:71]
	v_mfma_f32_16x16x32_bf16 v[16:19], v[84:87], v[122:125], v[72:75]
	v_mfma_f32_16x16x32_bf16 v[12:15], v[130:133], v[126:129], v[88:91]
	v_mfma_f32_16x16x32_bf16 v[8:11], v[134:137], v[126:129], v[92:95]
	v_mfma_f32_16x16x32_bf16 v[4:7], v[138:141], v[126:129], v[96:99]
	v_mfma_f32_16x16x32_bf16 v[0:3], v[84:87], v[126:129], v[76:79]
	s_setprio 0
	v_or_b32_e32 v64, s42, v83
	s_nop 0
	v_lshl_add_u32 v76, v82, 6, v64
	v_mul_hi_i32 v64, v76, s36
	v_lshrrev_b32_e32 v65, 31, v64
	v_ashrrev_i32_e32 v64, 11, v64
	s_waitcnt vmcnt(0)
	v_add_u32_e32 v64, v64, v65
	s_movk_i32 s0, 0xef00
	v_readlane_b32 s4, v254, 28
	v_mad_i32_i24 v77, v64, s0, v76
	v_readlane_b32 s5, v254, 29
	v_cmp_lt_i32_e64 s[42:43], s2, v77
	s_mov_b64 s[0:1], -1
	s_and_b64 vcc, exec, s[4:5]
	s_barrier
	s_cbranch_vccz .LBB0_191
	s_and_saveexec_b64 s[0:1], s[42:43]
	s_xor_b64 s[0:1], exec, s[0:1]
	v_ashrrev_i32_e32 v65, 31, v64
	v_add_u32_e32 v104, 0xffffff00, v77
	v_lshlrev_b64 v[66:67], 24, v[64:65]
	v_lshl_add_u64 v[66:67], s[24:25], 0, v[66:67]
	v_mov_b64_e32 v[68:69], v[104:105]
	s_andn2_saveexec_b64 s[0:1], s[0:1]
	s_cbranch_execz .LBB0_188
	v_readlane_b32 s4, v251, 30
	v_lshl_add_u32 v68, v64, 8, v77
	v_readlane_b32 s5, v251, 31
	v_ashrrev_i32_e32 v69, 31, v68
	s_nop 0
	v_mov_b64_e32 v[66:67], s[4:5]

; __device__ __forceinline__ unsigned pack2bf(float a, float b) { const f32x2 v = {a, b}; return __builtin_bit_cast(unsigned, __builtin_convertvector(v, bf2_t)); }
;     __device__ __forceinline__ void operator()(const f32x4 (&acc)[4][4], int m0, int n0, int wr, int wc, int fr, int fq, char* smem) const {
;     ...
;         for (int m = 0; m < 4; ++m) {
;             const int rl = wr * 64 + m * 16 + fr, row = m0 + rl;
;             const int b = row / TT, t = row - b * TT;
;             const float tot = red[rl] + red[128 + rl];
;             float sq = 0.f;
; #pragma unroll
;             for (int i = 0; i < 8; ++i) sq += stats[(size_t)row * 12 + i];
;             const float rstd = rsqrtf(sq * (1.f / 512.f) + 1e-6f);
;             const float scale = rstd * rsqrtf(rstd * rstd * tot * (1.f / 96.f) + 1e-6f) * SCL_Q;
;             bf16_t* qrow = Q + ((size_t)(b * 8 + h) * TT + t) * 96;
;             if (wc == 0) {
; #pragma unroll
;                 for (int n = 0; n < 4; ++n) {
;                     const int c = n * 16 + fq * 4;
;                     const f32x4 g = *(const f32x4*)(gq + c);
;                     const f32x4 v = acc[m][n];
;                     uint2 w; w.x = pack2bf(v[0] * scale * g[0], v[1] * scale * g[1]); w.y = pack2bf(v[2] * scale * g[2], v[3] * scale * g[3]);
;                     *(uint2*)(qrow + c) = w;
;                 }
;             } else {
;                 const int i0 = fq * 4;
;                 const f32x4 g1 = *(const f32x4*)(gq + 64 + i0), g2 = *(const f32x4*)(gq + 80 + i0);
;                 float x1[4], x2[4];
; #pragma unroll
;                 for (int j = 0; j < 4; ++j) { x1[j] = acc[m][0][j] * scale * g1[j]; x2[j] = acc[m][1][j] * scale * g2[j]; }
;                 if (t >= CTX) {
;                     const float* rp = rope + ((size_t)(t - CTX) * 16 + i0) * 2;
; #pragma unroll
;                     for (int j = 0; j < 4; ++j) { const float c = rp[2 * j], s = rp[2 * j + 1]; const float a = x1[j] * c - x2[j] * s, bb = x1[j] * s + x2[j] * c; x1[j] = a; x2[j] = bb; }
;                 }
;                 uint2 w; w.x = pack2bf(x1[0], x1[1]); w.y = pack2bf(x1[2], x1[3]); *(uint2*)(qrow + 64 + i0) = w;
.LBB0_546:
	s_or_b64 exec, exec, s[0:1]
	v_lshl_or_b32 v76, v64, 6, v65
	v_add_u32_e32 v74, s30, v76
	v_readlane_b32 s0, v252, 20
	v_mul_hi_i32 v64, v74, s36
	v_readlane_b32 s1, v252, 21
	v_lshrrev_b32_e32 v65, 31, v64
	v_ashrrev_i32_e32 v64, 11, v64
	v_lshlrev_b32_e32 v77, 2, v76
	s_waitcnt lgkmcnt(0)
	v_mad_i64_i32 v[68:69], s[0:1], v74, 48, s[0:1]
	s_barrier
	v_lshlrev_b32_e32 v78, 2, v66
	v_lshlrev_b32_e32 v104, 5, v66
	v_add_u32_e32 v75, v64, v65
	ds_read2st64_b32 v[72:73], v77 offset1:2
	global_load_dwordx4 v[64:67], v[68:69], off offset:16
	global_load_dwordx4 v[114:117], v[68:69], off offset:784
	global_load_dwordx4 v[118:121], v[68:69], off offset:768
	global_load_dwordx4 v[122:125], v[68:69], off offset:1552
	global_load_dwordx4 v[126:129], v[68:69], off offset:1536
	global_load_dwordx4 v[130:133], v[68:69], off offset:2320
	global_load_dwordx4 v[134:137], v[68:69], off offset:2304
	s_nop 0
	global_load_dwordx4 v[68:71], v[68:69], off
	s_movk_i32 s0, 0xef00
	s_mov_b32 s4, 0x800000
	s_waitcnt vmcnt(0)
	v_add_f32_e32 v68, 0, v68
	v_add_f32_e32 v68, v68, v69
	v_add_f32_e32 v68, v68, v70
	v_add_f32_e32 v68, v68, v71
	v_add_f32_e32 v64, v68, v64
	v_add_f32_e32 v64, v64, v65
	v_add_f32_e32 v64, v64, v66
	v_add_f32_e32 v65, v64, v67
	v_fmamk_f32 v65, v65, 0x3b000000, v108
	v_mad_i32_i24 v64, v75, s0, v74
	v_cmp_gt_f32_e64 s[0:1], s4, v65
	v_mul_f32_e32 v67, 0x4b800000, v65
	s_waitcnt lgkmcnt(0)
	v_add_f32_e32 v66, v72, v73
	v_cndmask_b32_e64 v65, v65, v67, s[0:1]
	v_rsq_f32_e32 v65, v65
	s_nop 0
	v_mul_f32_e32 v67, 0x45800000, v65
	v_cndmask_b32_e64 v65, v65, v67, s[0:1]
	v_mul_f32_e32 v67, v65, v65
	v_mul_f32_e32 v66, v66, v67
	v_fmamk_f32 v66, v66, 0x3c2aaaab, v108
	v_cmp_gt_f32_e64 s[0:1], s4, v66
	v_mul_f32_e32 v67, 0x4b800000, v66
	s_movk_i32 s4, 0xc0
	v_cndmask_b32_e64 v66, v66, v67, s[0:1]
	v_rsq_f32_e32 v66, v66
	s_nop 0
	v_mul_f32_e32 v67, 0x45800000, v66
	v_cndmask_b32_e64 v66, v66, v67, s[0:1]
	v_mul_f32_e32 v65, v65, v66
	v_mul_f32_e32 v66, 0x3e16c740, v65
	v_lshl_add_u32 v67, v75, 3, s47
	v_ashrrev_i32_e32 v65, 31, v64
	s_movk_i32 s0, 0x1100
	v_mad_i64_i32 v[70:71], s[0:1], v67, s0, v[64:65]
	v_readlane_b32 s0, v251, 56
	v_readlane_b32 s1, v251, 57
	v_lshlrev_b32_e32 v67, 2, v78
	global_load_dwordx4 v[224:227], v67, s[86:87]
	global_load_dwordx4 v[228:231], v67, s[86:87] offset:64
	global_load_dwordx4 v[232:235], v67, s[86:87] offset:128
	global_load_dwordx4 v[236:239], v67, s[86:87] offset:192
	global_load_dwordx4 v[240:243], v67, s[86:87] offset:256
	global_load_dwordx4 v[244:247], v67, s[86:87] offset:320
	s_waitcnt vmcnt(0)
	s_nop 0
	v_mov_b64_e32 v[68:69], s[0:1]
	v_mad_u64_u32 v[68:69], s[0:1], v70, s4, v[68:69]
	v_mad_i32_i24 v69, v71, s4, v69
	s_and_saveexec_b64 s[0:1], vcc
	s_xor_b64 s[34:35], exec, s[0:1]
	s_cbranch_execz .LBB0_550
	v_mov_b64_e32 v[52:53], v[240:241]
	v_mov_b64_e32 v[54:55], v[242:243]
	v_mov_b64_e32 v[48:49], v[244:245]
	v_mov_b64_e32 v[50:51], v[246:247]
	v_mov_b32_e32 v70, v60
	v_mov_b32_e32 v71, v57
	v_mov_b32_e32 v57, v61
	v_mul_f32_e32 v65, v62, v66
	v_mov_b32_e32 v62, v59
	v_mul_f32_e32 v72, v58, v66
	v_pk_mul_f32 v[58:59], v[70:71], v[66:67] op_sel_hi:[1,0]
	v_pk_mul_f32 v[56:57], v[56:57], v[66:67] op_sel_hi:[1,0]
	v_pk_mul_f32 v[60:61], v[62:63], v[66:67] op_sel_hi:[1,0]
	v_cmp_lt_i32_e64 s[0:1], s2, v64
	v_mov_b32_e32 v62, v52
	v_mov_b32_e32 v63, v49
	v_mov_b32_e32 v49, v53
	v_mul_f32_e32 v52, v65, v54
	v_mov_b32_e32 v54, v51
	v_mul_f32_e32 v70, v72, v50
	v_pk_mul_f32 v[50:51], v[58:59], v[62:63]
	v_pk_mul_f32 v[48:49], v[56:57], v[48:49]
	v_pk_mul_f32 v[72:73], v[60:61], v[54:55]
	s_and_saveexec_b64 s[42:43], s[0:1]
	s_cbranch_execz .LBB0_549
	v_add_u32_e32 v54, 0xffffff00, v64
	v_mov_b32_e32 v55, v105
	v_readlane_b32 s0, v252, 22
	v_lshlrev_b64 v[54:55], 7, v[54:55]
	v_readlane_b32 s1, v252, 23
	v_mov_b32_e32 v74, v48
	v_mov_b32_e32 v75, v51
	v_lshl_add_u64 v[54:55], s[0:1], 0, v[54:55]
	v_lshl_add_u64 v[58:59], v[54:55], 0, v[104:105]
	global_load_dwordx4 v[54:57], v[58:59], off offset:16
	s_mov_b64 s[100:101], 0x1000
	v_lshl_add_u64 v[162:163], v[58:59], 0, s[100:101]
	global_load_dwordx4 v[138:141], v[58:59], off offset:2064
	global_load_dwordx4 v[142:145], v[58:59], off offset:2048
	global_load_dwordx4 v[146:149], v[162:163], off offset:16
	global_load_dwordx4 v[150:153], v[162:163], off
	global_load_dwordx4 v[154:157], v[162:163], off offset:2064
	global_load_dwordx4 v[158:161], v[162:163], off offset:2048
	s_nop 0
	global_load_dwordx4 v[58:61], v[58:59], off
	s_waitcnt vmcnt(1)
	v_mul_f32_e32 v82, v52, v55
	s_waitcnt vmcnt(0)
	v_mov_b32_e32 v62, v59
	v_mov_b32_e32 v63, v60
	v_mov_b32_e32 v80, v59
	v_mov_b32_e32 v81, v61
	v_mov_b32_e32 v59, v60
	v_mul_f32_e32 v60, v52, v54
	v_pk_mul_f32 v[52:53], v[72:73], v[56:57] op_sel:[1,0] op_sel_hi:[0,1]
	v_mov_b32_e32 v64, v58
	v_mov_b32_e32 v65, v61
	v_pk_mul_f32 v[74:75], v[74:75], v[80:81]
	v_mov_b32_e32 v61, v52
	v_mov_b32_e32 v81, v53
	v_pk_mul_f32 v[52:53], v[72:73], v[56:57]
	v_pk_mul_f32 v[64:65], v[48:49], v[64:65]
	v_mov_b32_e32 v48, v50
	v_mul_f32_e32 v80, v70, v55
	v_mul_f32_e32 v54, v70, v54
	v_mov_b32_e32 v55, v52
	v_mov_b32_e32 v83, v53
	v_pk_fma_f32 v[56:57], v[48:49], v[58:59], v[74:75] neg_lo:[0,0,1] neg_hi:[0,0,1]
	v_pk_add_f32 v[52:53], v[60:61], v[80:81] neg_lo:[0,1] neg_hi:[0,1]
	v_pk_fma_f32 v[48:49], v[50:51], v[62:63], v[64:65]
	v_pk_add_f32 v[70:71], v[54:55], v[82:83]
	v_mov_b32_e32 v51, v49
	v_mov_b32_e32 v72, v71
	v_mov_b32_e32 v50, v56
	v_mov_b32_e32 v49, v57
	v_mov_b32_e32 v73, v53

; __device__ __forceinline__ unsigned pack2bf(float a, float b) { const f32x2 v = {a, b}; return __builtin_bit_cast(unsigned, __builtin_convertvector(v, bf2_t)); }
;     __device__ __forceinline__ void operator()(const f32x4 (&acc)[4][4], int m0, int n0, int wr, int wc, int fr, int fq, char* smem) const {
;     ...
;         for (int m = 0; m < 4; ++m) {
;             const int rl = wr * 64 + m * 16 + fr, row = m0 + rl;
;             const int b = row / TT, t = row - b * TT;
;             const float tot = red[rl] + red[128 + rl];
;             float sq = 0.f;
; #pragma unroll
;             for (int i = 0; i < 8; ++i) sq += stats[(size_t)row * 12 + i];
;             const float rstd = rsqrtf(sq * (1.f / 512.f) + 1e-6f);
;             const float scale = rstd * rsqrtf(rstd * rstd * tot * (1.f / 96.f) + 1e-6f) * SCL_Q;
;             bf16_t* qrow = Q + ((size_t)(b * 8 + h) * TT + t) * 96;
;             if (wc == 0) {
; #pragma unroll
;                 for (int n = 0; n < 4; ++n) {
;                     const int c = n * 16 + fq * 4;
;                     const f32x4 g = *(const f32x4*)(gq + c);
;                     const f32x4 v = acc[m][n];
;                     uint2 w; w.x = pack2bf(v[0] * scale * g[0], v[1] * scale * g[1]); w.y = pack2bf(v[2] * scale * g[2], v[3] * scale * g[3]);
;                     *(uint2*)(qrow + c) = w;
;                 }
;             } else {
;                 const int i0 = fq * 4;
;                 const f32x4 g1 = *(const f32x4*)(gq + 64 + i0), g2 = *(const f32x4*)(gq + 80 + i0);
;                 float x1[4], x2[4];
; #pragma unroll
;                 for (int j = 0; j < 4; ++j) { x1[j] = acc[m][0][j] * scale * g1[j]; x2[j] = acc[m][1][j] * scale * g2[j]; }
;                 if (t >= CTX) {
;                     const float* rp = rope + ((size_t)(t - CTX) * 16 + i0) * 2;
; #pragma unroll
;                     for (int j = 0; j < 4; ++j) { const float c = rp[2 * j], s = rp[2 * j + 1]; const float a = x1[j] * c - x2[j] * s, bb = x1[j] * s + x2[j] * c; x1[j] = a; x2[j] = bb; }
;                 }
;                 uint2 w; w.x = pack2bf(x1[0], x1[1]); w.y = pack2bf(x1[2], x1[3]); *(uint2*)(qrow + 64 + i0) = w;
.LBB0_550:
	s_or_saveexec_b64 s[0:1], s[34:35]
	v_lshlrev_b32_e32 v64, 1, v78
	s_xor_b64 exec, exec, s[0:1]
	s_cbranch_execz .LBB0_552
	v_mov_b64_e32 v[70:71], v[224:225]
	v_mov_b64_e32 v[72:73], v[226:227]
	v_pk_mul_f32 v[60:61], v[60:61], v[66:67] op_sel_hi:[1,0]
	v_pk_mul_f32 v[62:63], v[62:63], v[66:67] op_sel_hi:[1,0]
	v_mov_b32_e32 v65, v105
	v_lshl_add_u64 v[68:69], v[68:69], 0, v[64:65]
	v_pk_mul_f32 v[56:57], v[56:57], v[66:67] op_sel_hi:[1,0]
	v_pk_mul_f32 v[58:59], v[58:59], v[66:67] op_sel_hi:[1,0]
	v_pk_mul_f32 v[52:53], v[52:53], v[66:67] op_sel_hi:[1,0]
	v_pk_mul_f32 v[54:55], v[54:55], v[66:67] op_sel_hi:[1,0]
	v_pk_mul_f32 v[48:49], v[48:49], v[66:67] op_sel_hi:[1,0]
	s_mov_b64 s[4:5], 0x60
	v_lshl_add_u64 v[74:75], v[68:69], 0, s[4:5]
	v_pk_mul_f32 v[60:61], v[60:61], v[70:71]
	v_pk_mul_f32 v[62:63], v[62:63], v[72:73]
	v_cvt_pk_bf16_f32 v60, v60, v61
	v_cvt_pk_bf16_f32 v61, v62, v63
	global_store_dwordx2 v[68:69], v[60:61], off
	v_mov_b64_e32 v[60:61], v[228:229]
	v_mov_b64_e32 v[62:63], v[230:231]
	v_pk_mul_f32 v[56:57], v[56:57], v[60:61]
	v_pk_mul_f32 v[58:59], v[58:59], v[62:63]
	v_cvt_pk_bf16_f32 v56, v56, v57
	v_cvt_pk_bf16_f32 v57, v58, v59
	global_store_dwordx2 v[68:69], v[56:57], off offset:32
	v_mov_b64_e32 v[56:57], v[232:233]
	v_mov_b64_e32 v[58:59], v[234:235]
	v_pk_mul_f32 v[52:53], v[52:53], v[56:57]
	v_pk_mul_f32 v[54:55], v[54:55], v[58:59]
	v_cvt_pk_bf16_f32 v52, v52, v53
	v_cvt_pk_bf16_f32 v53, v54, v55
	global_store_dwordx2 v[68:69], v[52:53], off offset:64
	v_mov_b64_e32 v[52:53], v[236:237]
	v_mov_b64_e32 v[54:55], v[238:239]
	v_pk_mul_f32 v[48:49], v[48:49], v[52:53]
	s_nop 0
	v_cvt_pk_bf16_f32 v52, v48, v49
	v_pk_mul_f32 v[48:49], v[50:51], v[66:67] op_sel_hi:[1,0]
	global_store_dword v[68:69], v52, off offset:96
	v_pk_mul_f32 v[70:71], v[48:49], v[54:55]
	s_nop 0
	v_mov_b32_e32 v72, v71
.LBB0_552:
	s_or_b64 exec, exec, s[0:1]
	v_cvt_pk_bf16_f32 v48, v70, v72
	v_add3_u32 v58, s30, v76, 16
	v_readlane_b32 s0, v252, 20
	global_store_dword v[74:75], v48, off offset:4
	v_mul_hi_i32 v48, v58, s36
	v_readlane_b32 s1, v252, 21
	v_lshrrev_b32_e32 v49, 31, v48
	v_ashrrev_i32_e32 v48, 11, v48
	v_mad_i64_i32 v[52:53], s[0:1], v58, 48, s[0:1]
	v_add_u32_e32 v59, v48, v49
	ds_read2_b32 v[56:57], v77 offset0:16 offset1:144
	v_mov_b64_e32 v[48:49], v[114:115]
	v_mov_b64_e32 v[50:51], v[116:117]
	s_nop 0
	v_mov_b64_e32 v[52:53], v[118:119]
	v_mov_b64_e32 v[54:55], v[120:121]
	s_movk_i32 s0, 0xef00
	s_mov_b32 s4, 0x800000
	v_add_f32_e32 v52, 0, v52
	v_add_f32_e32 v52, v52, v53
	v_add_f32_e32 v52, v52, v54
	v_add_f32_e32 v52, v52, v55
	v_add_f32_e32 v48, v52, v48
	v_add_f32_e32 v48, v48, v49
	v_add_f32_e32 v48, v48, v50
	v_add_f32_e32 v48, v48, v51
	v_fmamk_f32 v48, v48, 0x3b000000, v108
	v_mad_i32_i24 v50, v59, s0, v58
	v_cmp_gt_f32_e64 s[0:1], s4, v48
	v_mul_f32_e32 v51, 0x4b800000, v48
	s_waitcnt lgkmcnt(0)
	v_add_f32_e32 v49, v56, v57
	v_cndmask_b32_e64 v48, v48, v51, s[0:1]
	v_rsq_f32_e32 v48, v48
	s_nop 0
	v_mul_f32_e32 v51, 0x45800000, v48
	v_cndmask_b32_e64 v48, v48, v51, s[0:1]
	v_mul_f32_e32 v51, v48, v48
	v_mul_f32_e32 v49, v49, v51
	v_fmamk_f32 v49, v49, 0x3c2aaaab, v108
	v_cmp_gt_f32_e64 s[0:1], s4, v49
	v_mul_f32_e32 v51, 0x4b800000, v49
	s_movk_i32 s4, 0xc0
	v_cndmask_b32_e64 v49, v49, v51, s[0:1]
	v_rsq_f32_e32 v49, v49
	s_nop 0
	v_mul_f32_e32 v51, 0x45800000, v49
	v_cndmask_b32_e64 v49, v49, v51, s[0:1]
	v_mul_f32_e32 v48, v48, v49
	v_lshl_add_u32 v49, v59, 3, s47
	v_ashrrev_i32_e32 v51, 31, v50
	s_movk_i32 s0, 0x1100
	v_mad_i64_i32 v[54:55], s[0:1], v49, s0, v[50:51]
	v_readlane_b32 s0, v251, 56
	v_readlane_b32 s1, v251, 57
	v_mul_f32_e32 v48, 0x3e16c740, v48
	s_nop 0
	v_mov_b64_e32 v[52:53], s[0:1]
	v_mad_u64_u32 v[52:53], s[0:1], v54, s4, v[52:53]
	v_mad_i32_i24 v53, v55, s4, v53
	s_and_saveexec_b64 s[0:1], vcc
	s_xor_b64 s[34:35], exec, s[0:1]
	s_cbranch_execz .LBB0_556
	v_mov_b64_e32 v[36:37], v[240:241]
	v_mov_b64_e32 v[38:39], v[242:243]
	v_mov_b64_e32 v[32:33], v[244:245]
	v_mov_b64_e32 v[34:35], v[246:247]
	v_mov_b32_e32 v54, v44
	v_mov_b32_e32 v55, v41
	v_mov_b32_e32 v41, v45
	v_mul_f32_e32 v49, v46, v48
	v_mov_b32_e32 v46, v43
	v_mul_f32_e32 v51, v42, v48
	v_pk_mul_f32 v[42:43], v[54:55], v[48:49] op_sel_hi:[1,0]
	v_pk_mul_f32 v[40:41], v[40:41], v[48:49] op_sel_hi:[1,0]
	v_pk_mul_f32 v[44:45], v[46:47], v[48:49] op_sel_hi:[1,0]
	v_cmp_lt_i32_e64 s[0:1], s2, v50
	v_mov_b32_e32 v46, v36
	v_mov_b32_e32 v47, v33
	v_mov_b32_e32 v33, v37
	v_mul_f32_e32 v36, v49, v38
	v_mov_b32_e32 v38, v35
	v_mul_f32_e32 v54, v51, v34
	v_pk_mul_f32 v[34:35], v[42:43], v[46:47]
	v_pk_mul_f32 v[32:33], v[40:41], v[32:33]
	v_pk_mul_f32 v[56:57], v[44:45], v[38:39]
	s_and_saveexec_b64 s[42:43], s[0:1]
	s_cbranch_execz .LBB0_555
	v_add_u32_e32 v38, 0xffffff00, v50
	v_mov_b32_e32 v39, v105
	v_readlane_b32 s0, v252, 22
	v_lshlrev_b64 v[38:39], 7, v[38:39]
	v_readlane_b32 s1, v252, 23
	v_mov_b32_e32 v50, v32
	v_mov_b32_e32 v51, v35
	v_lshl_add_u64 v[38:39], s[0:1], 0, v[38:39]
	v_lshl_add_u64 v[42:43], v[38:39], 0, v[104:105]
	v_mov_b64_e32 v[38:39], v[138:139]
	v_mov_b64_e32 v[40:41], v[140:141]
	s_nop 0
	v_mov_b64_e32 v[42:43], v[142:143]
	v_mov_b64_e32 v[44:45], v[144:145]
	v_mul_f32_e32 v60, v36, v39
	v_mov_b32_e32 v46, v43
	v_mov_b32_e32 v47, v44
	v_mov_b32_e32 v58, v43
	v_mov_b32_e32 v59, v45
	v_mov_b32_e32 v43, v44
	v_mul_f32_e32 v44, v36, v38
	v_pk_mul_f32 v[36:37], v[56:57], v[40:41] op_sel:[1,0] op_sel_hi:[0,1]
	v_mov_b32_e32 v48, v42
	v_mov_b32_e32 v49, v45
	v_pk_mul_f32 v[50:51], v[50:51], v[58:59]
	v_mov_b32_e32 v45, v36
	v_mov_b32_e32 v59, v37
	v_pk_mul_f32 v[36:37], v[56:57], v[40:41]
	v_pk_mul_f32 v[48:49], v[32:33], v[48:49]
	v_mov_b32_e32 v32, v34
	v_mul_f32_e32 v58, v54, v39
	v_mul_f32_e32 v38, v54, v38
	v_mov_b32_e32 v39, v36
	v_mov_b32_e32 v61, v37
	v_pk_fma_f32 v[40:41], v[32:33], v[42:43], v[50:51] neg_lo:[0,0,1] neg_hi:[0,0,1]
	v_pk_add_f32 v[36:37], v[44:45], v[58:59] neg_lo:[0,1] neg_hi:[0,1]
	v_pk_fma_f32 v[32:33], v[34:35], v[46:47], v[48:49]
	v_pk_add_f32 v[54:55], v[38:39], v[60:61]
	v_mov_b32_e32 v35, v33
	v_mov_b32_e32 v56, v55
	v_mov_b32_e32 v34, v40
	v_mov_b32_e32 v33, v41
	v_mov_b32_e32 v57, v37

; __device__ __forceinline__ unsigned pack2bf(float a, float b) { const f32x2 v = {a, b}; return __builtin_bit_cast(unsigned, __builtin_convertvector(v, bf2_t)); }
;     __device__ __forceinline__ void operator()(const f32x4 (&acc)[4][4], int m0, int n0, int wr, int wc, int fr, int fq, char* smem) const {
;     ...
;         for (int m = 0; m < 4; ++m) {
;             const int rl = wr * 64 + m * 16 + fr, row = m0 + rl;
;             const int b = row / TT, t = row - b * TT;
;             const float tot = red[rl] + red[128 + rl];
;             float sq = 0.f;
; #pragma unroll
;             for (int i = 0; i < 8; ++i) sq += stats[(size_t)row * 12 + i];
;             const float rstd = rsqrtf(sq * (1.f / 512.f) + 1e-6f);
;             const float scale = rstd * rsqrtf(rstd * rstd * tot * (1.f / 96.f) + 1e-6f) * SCL_Q;
;             bf16_t* qrow = Q + ((size_t)(b * 8 + h) * TT + t) * 96;
;             if (wc == 0) {
; #pragma unroll
;                 for (int n = 0; n < 4; ++n) {
;                     const int c = n * 16 + fq * 4;
;                     const f32x4 g = *(const f32x4*)(gq + c);
;                     const f32x4 v = acc[m][n];
;                     uint2 w; w.x = pack2bf(v[0] * scale * g[0], v[1] * scale * g[1]); w.y = pack2bf(v[2] * scale * g[2], v[3] * scale * g[3]);
;                     *(uint2*)(qrow + c) = w;
;                 }
;             } else {
;                 const int i0 = fq * 4;
;                 const f32x4 g1 = *(const f32x4*)(gq + 64 + i0), g2 = *(const f32x4*)(gq + 80 + i0);
;                 float x1[4], x2[4];
; #pragma unroll
;                 for (int j = 0; j < 4; ++j) { x1[j] = acc[m][0][j] * scale * g1[j]; x2[j] = acc[m][1][j] * scale * g2[j]; }
;                 if (t >= CTX) {
;                     const float* rp = rope + ((size_t)(t - CTX) * 16 + i0) * 2;
; #pragma unroll
;                     for (int j = 0; j < 4; ++j) { const float c = rp[2 * j], s = rp[2 * j + 1]; const float a = x1[j] * c - x2[j] * s, bb = x1[j] * s + x2[j] * c; x1[j] = a; x2[j] = bb; }
;                 }
;                 uint2 w; w.x = pack2bf(x1[0], x1[1]); w.y = pack2bf(x1[2], x1[3]); *(uint2*)(qrow + 64 + i0) = w;
.LBB0_556:
	s_andn2_saveexec_b64 s[0:1], s[34:35]
	s_cbranch_execz .LBB0_558
	v_mov_b64_e32 v[54:55], v[224:225]
	v_mov_b64_e32 v[56:57], v[226:227]
	v_pk_mul_f32 v[44:45], v[44:45], v[48:49] op_sel_hi:[1,0]
	v_pk_mul_f32 v[46:47], v[46:47], v[48:49] op_sel_hi:[1,0]
	v_mov_b32_e32 v65, v105
	v_lshl_add_u64 v[50:51], v[52:53], 0, v[64:65]
	v_pk_mul_f32 v[40:41], v[40:41], v[48:49] op_sel_hi:[1,0]
	v_pk_mul_f32 v[42:43], v[42:43], v[48:49] op_sel_hi:[1,0]
	v_pk_mul_f32 v[36:37], v[36:37], v[48:49] op_sel_hi:[1,0]
	v_pk_mul_f32 v[38:39], v[38:39], v[48:49] op_sel_hi:[1,0]
	v_pk_mul_f32 v[32:33], v[32:33], v[48:49] op_sel_hi:[1,0]
	s_mov_b64 s[4:5], 0x60
	v_lshl_add_u64 v[58:59], v[50:51], 0, s[4:5]
	v_pk_mul_f32 v[44:45], v[44:45], v[54:55]
	v_pk_mul_f32 v[46:47], v[46:47], v[56:57]
	v_cvt_pk_bf16_f32 v44, v44, v45
	v_cvt_pk_bf16_f32 v45, v46, v47
	global_store_dwordx2 v[50:51], v[44:45], off
	v_mov_b64_e32 v[44:45], v[228:229]
	v_mov_b64_e32 v[46:47], v[230:231]
	v_pk_mul_f32 v[40:41], v[40:41], v[44:45]
	v_pk_mul_f32 v[42:43], v[42:43], v[46:47]
	v_cvt_pk_bf16_f32 v40, v40, v41
	v_cvt_pk_bf16_f32 v41, v42, v43
	global_store_dwordx2 v[50:51], v[40:41], off offset:32
	v_mov_b64_e32 v[40:41], v[232:233]
	v_mov_b64_e32 v[42:43], v[234:235]
	v_pk_mul_f32 v[36:37], v[36:37], v[40:41]
	v_pk_mul_f32 v[38:39], v[38:39], v[42:43]
	v_cvt_pk_bf16_f32 v36, v36, v37
	v_cvt_pk_bf16_f32 v37, v38, v39
	global_store_dwordx2 v[50:51], v[36:37], off offset:64
	v_mov_b64_e32 v[36:37], v[236:237]
	v_mov_b64_e32 v[38:39], v[238:239]
	v_pk_mul_f32 v[32:33], v[32:33], v[36:37]
	s_nop 0
	v_cvt_pk_bf16_f32 v36, v32, v33
	v_pk_mul_f32 v[32:33], v[34:35], v[48:49] op_sel_hi:[1,0]
	global_store_dword v[50:51], v36, off offset:96
	v_pk_mul_f32 v[54:55], v[32:33], v[38:39]
	s_nop 0
	v_mov_b32_e32 v56, v55
.LBB0_558:
	s_or_b64 exec, exec, s[0:1]
	v_cvt_pk_bf16_f32 v32, v54, v56
	v_add3_u32 v42, s30, v76, 32
	v_readlane_b32 s0, v252, 20
	global_store_dword v[58:59], v32, off offset:4
	v_mul_hi_i32 v32, v42, s36
	v_readlane_b32 s1, v252, 21
	v_lshrrev_b32_e32 v33, 31, v32
	v_ashrrev_i32_e32 v32, 11, v32
	v_mad_i64_i32 v[36:37], s[0:1], v42, 48, s[0:1]
	v_add_u32_e32 v43, v32, v33
	ds_read2_b32 v[40:41], v77 offset0:32 offset1:160
	v_mov_b64_e32 v[32:33], v[122:123]
	v_mov_b64_e32 v[34:35], v[124:125]
	s_nop 0
	v_mov_b64_e32 v[36:37], v[126:127]
	v_mov_b64_e32 v[38:39], v[128:129]
	s_movk_i32 s0, 0xef00
	s_mov_b32 s4, 0x800000
	v_add_f32_e32 v36, 0, v36
	v_add_f32_e32 v36, v36, v37
	v_add_f32_e32 v36, v36, v38
	v_add_f32_e32 v36, v36, v39
	v_add_f32_e32 v32, v36, v32
	v_add_f32_e32 v32, v32, v33
	v_add_f32_e32 v32, v32, v34
	v_add_f32_e32 v32, v32, v35
	v_fmamk_f32 v32, v32, 0x3b000000, v108
	v_mad_i32_i24 v34, v43, s0, v42
	v_cmp_gt_f32_e64 s[0:1], s4, v32
	v_mul_f32_e32 v35, 0x4b800000, v32
	s_waitcnt lgkmcnt(0)
	v_add_f32_e32 v33, v40, v41
	v_cndmask_b32_e64 v32, v32, v35, s[0:1]
	v_rsq_f32_e32 v32, v32
	s_nop 0
	v_mul_f32_e32 v35, 0x45800000, v32
	v_cndmask_b32_e64 v32, v32, v35, s[0:1]
	v_mul_f32_e32 v35, v32, v32
	v_mul_f32_e32 v33, v33, v35
	v_fmamk_f32 v33, v33, 0x3c2aaaab, v108
	v_cmp_gt_f32_e64 s[0:1], s4, v33
	v_mul_f32_e32 v35, 0x4b800000, v33
	s_movk_i32 s4, 0xc0
	v_cndmask_b32_e64 v33, v33, v35, s[0:1]
	v_rsq_f32_e32 v33, v33
	s_nop 0
	v_mul_f32_e32 v35, 0x45800000, v33
	v_cndmask_b32_e64 v33, v33, v35, s[0:1]
	v_mul_f32_e32 v32, v32, v33
	v_lshl_add_u32 v33, v43, 3, s47
	v_ashrrev_i32_e32 v35, 31, v34
	s_movk_i32 s0, 0x1100
	v_mad_i64_i32 v[38:39], s[0:1], v33, s0, v[34:35]
	v_readlane_b32 s0, v251, 56
	v_readlane_b32 s1, v251, 57
	v_mul_f32_e32 v32, 0x3e16c740, v32
	s_nop 0
	v_mov_b64_e32 v[36:37], s[0:1]
	v_mad_u64_u32 v[36:37], s[0:1], v38, s4, v[36:37]
	v_mad_i32_i24 v37, v39, s4, v37
	s_and_saveexec_b64 s[0:1], vcc
	s_xor_b64 s[34:35], exec, s[0:1]
	s_cbranch_execz .LBB0_562
	v_mov_b64_e32 v[20:21], v[240:241]
	v_mov_b64_e32 v[22:23], v[242:243]
	v_mov_b64_e32 v[16:17], v[244:245]
	v_mov_b64_e32 v[18:19], v[246:247]
	v_mov_b32_e32 v38, v28
	v_mov_b32_e32 v39, v25
	v_mov_b32_e32 v25, v29
	v_mul_f32_e32 v33, v30, v32
	v_mov_b32_e32 v30, v27
	v_mul_f32_e32 v35, v26, v32
	v_pk_mul_f32 v[26:27], v[38:39], v[32:33] op_sel_hi:[1,0]
	v_pk_mul_f32 v[24:25], v[24:25], v[32:33] op_sel_hi:[1,0]
	v_pk_mul_f32 v[28:29], v[30:31], v[32:33] op_sel_hi:[1,0]
	v_cmp_lt_i32_e64 s[0:1], s2, v34
	v_mov_b32_e32 v30, v20
	v_mov_b32_e32 v31, v17
	v_mov_b32_e32 v17, v21
	v_mul_f32_e32 v20, v33, v22
	v_mov_b32_e32 v22, v19
	v_mul_f32_e32 v38, v35, v18
	v_pk_mul_f32 v[18:19], v[26:27], v[30:31]
	v_pk_mul_f32 v[16:17], v[24:25], v[16:17]
	v_pk_mul_f32 v[40:41], v[28:29], v[22:23]
	s_and_saveexec_b64 s[42:43], s[0:1]
	s_cbranch_execz .LBB0_561
	v_add_u32_e32 v22, 0xffffff00, v34
	v_mov_b32_e32 v23, v105
	v_readlane_b32 s0, v252, 22
	v_lshlrev_b64 v[22:23], 7, v[22:23]
	v_readlane_b32 s1, v252, 23
	v_mov_b32_e32 v34, v16
	v_mov_b32_e32 v35, v19
	v_lshl_add_u64 v[22:23], s[0:1], 0, v[22:23]
	v_lshl_add_u64 v[26:27], v[22:23], 0, v[104:105]
	v_mov_b64_e32 v[22:23], v[146:147]
	v_mov_b64_e32 v[24:25], v[148:149]
	s_nop 0
	v_mov_b64_e32 v[26:27], v[150:151]
	v_mov_b64_e32 v[28:29], v[152:153]
	v_mul_f32_e32 v44, v20, v23
	v_mov_b32_e32 v30, v27
	v_mov_b32_e32 v31, v28
	v_mov_b32_e32 v42, v27
	v_mov_b32_e32 v43, v29
	v_mov_b32_e32 v27, v28
	v_mul_f32_e32 v28, v20, v22
	v_pk_mul_f32 v[20:21], v[40:41], v[24:25] op_sel:[1,0] op_sel_hi:[0,1]
	v_mov_b32_e32 v32, v26
	v_mov_b32_e32 v33, v29
	v_pk_mul_f32 v[34:35], v[34:35], v[42:43]
	v_mov_b32_e32 v29, v20
	v_mov_b32_e32 v43, v21
	v_pk_mul_f32 v[20:21], v[40:41], v[24:25]
	v_pk_mul_f32 v[32:33], v[16:17], v[32:33]
	v_mov_b32_e32 v16, v18
	v_mul_f32_e32 v42, v38, v23
	v_mul_f32_e32 v22, v38, v22
	v_mov_b32_e32 v23, v20
	v_mov_b32_e32 v45, v21
	v_pk_fma_f32 v[24:25], v[16:17], v[26:27], v[34:35] neg_lo:[0,0,1] neg_hi:[0,0,1]
	v_pk_add_f32 v[20:21], v[28:29], v[42:43] neg_lo:[0,1] neg_hi:[0,1]
	v_pk_fma_f32 v[16:17], v[18:19], v[30:31], v[32:33]
	v_pk_add_f32 v[38:39], v[22:23], v[44:45]
	v_mov_b32_e32 v19, v17
	v_mov_b32_e32 v40, v39
	v_mov_b32_e32 v18, v24
	v_mov_b32_e32 v17, v25
	v_mov_b32_e32 v41, v21

; __device__ __forceinline__ unsigned pack2bf(float a, float b) { const f32x2 v = {a, b}; return __builtin_bit_cast(unsigned, __builtin_convertvector(v, bf2_t)); }
;     __device__ __forceinline__ void operator()(const f32x4 (&acc)[4][4], int m0, int n0, int wr, int wc, int fr, int fq, char* smem) const {
;     ...
;         for (int m = 0; m < 4; ++m) {
;             const int rl = wr * 64 + m * 16 + fr, row = m0 + rl;
;             const int b = row / TT, t = row - b * TT;
;             const float tot = red[rl] + red[128 + rl];
;             float sq = 0.f;
; #pragma unroll
;             for (int i = 0; i < 8; ++i) sq += stats[(size_t)row * 12 + i];
;             const float rstd = rsqrtf(sq * (1.f / 512.f) + 1e-6f);
;             const float scale = rstd * rsqrtf(rstd * rstd * tot * (1.f / 96.f) + 1e-6f) * SCL_Q;
;             bf16_t* qrow = Q + ((size_t)(b * 8 + h) * TT + t) * 96;
;             if (wc == 0) {
; #pragma unroll
;                 for (int n = 0; n < 4; ++n) {
;                     const int c = n * 16 + fq * 4;
;                     const f32x4 g = *(const f32x4*)(gq + c);
;                     const f32x4 v = acc[m][n];
;                     uint2 w; w.x = pack2bf(v[0] * scale * g[0], v[1] * scale * g[1]); w.y = pack2bf(v[2] * scale * g[2], v[3] * scale * g[3]);
;                     *(uint2*)(qrow + c) = w;
;                 }
;             } else {
;                 const int i0 = fq * 4;
;                 const f32x4 g1 = *(const f32x4*)(gq + 64 + i0), g2 = *(const f32x4*)(gq + 80 + i0);
;                 float x1[4], x2[4];
; #pragma unroll
;                 for (int j = 0; j < 4; ++j) { x1[j] = acc[m][0][j] * scale * g1[j]; x2[j] = acc[m][1][j] * scale * g2[j]; }
;                 if (t >= CTX) {
;                     const float* rp = rope + ((size_t)(t - CTX) * 16 + i0) * 2;
; #pragma unroll
;                     for (int j = 0; j < 4; ++j) { const float c = rp[2 * j], s = rp[2 * j + 1]; const float a = x1[j] * c - x2[j] * s, bb = x1[j] * s + x2[j] * c; x1[j] = a; x2[j] = bb; }
;                 }
;                 uint2 w; w.x = pack2bf(x1[0], x1[1]); w.y = pack2bf(x1[2], x1[3]); *(uint2*)(qrow + 64 + i0) = w;
.LBB0_562:
	s_andn2_saveexec_b64 s[0:1], s[34:35]
	s_cbranch_execz .LBB0_564
	v_mov_b64_e32 v[38:39], v[224:225]
	v_mov_b64_e32 v[40:41], v[226:227]
	v_pk_mul_f32 v[28:29], v[28:29], v[32:33] op_sel_hi:[1,0]
	v_pk_mul_f32 v[30:31], v[30:31], v[32:33] op_sel_hi:[1,0]
	v_mov_b32_e32 v65, v105
	v_lshl_add_u64 v[34:35], v[36:37], 0, v[64:65]
	v_pk_mul_f32 v[24:25], v[24:25], v[32:33] op_sel_hi:[1,0]
	v_pk_mul_f32 v[26:27], v[26:27], v[32:33] op_sel_hi:[1,0]
	v_pk_mul_f32 v[20:21], v[20:21], v[32:33] op_sel_hi:[1,0]
	v_pk_mul_f32 v[22:23], v[22:23], v[32:33] op_sel_hi:[1,0]
	v_pk_mul_f32 v[16:17], v[16:17], v[32:33] op_sel_hi:[1,0]
	s_mov_b64 s[4:5], 0x60
	v_lshl_add_u64 v[42:43], v[34:35], 0, s[4:5]
	v_pk_mul_f32 v[28:29], v[28:29], v[38:39]
	v_pk_mul_f32 v[30:31], v[30:31], v[40:41]
	v_cvt_pk_bf16_f32 v28, v28, v29
	v_cvt_pk_bf16_f32 v29, v30, v31
	global_store_dwordx2 v[34:35], v[28:29], off
	v_mov_b64_e32 v[28:29], v[228:229]
	v_mov_b64_e32 v[30:31], v[230:231]
	v_pk_mul_f32 v[24:25], v[24:25], v[28:29]
	v_pk_mul_f32 v[26:27], v[26:27], v[30:31]
	v_cvt_pk_bf16_f32 v24, v24, v25
	v_cvt_pk_bf16_f32 v25, v26, v27
	global_store_dwordx2 v[34:35], v[24:25], off offset:32
	v_mov_b64_e32 v[24:25], v[232:233]
	v_mov_b64_e32 v[26:27], v[234:235]
	v_pk_mul_f32 v[20:21], v[20:21], v[24:25]
	v_pk_mul_f32 v[22:23], v[22:23], v[26:27]
	v_cvt_pk_bf16_f32 v20, v20, v21
	v_cvt_pk_bf16_f32 v21, v22, v23
	global_store_dwordx2 v[34:35], v[20:21], off offset:64
	v_mov_b64_e32 v[20:21], v[236:237]
	v_mov_b64_e32 v[22:23], v[238:239]
	v_pk_mul_f32 v[16:17], v[16:17], v[20:21]
	s_nop 0
	v_cvt_pk_bf16_f32 v20, v16, v17
	v_pk_mul_f32 v[16:17], v[18:19], v[32:33] op_sel_hi:[1,0]
	global_store_dword v[34:35], v20, off offset:96
	v_pk_mul_f32 v[38:39], v[16:17], v[22:23]
	s_nop 0
	v_mov_b32_e32 v40, v39
.LBB0_564:
	s_or_b64 exec, exec, s[0:1]
	v_cvt_pk_bf16_f32 v16, v38, v40
	v_add3_u32 v26, s30, v76, 48
	v_readlane_b32 s0, v252, 20
	global_store_dword v[42:43], v16, off offset:4
	v_mul_hi_i32 v16, v26, s36
	v_readlane_b32 s1, v252, 21
	v_lshrrev_b32_e32 v17, 31, v16
	v_ashrrev_i32_e32 v16, 11, v16
	v_mad_i64_i32 v[20:21], s[0:1], v26, 48, s[0:1]
	v_add_u32_e32 v27, v16, v17
	ds_read2_b32 v[24:25], v77 offset0:48 offset1:176
	v_mov_b64_e32 v[16:17], v[130:131]
	v_mov_b64_e32 v[18:19], v[132:133]
	s_nop 0
	v_mov_b64_e32 v[20:21], v[134:135]
	v_mov_b64_e32 v[22:23], v[136:137]
	s_movk_i32 s0, 0xef00
	s_mov_b32 s4, 0x800000
	v_add_f32_e32 v20, 0, v20
	v_add_f32_e32 v20, v20, v21
	v_add_f32_e32 v20, v20, v22
	v_add_f32_e32 v20, v20, v23
	v_add_f32_e32 v16, v20, v16
	v_add_f32_e32 v16, v16, v17
	v_add_f32_e32 v16, v16, v18
	v_add_f32_e32 v16, v16, v19
	v_fmamk_f32 v16, v16, 0x3b000000, v108
	v_mad_i32_i24 v18, v27, s0, v26
	v_cmp_gt_f32_e64 s[0:1], s4, v16
	v_mul_f32_e32 v19, 0x4b800000, v16
	s_waitcnt lgkmcnt(0)
	v_add_f32_e32 v17, v24, v25
	v_cndmask_b32_e64 v16, v16, v19, s[0:1]
	v_rsq_f32_e32 v16, v16
	s_nop 0
	v_mul_f32_e32 v19, 0x45800000, v16
	v_cndmask_b32_e64 v16, v16, v19, s[0:1]
	v_mul_f32_e32 v19, v16, v16
	v_mul_f32_e32 v17, v17, v19
	v_fmamk_f32 v17, v17, 0x3c2aaaab, v108
	v_cmp_gt_f32_e64 s[0:1], s4, v17
	v_mul_f32_e32 v19, 0x4b800000, v17
	s_movk_i32 s4, 0xc0
	v_cndmask_b32_e64 v17, v17, v19, s[0:1]
	v_rsq_f32_e32 v17, v17
	s_nop 0
	v_mul_f32_e32 v19, 0x45800000, v17
	v_cndmask_b32_e64 v17, v17, v19, s[0:1]
	v_mul_f32_e32 v16, v16, v17
	v_lshl_add_u32 v17, v27, 3, s47
	v_ashrrev_i32_e32 v19, 31, v18
	s_movk_i32 s0, 0x1100
	v_mad_i64_i32 v[22:23], s[0:1], v17, s0, v[18:19]
	v_readlane_b32 s0, v251, 56
	v_readlane_b32 s1, v251, 57
	v_mul_f32_e32 v16, 0x3e16c740, v16
	s_nop 0
	v_mov_b64_e32 v[20:21], s[0:1]
	v_mad_u64_u32 v[20:21], s[0:1], v22, s4, v[20:21]
	v_mad_i32_i24 v21, v23, s4, v21
	s_and_saveexec_b64 s[0:1], vcc
	s_xor_b64 s[0:1], exec, s[0:1]
	s_cbranch_execz .LBB0_568
	v_mov_b64_e32 v[4:5], v[240:241]
	v_mov_b64_e32 v[6:7], v[242:243]
	v_mov_b64_e32 v[0:1], v[244:245]
	v_mov_b64_e32 v[2:3], v[246:247]
	v_mov_b32_e32 v22, v12
	v_mov_b32_e32 v23, v9
	v_mov_b32_e32 v9, v13
	v_mul_f32_e32 v17, v14, v16
	v_mov_b32_e32 v14, v11
	v_mul_f32_e32 v19, v10, v16
	v_pk_mul_f32 v[10:11], v[22:23], v[16:17] op_sel_hi:[1,0]
	v_pk_mul_f32 v[8:9], v[8:9], v[16:17] op_sel_hi:[1,0]
	v_pk_mul_f32 v[12:13], v[14:15], v[16:17] op_sel_hi:[1,0]
	v_cmp_lt_i32_e32 vcc, s2, v18
	v_mov_b32_e32 v14, v4
	v_mov_b32_e32 v15, v1
	v_mov_b32_e32 v1, v5
	v_mul_f32_e32 v4, v17, v6
	v_mov_b32_e32 v6, v3
	v_mul_f32_e32 v22, v19, v2
	v_pk_mul_f32 v[2:3], v[10:11], v[14:15]
	v_pk_mul_f32 v[0:1], v[8:9], v[0:1]
	v_pk_mul_f32 v[24:25], v[12:13], v[6:7]
	s_and_saveexec_b64 s[34:35], vcc
	s_cbranch_execz .LBB0_567
	v_add_u32_e32 v6, 0xffffff00, v18
	v_mov_b32_e32 v7, v105
	v_readlane_b32 s4, v252, 22
	v_lshlrev_b64 v[6:7], 7, v[6:7]
	v_readlane_b32 s5, v252, 23
	v_mov_b32_e32 v18, v0
	v_mov_b32_e32 v19, v3
	v_lshl_add_u64 v[6:7], s[4:5], 0, v[6:7]
	v_lshl_add_u64 v[10:11], v[6:7], 0, v[104:105]
	v_mov_b64_e32 v[6:7], v[154:155]
	v_mov_b64_e32 v[8:9], v[156:157]
	s_nop 0
	v_mov_b64_e32 v[10:11], v[158:159]
	v_mov_b64_e32 v[12:13], v[160:161]
	v_mul_f32_e32 v28, v4, v7
	v_mov_b32_e32 v14, v11
	v_mov_b32_e32 v15, v12
	v_mov_b32_e32 v26, v11
	v_mov_b32_e32 v27, v13
	v_mov_b32_e32 v11, v12
	v_mul_f32_e32 v12, v4, v6
	v_pk_mul_f32 v[4:5], v[24:25], v[8:9] op_sel:[1,0] op_sel_hi:[0,1]
	v_mov_b32_e32 v16, v10
	v_mov_b32_e32 v17, v13
	v_pk_mul_f32 v[18:19], v[18:19], v[26:27]
	v_mov_b32_e32 v13, v4
	v_mov_b32_e32 v27, v5
	v_pk_mul_f32 v[4:5], v[24:25], v[8:9]
	v_pk_mul_f32 v[16:17], v[0:1], v[16:17]
	v_mov_b32_e32 v0, v2
	v_mul_f32_e32 v26, v22, v7
	v_mul_f32_e32 v6, v22, v6
	v_mov_b32_e32 v7, v4
	v_mov_b32_e32 v29, v5
	v_pk_fma_f32 v[8:9], v[0:1], v[10:11], v[18:19] neg_lo:[0,0,1] neg_hi:[0,0,1]
	v_pk_add_f32 v[4:5], v[12:13], v[26:27] neg_lo:[0,1] neg_hi:[0,1]
	v_pk_fma_f32 v[0:1], v[2:3], v[14:15], v[16:17]
	v_pk_add_f32 v[22:23], v[6:7], v[28:29]
	v_mov_b32_e32 v3, v1
	v_mov_b32_e32 v24, v23
	v_mov_b32_e32 v2, v8
	v_mov_b32_e32 v1, v9
	v_mov_b32_e32 v25, v5

; __device__ __forceinline__ unsigned pack2bf(float a, float b) { const f32x2 v = {a, b}; return __builtin_bit_cast(unsigned, __builtin_convertvector(v, bf2_t)); }
;     __device__ __forceinline__ void operator()(const f32x4 (&acc)[4][4], int m0, int n0, int wr, int wc, int fr, int fq, char* smem) const {
;     ...
;             if (wc == 0) {
; #pragma unroll
;                 for (int n = 0; n < 4; ++n) {
;                     const int c = n * 16 + fq * 4;
;                     const f32x4 g = *(const f32x4*)(gq + c);
;                     const f32x4 v = acc[m][n];
;                     uint2 w; w.x = pack2bf(v[0] * scale * g[0], v[1] * scale * g[1]); w.y = pack2bf(v[2] * scale * g[2], v[3] * scale * g[3]);
;                     *(uint2*)(qrow + c) = w;
;                 }
.LBB0_568:
	s_andn2_saveexec_b64 s[0:1], s[0:1]
	s_cbranch_execz .LBB0_533
	v_mov_b64_e32 v[22:23], v[224:225]
	v_mov_b64_e32 v[24:25], v[226:227]
	v_pk_mul_f32 v[12:13], v[12:13], v[16:17] op_sel_hi:[1,0]
	v_pk_mul_f32 v[14:15], v[14:15], v[16:17] op_sel_hi:[1,0]
	v_mov_b32_e32 v65, v105
	v_lshl_add_u64 v[18:19], v[20:21], 0, v[64:65]
	v_pk_mul_f32 v[8:9], v[8:9], v[16:17] op_sel_hi:[1,0]
	v_pk_mul_f32 v[10:11], v[10:11], v[16:17] op_sel_hi:[1,0]
	v_pk_mul_f32 v[4:5], v[4:5], v[16:17] op_sel_hi:[1,0]
	v_pk_mul_f32 v[6:7], v[6:7], v[16:17] op_sel_hi:[1,0]
	v_pk_mul_f32 v[0:1], v[0:1], v[16:17] op_sel_hi:[1,0]
	s_mov_b64 s[4:5], 0x60
	v_lshl_add_u64 v[26:27], v[18:19], 0, s[4:5]
	v_pk_mul_f32 v[12:13], v[12:13], v[22:23]
	v_pk_mul_f32 v[14:15], v[14:15], v[24:25]
	v_cvt_pk_bf16_f32 v12, v12, v13
	v_cvt_pk_bf16_f32 v13, v14, v15
	global_store_dwordx2 v[18:19], v[12:13], off
	v_mov_b64_e32 v[12:13], v[228:229]
	v_mov_b64_e32 v[14:15], v[230:231]
	v_pk_mul_f32 v[8:9], v[8:9], v[12:13]
	v_pk_mul_f32 v[10:11], v[10:11], v[14:15]
	v_cvt_pk_bf16_f32 v8, v8, v9
	v_cvt_pk_bf16_f32 v9, v10, v11
	global_store_dwordx2 v[18:19], v[8:9], off offset:32
	v_mov_b64_e32 v[8:9], v[232:233]
	v_mov_b64_e32 v[10:11], v[234:235]
	v_pk_mul_f32 v[4:5], v[4:5], v[8:9]
	v_pk_mul_f32 v[6:7], v[6:7], v[10:11]
	v_cvt_pk_bf16_f32 v4, v4, v5
	v_cvt_pk_bf16_f32 v5, v6, v7
	global_store_dwordx2 v[18:19], v[4:5], off offset:64
	v_mov_b64_e32 v[4:5], v[236:237]
	v_mov_b64_e32 v[6:7], v[238:239]
	v_pk_mul_f32 v[0:1], v[0:1], v[4:5]
	s_nop 0
	v_cvt_pk_bf16_f32 v4, v0, v1
	v_pk_mul_f32 v[0:1], v[2:3], v[16:17] op_sel_hi:[1,0]
	global_store_dword v[18:19], v4, off offset:96
	v_pk_mul_f32 v[22:23], v[0:1], v[6:7]
	s_nop 0
	v_mov_b32_e32 v24, v23
	s_branch .LBB0_533

; __device__ __forceinline__ int opaque_tid() { int t = threadIdx.x; asm volatile("" : "+v"(t)); return t; }
; template <class Epi>
; __device__ __forceinline__ void gemm_tile(const bf16_t* A, int lda, const bf16_t* Bt, int ldb, int K, int m0, int n0, const Epi& epi, char* smem) {
;     const int tid = opaque_tid(), lane = tid & 63, wid = tid >> 6, wr = wid >> 1, wc = wid & 1, fr = lane & 15, fq = lane >> 4;
;     f32x4 acc[4][4];
; #pragma unroll
;     for (int m = 0; m < 4; ++m)
; #pragma unroll
;         for (int n = 0; n < 4; ++n) acc[m][n] = (f32x4){0.f, 0.f, 0.f, 0.f};
;     const int lr = lane >> 3;
;     const bf16_t* Ag[4]; const bf16_t* Bg[4];
; #pragma unroll
;     for (int i = 0; i < 4; ++i) {
;         const int r = (wid + 4 * i) * 8 + lr, lc = (lane & 7) ^ ((r >> 1) & 7);
;         Ag[i] = A + (size_t)(m0 + r) * lda + lc * 8; Bg[i] = Bt + (size_t)(n0 + r) * ldb + lc * 8;
;     }
;     const unsigned lds0 = (unsigned)(uintptr_t)smem;
;     const int rsw = (fr >> 1) & 7;
;     const int aofs = (wr * 64 + fr) * 128, bofs = 16384 + (wc * 64 + fr) * 128;
;     const int nk = K >> 6;
;     ...
;     G_ISSUE(0, 0)
;     asm volatile("s_waitcnt vmcnt(0)" ::: "memory");
;     __syncthreads();
;     for (int kt = 0; kt < nk; ++kt) {
;         const int st = (kt & 1) * 32768;
;         if (kt + 1 < nk) G_ISSUE(((kt + 1) & 1) * 32768, (kt + 1) * 64)
.LBB0_611:
	v_mov_b32_e32 v86, v109
	s_lshl_b32 s30, s49, 7
	s_waitcnt vmcnt(1)
	v_ashrrev_i32_e32 v16, 6, v86
	s_waitcnt vmcnt(1)
	v_bfe_u32 v0, v86, 3, 3
	v_lshl_or_b32 v14, v16, 3, v0
	v_lshrrev_b32_e32 v0, 1, v14
	v_xor_b32_e32 v2, v0, v86
	s_lshl_b32 s31, s47, 7
	v_readlane_b32 s0, v252, 28
	v_lshlrev_b32_e32 v2, 4, v2
	v_add_u32_e32 v0, s30, v14
	v_readlane_b32 s1, v252, 29
	v_and_b32_e32 v104, 0x70, v2
	v_add_u32_e32 v2, s31, v14
	s_waitcnt vmcnt(0)
	v_add_u32_e32 v6, 32, v14
	v_add_u32_e32 v10, 64, v14
	v_add_u32_e32 v14, 0x60, v14
	v_mov_b64_e32 v[12:13], s[0:1]
	s_movk_i32 s6, 0x640
	v_add_u32_e32 v4, s30, v6
	v_add_u32_e32 v8, s30, v10
	v_add_u32_e32 v15, s30, v14
	v_lshlrev_b32_e32 v20, 10, v16
	v_and_b32_e32 v87, 1, v16
	v_mad_i64_i32 v[0:1], s[0:1], v0, s6, v[12:13]
	v_mad_i64_i32 v[4:5], s[0:1], v4, s6, v[12:13]
	v_mad_i64_i32 v[8:9], s[0:1], v8, s6, v[12:13]
	v_mad_i64_i32 v[12:13], s[0:1], v15, s6, v[12:13]
	v_add_u32_e32 v16, 0x4000, v20
	v_ashrrev_i32_e32 v3, 31, v2
	v_readlane_b32 s4, v252, 30
	v_readfirstlane_b32 s1, v16
	v_add_u32_e32 v16, 0x1000, v20
	v_lshlrev_b64 v[2:3], 9, v[2:3]
	v_readlane_b32 s5, v252, 31
	v_add_u32_e32 v6, s31, v6
	v_readfirstlane_b32 s54, v20
	v_readfirstlane_b32 s34, v16
	v_add_u32_e32 v16, 0x5000, v20
	v_lshl_add_u64 v[0:1], v[0:1], 0, v[104:105]
	v_lshl_add_u64 v[2:3], s[4:5], 0, v[2:3]
	v_ashrrev_i32_e32 v7, 31, v6
	s_mov_b32 m0, s54
	v_readfirstlane_b32 s35, v16
	v_add_u32_e32 v16, 0x2000, v20
	v_lshl_add_u64 v[2:3], v[2:3], 0, v[104:105]
	v_lshlrev_b64 v[6:7], 9, v[6:7]
	v_add_u32_e32 v10, s31, v10
	global_load_lds_dwordx4 v[0:1], off
	s_mov_b32 m0, s1
	v_readfirstlane_b32 s50, v16
	v_add_u32_e32 v16, 0x6000, v20
	v_lshl_add_u64 v[4:5], v[4:5], 0, v[104:105]
	v_lshl_add_u64 v[6:7], s[4:5], 0, v[6:7]
	v_ashrrev_i32_e32 v11, 31, v10
	v_add_u32_e32 v14, s31, v14
	global_load_lds_dwordx4 v[2:3], off
	s_mov_b32 m0, s34
	v_readfirstlane_b32 s51, v16
	v_add_u32_e32 v16, 0x3000, v20
	v_and_b32_e32 v85, 15, v86
	v_lshl_add_u64 v[6:7], v[6:7], 0, v[104:105]
	v_lshlrev_b64 v[10:11], 9, v[10:11]
	v_ashrrev_i32_e32 v15, 31, v14
	v_lshrrev_b32_e32 v17, 1, v86
	v_bfe_u32 v18, v86, 1, 3
	global_load_lds_dwordx4 v[4:5], off
	s_mov_b32 m0, s35
	v_readfirstlane_b32 s53, v16
	v_add_u32_e32 v16, 0x7000, v20
	v_bfe_u32 v64, v86, 4, 2
	v_ashrrev_i32_e32 v65, 7, v86
	v_lshl_add_u64 v[8:9], v[8:9], 0, v[104:105]
	v_lshl_add_u64 v[10:11], s[4:5], 0, v[10:11]
	v_lshlrev_b64 v[14:15], 9, v[14:15]
	v_lshlrev_b32_e32 v19, 7, v85
	global_load_lds_dwordx4 v[6:7], off
	s_mov_b32 m0, s50
	v_readfirstlane_b32 s55, v16
	v_bitop3_b32 v16, v64, v17, 7 bitop3:0x78
	v_bitop3_b32 v17, v64, v18, 4 bitop3:0x36
	v_lshl_add_u64 v[10:11], v[10:11], 0, v[104:105]
	v_lshl_add_u64 v[14:15], s[4:5], 0, v[14:15]
	global_load_lds_dwordx4 v[8:9], off
	s_mov_b32 m0, s51
	v_lshlrev_b32_e32 v16, 4, v16
	v_lshlrev_b32_e32 v17, 4, v17
	v_lshl_or_b32 v18, v65, 13, v19
	v_lshl_add_u64 v[12:13], v[12:13], 0, v[104:105]
	v_lshl_add_u64 v[14:15], v[14:15], 0, v[104:105]
	global_load_lds_dwordx4 v[10:11], off
	s_mov_b32 m0, s53
	v_or_b32_e32 v82, v18, v16
	v_or_b32_e32 v104, v18, v17
	v_add_u32_e32 v18, 0x8000, v20
	global_load_lds_dwordx4 v[12:13], off
	s_mov_b32 m0, s55
	v_lshl_or_b32 v19, v87, 13, v19
	s_mov_b64 s[4:5], 0x80
	v_readfirstlane_b32 s43, v18
	v_add_u32_e32 v18, 0xc000, v20
	global_load_lds_dwordx4 v[14:15], off
	v_or_b32_e32 v83, v19, v16
	v_or_b32_e32 v111, v19, v17
	v_lshl_add_u64 v[16:17], v[0:1], 0, s[4:5]
	s_mov_b32 m0, s43
	v_readfirstlane_b32 s0, v18
	v_add_u32_e32 v18, 0x9000, v20
	s_waitcnt vmcnt(0)
	s_waitcnt vmcnt(0) lgkmcnt(0)
	s_barrier
	global_load_lds_dwordx4 v[16:17], off
	v_lshl_add_u64 v[16:17], v[2:3], 0, s[4:5]
	s_mov_b32 m0, s0
	v_readfirstlane_b32 s31, v18
	v_add_u32_e32 v18, 0xd000, v20
	global_load_lds_dwordx4 v[16:17], off
	v_lshl_add_u64 v[16:17], v[4:5], 0, s[4:5]
	s_mov_b32 m0, s31
	v_readfirstlane_b32 s42, v18
	v_add_u32_e32 v18, 0xa000, v20
	global_load_lds_dwordx4 v[16:17], off
	v_lshl_add_u64 v[16:17], v[6:7], 0, s[4:5]
	s_mov_b32 m0, s42
	v_readfirstlane_b32 s52, v18
	v_add_u32_e32 v18, 0xe000, v20
	global_load_lds_dwordx4 v[16:17], off
	v_lshl_add_u64 v[16:17], v[8:9], 0, s[4:5]
	s_mov_b32 m0, s52
	v_readfirstlane_b32 s56, v18
	v_add_u32_e32 v18, 0xb000, v20
	global_load_lds_dwordx4 v[16:17], off
	v_lshl_add_u64 v[16:17], v[10:11], 0, s[4:5]
	s_mov_b32 m0, s56
	v_readfirstlane_b32 s57, v18
	v_add_u32_e32 v18, 0xf000, v20
	global_load_lds_dwordx4 v[16:17], off
	v_lshl_add_u64 v[16:17], v[12:13], 0, s[4:5]
	s_mov_b32 m0, s57
	v_readfirstlane_b32 s58, v18
	global_load_lds_dwordx4 v[16:17], off
	v_lshl_add_u64 v[16:17], v[14:15], 0, s[4:5]
	s_mov_b32 m0, s58
	s_nop 0
	global_load_lds_dwordx4 v[16:17], off
	ds_read_b128 v[16:19], v82
	ds_read_b128 v[20:23], v82 offset:2048
	ds_read_b128 v[24:27], v82 offset:4096
	ds_read_b128 v[28:31], v82 offset:6144
	ds_read_b128 v[32:35], v83 offset:16384
	ds_read_b128 v[36:39], v83 offset:18432
	ds_read_b128 v[40:43], v83 offset:20480
	ds_read_b128 v[44:47], v83 offset:22528
	ds_read_b128 v[48:51], v104
	ds_read_b128 v[52:55], v104 offset:2048
	ds_read_b128 v[56:59], v104 offset:4096
	ds_read_b128 v[60:63], v104 offset:6144
	ds_read_b128 v[66:69], v111 offset:16384
	ds_read_b128 v[70:73], v111 offset:18432
	ds_read_b128 v[74:77], v111 offset:20480
	ds_read_b128 v[78:81], v111 offset:22528
	s_setprio 1
	s_waitcnt lgkmcnt(0)
; template <class Epi>
; __device__ __forceinline__ void gemm_tile(const bf16_t* A, int lda, const bf16_t* Bt, int ldb, int K, int m0, int n0, const Epi& epi, char* smem) {
;     ...
;     for (int kt = 0; kt < nk; ++kt) {
;         const int st = (kt & 1) * 32768;
;         if (kt + 1 < nk) G_ISSUE(((kt + 1) & 1) * 32768, (kt + 1) * 64)
;         {
;             bf16x8 a0[4], b0[4], a1[4], b1[4];
;             const int ch0 = ((0 + fq) ^ rsw) << 4, ch1 = ((4 + fq) ^ rsw) << 4;
; #pragma unroll
;             for (int m = 0; m < 4; ++m) a0[m] = *(const bf16x8*)(smem + st + aofs + m * 2048 + ch0);
; #pragma unroll
;             for (int n = 0; n < 4; ++n) b0[n] = *(const bf16x8*)(smem + st + bofs + n * 2048 + ch0);
;             __builtin_amdgcn_sched_barrier(0);
; #pragma unroll
;             for (int m = 0; m < 4; ++m) a1[m] = *(const bf16x8*)(smem + st + aofs + m * 2048 + ch1);
; #pragma unroll
;             for (int n = 0; n < 4; ++n) b1[n] = *(const bf16x8*)(smem + st + bofs + n * 2048 + ch1);
;             __builtin_amdgcn_sched_barrier(0);
;             __builtin_amdgcn_s_setprio(1);
; #pragma unroll
;             for (int m = 0; m < 4; ++m)
; #pragma unroll
;                 for (int n = 0; n < 4; ++n) acc[m][n] = __builtin_amdgcn_mfma_f32_16x16x32_bf16(b0[n], a0[m], acc[m][n], 0, 0, 0);
;             __builtin_amdgcn_sched_barrier(0);
; #pragma unroll
;             for (int m = 0; m < 4; ++m)
; #pragma unroll
;                 for (int n = 0; n < 4; ++n) acc[m][n] = __builtin_amdgcn_mfma_f32_16x16x32_bf16(b1[n], a1[m], acc[m][n], 0, 0, 0);
;             __builtin_amdgcn_s_setprio(0);
	v_mfma_f32_16x16x32_bf16 v[88:91], v[32:35], v[16:19], 0
	v_mfma_f32_16x16x32_bf16 v[92:95], v[36:39], v[16:19], 0
	v_mfma_f32_16x16x32_bf16 v[96:99], v[40:43], v[16:19], 0
	v_mfma_f32_16x16x32_bf16 v[16:19], v[44:47], v[16:19], 0
	v_mfma_f32_16x16x32_bf16 v[100:103], v[32:35], v[20:23], 0
	v_mfma_f32_16x16x32_bf16 v[114:117], v[36:39], v[20:23], 0
	v_mfma_f32_16x16x32_bf16 v[118:121], v[40:43], v[20:23], 0
	v_mfma_f32_16x16x32_bf16 v[20:23], v[44:47], v[20:23], 0
	v_mfma_f32_16x16x32_bf16 v[122:125], v[32:35], v[24:27], 0
	v_mfma_f32_16x16x32_bf16 v[126:129], v[36:39], v[24:27], 0
	v_mfma_f32_16x16x32_bf16 v[130:133], v[40:43], v[24:27], 0
	v_mfma_f32_16x16x32_bf16 v[24:27], v[44:47], v[24:27], 0
	v_mfma_f32_16x16x32_bf16 v[32:35], v[32:35], v[28:31], 0
	v_mfma_f32_16x16x32_bf16 v[36:39], v[36:39], v[28:31], 0
	v_mfma_f32_16x16x32_bf16 v[40:43], v[40:43], v[28:31], 0
	v_mfma_f32_16x16x32_bf16 v[28:31], v[44:47], v[28:31], 0
	v_mfma_f32_16x16x32_bf16 v[44:47], v[66:69], v[48:51], v[88:91]
	v_mfma_f32_16x16x32_bf16 v[88:91], v[70:73], v[48:51], v[92:95]
	v_mfma_f32_16x16x32_bf16 v[92:95], v[74:77], v[48:51], v[96:99]
	v_mfma_f32_16x16x32_bf16 v[16:19], v[78:81], v[48:51], v[16:19]
	v_mfma_f32_16x16x32_bf16 v[48:51], v[66:69], v[52:55], v[100:103]
	v_mfma_f32_16x16x32_bf16 v[96:99], v[70:73], v[52:55], v[114:117]
	v_mfma_f32_16x16x32_bf16 v[100:103], v[74:77], v[52:55], v[118:121]
	v_mfma_f32_16x16x32_bf16 v[20:23], v[78:81], v[52:55], v[20:23]
	v_mfma_f32_16x16x32_bf16 v[52:55], v[66:69], v[56:59], v[122:125]
	v_mfma_f32_16x16x32_bf16 v[24:27], v[78:81], v[56:59], v[24:27]
	v_mfma_f32_16x16x32_bf16 v[32:35], v[66:69], v[60:63], v[32:35]
	v_mfma_f32_16x16x32_bf16 v[36:39], v[70:73], v[60:63], v[36:39]
	v_mfma_f32_16x16x32_bf16 v[40:43], v[74:77], v[60:63], v[40:43]
	v_mfma_f32_16x16x32_bf16 v[28:31], v[78:81], v[60:63], v[28:31]
	v_mfma_f32_16x16x32_bf16 v[114:117], v[70:73], v[56:59], v[126:129]
	v_mfma_f32_16x16x32_bf16 v[118:121], v[74:77], v[56:59], v[130:133]
	s_setprio 0
	s_mov_b64 s[4:5], 0x100
	s_mov_b32 m0, s54
	v_lshl_add_u64 v[56:57], v[0:1], 0, s[4:5]
	s_waitcnt vmcnt(0)
	s_waitcnt vmcnt(0)
	s_barrier
	global_load_lds_dwordx4 v[56:57], off
	v_lshl_add_u64 v[56:57], v[2:3], 0, s[4:5]
	s_mov_b32 m0, s1
	s_nop 0
	global_load_lds_dwordx4 v[56:57], off
	v_lshl_add_u64 v[56:57], v[4:5], 0, s[4:5]
	s_mov_b32 m0, s34
	s_nop 0
	global_load_lds_dwordx4 v[56:57], off
	v_lshl_add_u64 v[56:57], v[6:7], 0, s[4:5]
	s_mov_b32 m0, s35
	s_nop 0
	global_load_lds_dwordx4 v[56:57], off
	v_lshl_add_u64 v[56:57], v[8:9], 0, s[4:5]
	s_mov_b32 m0, s50
	s_nop 0
	global_load_lds_dwordx4 v[56:57], off
	v_lshl_add_u64 v[56:57], v[10:11], 0, s[4:5]
	s_mov_b32 m0, s51
	s_nop 0
	global_load_lds_dwordx4 v[56:57], off
	v_lshl_add_u64 v[56:57], v[12:13], 0, s[4:5]
	s_mov_b32 m0, s53
	s_nop 0
	global_load_lds_dwordx4 v[56:57], off
	v_lshl_add_u64 v[56:57], v[14:15], 0, s[4:5]
	s_mov_b32 m0, s55
	s_nop 0
	global_load_lds_dwordx4 v[56:57], off
	ds_read_b128 v[56:59], v82 offset:32768
	ds_read_b128 v[60:63], v82 offset:34816
	ds_read_b128 v[66:69], v82 offset:36864
	ds_read_b128 v[70:73], v82 offset:38912
	ds_read_b128 v[74:77], v83 offset:49152
	ds_read_b128 v[78:81], v83 offset:51200
	ds_read_b128 v[122:125], v83 offset:53248
	ds_read_b128 v[126:129], v83 offset:55296
	ds_read_b128 v[130:133], v104 offset:32768
	ds_read_b128 v[134:137], v104 offset:34816
	ds_read_b128 v[138:141], v104 offset:36864
	ds_read_b128 v[142:145], v104 offset:38912
	ds_read_b128 v[146:149], v111 offset:49152
	ds_read_b128 v[150:153], v111 offset:51200
	ds_read_b128 v[154:157], v111 offset:53248
	ds_read_b128 v[158:161], v111 offset:55296
	s_setprio 1
	s_waitcnt lgkmcnt(0)
	v_mfma_f32_16x16x32_bf16 v[44:47], v[74:77], v[56:59], v[44:47]
	v_mfma_f32_16x16x32_bf16 v[88:91], v[78:81], v[56:59], v[88:91]
	v_mfma_f32_16x16x32_bf16 v[92:95], v[122:125], v[56:59], v[92:95]
	v_mfma_f32_16x16x32_bf16 v[16:19], v[126:129], v[56:59], v[16:19]
	v_mfma_f32_16x16x32_bf16 v[48:51], v[74:77], v[60:63], v[48:51]
	v_mfma_f32_16x16x32_bf16 v[56:59], v[78:81], v[60:63], v[96:99]
	v_mfma_f32_16x16x32_bf16 v[96:99], v[122:125], v[60:63], v[100:103]
	v_mfma_f32_16x16x32_bf16 v[20:23], v[126:129], v[60:63], v[20:23]
	v_mfma_f32_16x16x32_bf16 v[52:55], v[74:77], v[66:69], v[52:55]
	v_mfma_f32_16x16x32_bf16 v[60:63], v[78:81], v[66:69], v[114:117]
	v_mfma_f32_16x16x32_bf16 v[24:27], v[126:129], v[66:69], v[24:27]
	v_mfma_f32_16x16x32_bf16 v[32:35], v[74:77], v[70:73], v[32:35]
	v_mfma_f32_16x16x32_bf16 v[36:39], v[78:81], v[70:73], v[36:39]
	v_mfma_f32_16x16x32_bf16 v[40:43], v[122:125], v[70:73], v[40:43]
	v_mfma_f32_16x16x32_bf16 v[28:31], v[126:129], v[70:73], v[28:31]
	v_mfma_f32_16x16x32_bf16 v[100:103], v[122:125], v[66:69], v[118:121]
	v_mfma_f32_16x16x32_bf16 v[44:47], v[146:149], v[130:133], v[44:47]
	v_mfma_f32_16x16x32_bf16 v[16:19], v[158:161], v[130:133], v[16:19]
	v_mfma_f32_16x16x32_bf16 v[48:51], v[146:149], v[134:137], v[48:51]
	v_mfma_f32_16x16x32_bf16 v[56:59], v[150:153], v[134:137], v[56:59]
	v_mfma_f32_16x16x32_bf16 v[20:23], v[158:161], v[134:137], v[20:23]
	v_mfma_f32_16x16x32_bf16 v[52:55], v[146:149], v[138:141], v[52:55]
	v_mfma_f32_16x16x32_bf16 v[60:63], v[150:153], v[138:141], v[60:63]
	v_mfma_f32_16x16x32_bf16 v[24:27], v[158:161], v[138:141], v[24:27]
	v_mfma_f32_16x16x32_bf16 v[32:35], v[146:149], v[142:145], v[32:35]
	v_mfma_f32_16x16x32_bf16 v[36:39], v[150:153], v[142:145], v[36:39]
	v_mfma_f32_16x16x32_bf16 v[40:43], v[154:157], v[142:145], v[40:43]
	v_mfma_f32_16x16x32_bf16 v[28:31], v[158:161], v[142:145], v[28:31]
	v_mfma_f32_16x16x32_bf16 v[66:69], v[150:153], v[130:133], v[88:91]
	v_mfma_f32_16x16x32_bf16 v[70:73], v[154:157], v[130:133], v[92:95]
	v_mfma_f32_16x16x32_bf16 v[74:77], v[154:157], v[134:137], v[96:99]
	v_mfma_f32_16x16x32_bf16 v[78:81], v[154:157], v[138:141], v[100:103]
	s_setprio 0
	s_mov_b64 s[4:5], 0x180
	s_mov_b32 m0, s43
	v_lshl_add_u64 v[0:1], v[0:1], 0, s[4:5]
	s_waitcnt vmcnt(0)
	s_waitcnt vmcnt(0)
	s_barrier
; template <class Epi>
; __device__ __forceinline__ void gemm_tile(const bf16_t* A, int lda, const bf16_t* Bt, int ldb, int K, int m0, int n0, const Epi& epi, char* smem) {
;     ...
;     for (int kt = 0; kt < nk; ++kt) {
;         const int st = (kt & 1) * 32768;
;         if (kt + 1 < nk) G_ISSUE(((kt + 1) & 1) * 32768, (kt + 1) * 64)
;         {
;             bf16x8 a0[4], b0[4], a1[4], b1[4];
;             const int ch0 = ((0 + fq) ^ rsw) << 4, ch1 = ((4 + fq) ^ rsw) << 4;
; #pragma unroll
;             for (int m = 0; m < 4; ++m) a0[m] = *(const bf16x8*)(smem + st + aofs + m * 2048 + ch0);
; #pragma unroll
;             for (int n = 0; n < 4; ++n) b0[n] = *(const bf16x8*)(smem + st + bofs + n * 2048 + ch0);
;             __builtin_amdgcn_sched_barrier(0);
; #pragma unroll
;             for (int m = 0; m < 4; ++m) a1[m] = *(const bf16x8*)(smem + st + aofs + m * 2048 + ch1);
; #pragma unroll
;             for (int n = 0; n < 4; ++n) b1[n] = *(const bf16x8*)(smem + st + bofs + n * 2048 + ch1);
;             __builtin_amdgcn_sched_barrier(0);
;             __builtin_amdgcn_s_setprio(1);
; #pragma unroll
;             for (int m = 0; m < 4; ++m)
; #pragma unroll
;                 for (int n = 0; n < 4; ++n) acc[m][n] = __builtin_amdgcn_mfma_f32_16x16x32_bf16(b0[n], a0[m], acc[m][n], 0, 0, 0);
;             __builtin_amdgcn_sched_barrier(0);
; #pragma unroll
;             for (int m = 0; m < 4; ++m)
; #pragma unroll
;                 for (int n = 0; n < 4; ++n) acc[m][n] = __builtin_amdgcn_mfma_f32_16x16x32_bf16(b1[n], a1[m], acc[m][n], 0, 0, 0);
;             __builtin_amdgcn_s_setprio(0);
;             __builtin_amdgcn_sched_barrier(0);
;         }
;         asm volatile("s_waitcnt vmcnt(0)" ::: "memory");
;         __syncthreads();
;     }
;     ...
;     epi(acc, m0, n0, wr, wc, fr, fq, smem);
;     __device__ __forceinline__ void operator()(const f32x4 (&acc)[4][4], int m0, int n0, int wr, int wc, int fr, int fq, char* smem) const {
;         const int h = n0 >> 7;
; #pragma unroll
;         for (int m = 0; m < 4; ++m) {
;             const int row = m0 + wr * 64 + m * 16 + fr;
;             const int b = row / TT, t = row - b * TT;
;             const float skv = stats[(size_t)row * 12 + 8] + stats[(size_t)row * 12 + 9] + stats[(size_t)row * 12 + 10] + stats[(size_t)row * 12 + 11];
;             const float rstd = rsqrtf(skv * (1.f / 256.f) + 1e-6f);
	global_load_lds_dwordx4 v[0:1], off
	v_lshl_add_u64 v[0:1], v[2:3], 0, s[4:5]
	s_mov_b32 m0, s0
	s_nop 0
	global_load_lds_dwordx4 v[0:1], off
	v_lshl_add_u64 v[0:1], v[4:5], 0, s[4:5]
	s_mov_b32 m0, s31
	s_nop 0
	global_load_lds_dwordx4 v[0:1], off
	v_lshl_add_u64 v[0:1], v[6:7], 0, s[4:5]
	s_mov_b32 m0, s42
	s_nop 0
	global_load_lds_dwordx4 v[0:1], off
	v_lshl_add_u64 v[0:1], v[8:9], 0, s[4:5]
	s_mov_b32 m0, s52
	s_nop 0
	global_load_lds_dwordx4 v[0:1], off
	v_lshl_add_u64 v[0:1], v[10:11], 0, s[4:5]
	s_mov_b32 m0, s56
	s_nop 0
	global_load_lds_dwordx4 v[0:1], off
	v_lshl_add_u64 v[0:1], v[12:13], 0, s[4:5]
	s_mov_b32 m0, s57
	s_nop 0
	global_load_lds_dwordx4 v[0:1], off
	v_lshl_add_u64 v[0:1], v[14:15], 0, s[4:5]
	s_mov_b32 m0, s58
	s_nop 0
	global_load_lds_dwordx4 v[0:1], off
	ds_read_b128 v[0:3], v82
	ds_read_b128 v[4:7], v82 offset:2048
	ds_read_b128 v[8:11], v82 offset:4096
	ds_read_b128 v[12:15], v82 offset:6144
	ds_read_b128 v[88:91], v83 offset:16384
	ds_read_b128 v[92:95], v83 offset:18432
	ds_read_b128 v[96:99], v83 offset:20480
	ds_read_b128 v[100:103], v83 offset:22528
	ds_read_b128 v[114:117], v104
	ds_read_b128 v[118:121], v104 offset:2048
	ds_read_b128 v[122:125], v104 offset:4096
	ds_read_b128 v[126:129], v104 offset:6144
	ds_read_b128 v[130:133], v111 offset:16384
	ds_read_b128 v[134:137], v111 offset:18432
	ds_read_b128 v[138:141], v111 offset:20480
	ds_read_b128 v[142:145], v111 offset:22528
	s_setprio 1
	s_waitcnt lgkmcnt(0)
	v_mfma_f32_16x16x32_bf16 v[44:47], v[88:91], v[0:3], v[44:47]
	v_mfma_f32_16x16x32_bf16 v[66:69], v[92:95], v[0:3], v[66:69]
	v_mfma_f32_16x16x32_bf16 v[70:73], v[96:99], v[0:3], v[70:73]
	v_mfma_f32_16x16x32_bf16 v[0:3], v[100:103], v[0:3], v[16:19]
	v_mfma_f32_16x16x32_bf16 v[16:19], v[88:91], v[4:7], v[48:51]
	v_mfma_f32_16x16x32_bf16 v[48:51], v[92:95], v[4:7], v[56:59]
	v_mfma_f32_16x16x32_bf16 v[56:59], v[96:99], v[4:7], v[74:77]
	v_mfma_f32_16x16x32_bf16 v[4:7], v[100:103], v[4:7], v[20:23]
	v_mfma_f32_16x16x32_bf16 v[20:23], v[88:91], v[8:11], v[52:55]
	v_mfma_f32_16x16x32_bf16 v[52:55], v[92:95], v[8:11], v[60:63]
	v_mfma_f32_16x16x32_bf16 v[60:63], v[96:99], v[8:11], v[78:81]
	v_mfma_f32_16x16x32_bf16 v[8:11], v[100:103], v[8:11], v[24:27]
	v_mfma_f32_16x16x32_bf16 v[24:27], v[88:91], v[12:15], v[32:35]
	v_mfma_f32_16x16x32_bf16 v[32:35], v[92:95], v[12:15], v[36:39]
	v_mfma_f32_16x16x32_bf16 v[36:39], v[96:99], v[12:15], v[40:43]
	v_mfma_f32_16x16x32_bf16 v[12:15], v[100:103], v[12:15], v[28:31]
	v_mfma_f32_16x16x32_bf16 v[28:31], v[130:133], v[114:117], v[44:47]
	v_mfma_f32_16x16x32_bf16 v[40:43], v[134:137], v[114:117], v[66:69]
	v_mfma_f32_16x16x32_bf16 v[44:47], v[138:141], v[114:117], v[70:73]
	v_mfma_f32_16x16x32_bf16 v[0:3], v[142:145], v[114:117], v[0:3]
	v_mfma_f32_16x16x32_bf16 v[16:19], v[130:133], v[118:121], v[16:19]
	v_mfma_f32_16x16x32_bf16 v[48:51], v[134:137], v[118:121], v[48:51]
	v_mfma_f32_16x16x32_bf16 v[56:59], v[138:141], v[118:121], v[56:59]
	v_mfma_f32_16x16x32_bf16 v[4:7], v[142:145], v[118:121], v[4:7]
	v_mfma_f32_16x16x32_bf16 v[20:23], v[130:133], v[122:125], v[20:23]
	v_mfma_f32_16x16x32_bf16 v[52:55], v[134:137], v[122:125], v[52:55]
	v_mfma_f32_16x16x32_bf16 v[60:63], v[138:141], v[122:125], v[60:63]
	v_mfma_f32_16x16x32_bf16 v[8:11], v[142:145], v[122:125], v[8:11]
	v_mfma_f32_16x16x32_bf16 v[24:27], v[130:133], v[126:129], v[24:27]
	v_mfma_f32_16x16x32_bf16 v[32:35], v[134:137], v[126:129], v[32:35]
	v_mfma_f32_16x16x32_bf16 v[36:39], v[138:141], v[126:129], v[36:39]
	v_mfma_f32_16x16x32_bf16 v[12:15], v[142:145], v[126:129], v[12:15]
	s_setprio 0
	s_waitcnt vmcnt(0)
	s_waitcnt vmcnt(0)
	s_barrier
	ds_read_b128 v[66:69], v83 offset:55296
	ds_read_b128 v[70:73], v83 offset:53248
	ds_read_b128 v[74:77], v83 offset:51200
	ds_read_b128 v[78:81], v83 offset:49152
	ds_read_b128 v[88:91], v82 offset:38912
	ds_read_b128 v[92:95], v82 offset:36864
	ds_read_b128 v[96:99], v82 offset:34816
	ds_read_b128 v[100:103], v82 offset:32768
	ds_read_b128 v[114:117], v104 offset:32768
	ds_read_b128 v[118:121], v104 offset:34816
	ds_read_b128 v[122:125], v104 offset:36864
	ds_read_b128 v[126:129], v104 offset:38912
	ds_read_b128 v[130:133], v111 offset:49152
	ds_read_b128 v[134:137], v111 offset:51200
	ds_read_b128 v[138:141], v111 offset:53248
	ds_read_b128 v[142:145], v111 offset:55296
	s_setprio 1
	s_waitcnt lgkmcnt(8)
	v_mfma_f32_16x16x32_bf16 v[28:31], v[78:81], v[100:103], v[28:31]
	v_mfma_f32_16x16x32_bf16 v[40:43], v[74:77], v[100:103], v[40:43]
	v_mfma_f32_16x16x32_bf16 v[44:47], v[70:73], v[100:103], v[44:47]
	v_mfma_f32_16x16x32_bf16 v[0:3], v[66:69], v[100:103], v[0:3]
	v_mfma_f32_16x16x32_bf16 v[16:19], v[78:81], v[96:99], v[16:19]
	v_mfma_f32_16x16x32_bf16 v[4:7], v[66:69], v[96:99], v[4:7]
	v_mfma_f32_16x16x32_bf16 v[20:23], v[78:81], v[92:95], v[20:23]
	v_mfma_f32_16x16x32_bf16 v[8:11], v[66:69], v[92:95], v[8:11]
	v_mfma_f32_16x16x32_bf16 v[100:103], v[74:77], v[96:99], v[48:51]
	v_mfma_f32_16x16x32_bf16 v[146:149], v[70:73], v[96:99], v[56:59]
	v_mfma_f32_16x16x32_bf16 v[96:99], v[74:77], v[92:95], v[52:55]
	v_mfma_f32_16x16x32_bf16 v[150:153], v[70:73], v[92:95], v[60:63]
	v_mfma_f32_16x16x32_bf16 v[78:81], v[78:81], v[88:91], v[24:27]
	v_mfma_f32_16x16x32_bf16 v[74:77], v[74:77], v[88:91], v[32:35]
	v_mfma_f32_16x16x32_bf16 v[70:73], v[70:73], v[88:91], v[36:39]
	v_mfma_f32_16x16x32_bf16 v[66:69], v[66:69], v[88:91], v[12:15]
	s_waitcnt lgkmcnt(3)
	v_mfma_f32_16x16x32_bf16 v[60:63], v[130:133], v[114:117], v[28:31]
	s_waitcnt lgkmcnt(2)
	v_mfma_f32_16x16x32_bf16 v[56:59], v[134:137], v[114:117], v[40:43]
	s_waitcnt lgkmcnt(1)
	v_mfma_f32_16x16x32_bf16 v[52:55], v[138:141], v[114:117], v[44:47]
	s_waitcnt lgkmcnt(0)
	v_mfma_f32_16x16x32_bf16 v[48:51], v[142:145], v[114:117], v[0:3]
	v_mfma_f32_16x16x32_bf16 v[44:47], v[130:133], v[118:121], v[16:19]
	v_mfma_f32_16x16x32_bf16 v[40:43], v[134:137], v[118:121], v[100:103]
	v_mfma_f32_16x16x32_bf16 v[36:39], v[138:141], v[118:121], v[146:149]
	v_mfma_f32_16x16x32_bf16 v[32:35], v[142:145], v[118:121], v[4:7]
	v_mfma_f32_16x16x32_bf16 v[28:31], v[130:133], v[122:125], v[20:23]
	v_mfma_f32_16x16x32_bf16 v[24:27], v[134:137], v[122:125], v[96:99]
	v_mfma_f32_16x16x32_bf16 v[20:23], v[138:141], v[122:125], v[150:153]
	v_mfma_f32_16x16x32_bf16 v[16:19], v[142:145], v[122:125], v[8:11]
	v_mfma_f32_16x16x32_bf16 v[12:15], v[130:133], v[126:129], v[78:81]
	v_mfma_f32_16x16x32_bf16 v[8:11], v[134:137], v[126:129], v[74:77]
	v_mfma_f32_16x16x32_bf16 v[4:7], v[138:141], v[126:129], v[70:73]
	v_mfma_f32_16x16x32_bf16 v[0:3], v[142:145], v[126:129], v[66:69]
	s_setprio 0
	v_lshlrev_b32_e32 v65, 6, v65
	s_nop 0
	v_or_b32_e32 v66, s30, v85
	v_readlane_b32 s0, v252, 20
	v_add_u32_e32 v90, v66, v65
	v_readlane_b32 s1, v252, 21
	s_waitcnt vmcnt(0)
	s_barrier
;     __device__ __forceinline__ void operator()(const f32x4 (&acc)[4][4], int m0, int n0, int wr, int wc, int fr, int fq, char* smem) const {
;     ...
;         for (int m = 0; m < 4; ++m) {
;             const int row = m0 + wr * 64 + m * 16 + fr;
;             const int b = row / TT, t = row - b * TT;
;             const float skv = stats[(size_t)row * 12 + 8] + stats[(size_t)row * 12 + 9] + stats[(size_t)row * 12 + 10] + stats[(size_t)row * 12 + 11];
;             const float rstd = rsqrtf(skv * (1.f / 256.f) + 1e-6f);
;             if (wc == 0) {
;                 float ss = 0.f;
; #pragma unroll
;                 for (int n = 0; n < 4; ++n) { const f32x4 v = acc[m][n]; ss += v[0] * v[0] + v[1] * v[1] + v[2] * v[2] + v[3] * v[3]; }
;                 const int i0 = fq * 4;
;                 const u16x4 r1 = *(const u16x4*)(zb + (size_t)row * 800 + 768 + i0), r2 = *(const u16x4*)(zb + (size_t)row * 800 + 784 + i0);
;                 float x1[4], x2[4]; float sr = 0.f;
; #pragma unroll
;                 for (int j = 0; j < 4; ++j) { x1[j] = bf2f(r1[j]); x2[j] = bf2f(r2[j]); sr += x1[j] * x1[j] + x2[j] * x2[j]; }
;                 ss = ss * rstd * rstd + sr;
;                 ss += __shfl_xor(ss, 16); ss += __shfl_xor(ss, 32);
;                 const float sc = rsqrtf(ss * (1.f / 96.f) + 1e-6f);
;                 bf16_t* krow = Kb + ((size_t)(b * 8 + h) * TT + t) * 96;
;                 const float s1 = rstd * sc;
; #pragma unroll
;                 for (int n = 0; n < 4; ++n) {
;                     const int c = n * 16 + fq * 4;
;                     const f32x4 g = *(const f32x4*)(gk + c);
;                     const f32x4 v = acc[m][n];
;                     uint2 w; w.x = pack2bf(v[0] * s1 * g[0], v[1] * s1 * g[1]); w.y = pack2bf(v[2] * s1 * g[2], v[3] * s1 * g[3]);
;                     *(uint2*)(krow + c) = w;
;                 }
;                 const f32x4 g1 = *(const f32x4*)(gk + 64 + i0), g2 = *(const f32x4*)(gk + 80 + i0);
; #pragma unroll
;                 for (int j = 0; j < 4; ++j) { x1[j] *= sc * g1[j]; x2[j] *= sc * g2[j]; }
;                 if (t >= CTX) {
;                     const float* rp = rope + ((size_t)(t - CTX) * 16 + i0) * 2;
; #pragma unroll
;                     for (int j = 0; j < 4; ++j) { const float c = rp[2 * j], s = rp[2 * j + 1]; const float a = x1[j] * c - x2[j] * s, bb = x1[j] * s + x2[j] * c; x1[j] = a; x2[j] = bb; }
	s_nop 0
	v_mad_i64_i32 v[66:67], s[0:1], v90, 48, s[0:1]
	global_load_dwordx4 v[118:121], v[66:67], off offset:800
	global_load_dwordx4 v[122:125], v[66:67], off offset:1568
	global_load_dwordx4 v[126:129], v[66:67], off offset:2336
	global_load_dwordx4 v[66:69], v[66:67], off offset:32
	s_mov_b32 s0, 0x800000
	v_or_b32_e32 v65, v65, v85
	v_cmp_eq_u32_e32 vcc, 1, v87
	s_waitcnt vmcnt(0)
	v_add_f32_e32 v66, v66, v67
	v_add_f32_e32 v66, v66, v68
	v_add_f32_e32 v66, v66, v69
	v_fmamk_f32 v66, v66, 0x3b800000, v108
	v_mul_f32_e32 v67, 0x4b800000, v66
	v_cmp_gt_f32_e64 s[0:1], s0, v66
	s_nop 1
	v_cndmask_b32_e64 v66, v66, v67, s[0:1]
	v_rsq_f32_e32 v66, v66
	v_mul_u32_u24_e32 v67, 0x440, v64
	v_lshl_add_u32 v89, v65, 1, v67
	v_mul_f32_e32 v68, 0x45800000, v66
	v_cndmask_b32_e64 v91, v66, v68, s[0:1]
	s_and_saveexec_b64 s[0:1], vcc
	s_xor_b64 s[0:1], exec, s[0:1]
	s_cbranch_execz .LBB0_613
	v_mul_f32_e32 v60, v60, v91
	v_bfe_u32 v65, v60, 16, 1
	s_movk_i32 s4, 0x7fff
	v_add3_u32 v60, v60, v65, s4
	ds_write_b16_d16_hi v89, v60
	v_mul_f32_e32 v60, v61, v91
	v_bfe_u32 v61, v60, 16, 1
	v_add3_u32 v60, v60, v61, s4
	ds_write_b16_d16_hi v89, v60 offset:272
	v_mul_f32_e32 v60, v62, v91
	v_bfe_u32 v61, v60, 16, 1
	v_add3_u32 v60, v60, v61, s4
	ds_write_b16_d16_hi v89, v60 offset:544
	v_mul_f32_e32 v60, v63, v91
	v_bfe_u32 v61, v60, 16, 1
	v_add3_u32 v60, v60, v61, s4
	v_mul_f32_e32 v56, v56, v91
	ds_write_b16_d16_hi v89, v60 offset:816
	v_bfe_u32 v60, v56, 16, 1
	v_add3_u32 v56, v56, v60, s4
	ds_write_b16_d16_hi v89, v56 offset:4352
	v_mul_f32_e32 v56, v57, v91
	v_bfe_u32 v57, v56, 16, 1
	v_add3_u32 v56, v56, v57, s4
	ds_write_b16_d16_hi v89, v56 offset:4624
	v_mul_f32_e32 v56, v58, v91
	v_bfe_u32 v57, v56, 16, 1
	v_add3_u32 v56, v56, v57, s4
	ds_write_b16_d16_hi v89, v56 offset:4896
	v_mul_f32_e32 v56, v59, v91
	v_bfe_u32 v57, v56, 16, 1
	v_add3_u32 v56, v56, v57, s4
	v_mul_f32_e32 v52, v52, v91
	ds_write_b16_d16_hi v89, v56 offset:5168
	v_bfe_u32 v56, v52, 16, 1
	v_add3_u32 v52, v52, v56, s4
	ds_write_b16_d16_hi v89, v52 offset:8704
	v_mul_f32_e32 v52, v53, v91
	v_bfe_u32 v53, v52, 16, 1
	v_add3_u32 v52, v52, v53, s4
	ds_write_b16_d16_hi v89, v52 offset:8976
	v_mul_f32_e32 v52, v54, v91
	v_bfe_u32 v53, v52, 16, 1
	v_add3_u32 v52, v52, v53, s4
	ds_write_b16_d16_hi v89, v52 offset:9248
	v_mul_f32_e32 v52, v55, v91
	v_bfe_u32 v53, v52, 16, 1
	v_add3_u32 v52, v52, v53, s4
	v_mul_f32_e32 v48, v48, v91
	ds_write_b16_d16_hi v89, v52 offset:9520
	v_bfe_u32 v52, v48, 16, 1
	v_add3_u32 v48, v48, v52, s4
	ds_write_b16_d16_hi v89, v48 offset:13056
	v_mul_f32_e32 v48, v49, v91
	v_bfe_u32 v49, v48, 16, 1
	v_add3_u32 v48, v48, v49, s4
	ds_write_b16_d16_hi v89, v48 offset:13328
	v_mul_f32_e32 v48, v50, v91
	v_bfe_u32 v49, v48, 16, 1
	v_add3_u32 v48, v48, v49, s4
	ds_write_b16_d16_hi v89, v48 offset:13600
	v_mul_f32_e32 v48, v51, v91
	v_bfe_u32 v49, v48, 16, 1
	v_add3_u32 v48, v48, v49, s4
	ds_write_b16_d16_hi v89, v48 offset:13872
.LBB0_613:
	s_or_saveexec_b64 s[34:35], s[0:1]
	v_lshlrev_b32_e32 v65, 2, v64
	v_lshlrev_b32_e32 v104, 5, v64
	v_lshlrev_b32_e32 v64, 1, v65
	v_lshlrev_b32_e32 v88, 2, v65
	global_load_dwordx4 v[224:227], v88, s[62:63]
	global_load_dwordx4 v[228:231], v88, s[62:63] offset:64
	global_load_dwordx4 v[232:235], v88, s[62:63] offset:128
	global_load_dwordx4 v[236:239], v88, s[62:63] offset:192
	global_load_dwordx4 v[240:243], v88, s[62:63] offset:256
	global_load_dwordx4 v[244:247], v88, s[62:63] offset:320
	s_xor_b64 exec, exec, s[34:35]
	s_cbranch_execz .LBB0_617
	v_mul_f32_e32 v68, v57, v57
	v_pk_fma_f32 v[68:69], v[56:57], v[56:57], v[68:69] op_sel_hi:[1,1,0]
	v_mul_f32_e32 v70, v59, v59
	v_pk_fma_f32 v[68:69], v[58:59], v[58:59], v[68:69]
	v_mul_hi_i32 v65, v90, s36
	v_pk_add_f32 v[76:77], v[70:71], v[68:69] op_sel_hi:[0,1]
	v_pk_mul_f32 v[70:71], v[52:53], v[52:53]
	v_lshrrev_b32_e32 v66, 31, v65
	v_ashrrev_i32_e32 v65, 11, v65
	v_pk_mul_f32 v[68:69], v[54:55], v[54:55]
	v_fmac_f32_e32 v71, v52, v52
	v_add_u32_e32 v67, v65, v66
	s_movk_i32 s0, 0xef00
	v_add_f32_e32 v78, v68, v71
	v_mul_f32_e32 v68, v49, v49
	v_mad_i32_i24 v66, v67, s0, v90
	v_pk_fma_f32 v[68:69], v[48:49], v[48:49], v[68:69] op_sel_hi:[1,1,0]
	v_readlane_b32 s0, v252, 24
	v_pk_fma_f32 v[68:69], v[50:51], v[50:51], v[68:69]
	v_mul_f32_e32 v70, v51, v51
	v_readlane_b32 s1, v252, 25
	v_pk_add_f32 v[74:75], v[70:71], v[68:69] op_sel_hi:[0,1]
	v_mov_b32_e32 v65, v105
	v_mov_b64_e32 v[68:69], s[0:1]
	s_movk_i32 s0, 0x640
	v_mad_i64_i32 v[68:69], s[0:1], v90, s0, v[68:69]
	v_lshl_add_u64 v[68:69], v[68:69], 0, v[64:65]
	global_load_dwordx2 v[96:97], v[68:69], off offset:1536
	global_load_dwordx2 v[98:99], v[68:69], off offset:1568
	s_mov_b64 s[100:101], 0x6400
	v_lshl_add_u64 v[208:209], v[68:69], 0, s[100:101]
	global_load_dwordx2 v[130:131], v[208:209], off offset:1536
	global_load_dwordx2 v[132:133], v[208:209], off offset:1568
	v_lshl_add_u64 v[210:211], v[208:209], 0, s[100:101]
	global_load_dwordx2 v[134:135], v[210:211], off offset:1536
	global_load_dwordx2 v[136:137], v[210:211], off offset:1568
	v_lshl_add_u64 v[208:209], v[210:211], 0, s[100:101]
	global_load_dwordx2 v[138:139], v[208:209], off offset:1536
	global_load_dwordx2 v[140:141], v[208:209], off offset:1568
	v_mul_f32_e32 v82, v63, v63
	s_movk_i32 s4, 0xc0
	s_waitcnt vmcnt(1)
	v_and_b32_e32 v71, 0xffff0000, v97
	s_waitcnt vmcnt(0)
; __device__ __forceinline__ float bf2f(bf16_t h) { return __uint_as_float(((unsigned)h) << 16); }
; __device__ __forceinline__ unsigned pack2bf(float a, float b) { const f32x2 v = {a, b}; return __builtin_bit_cast(unsigned, __builtin_convertvector(v, bf2_t)); }
;     __device__ __forceinline__ void operator()(const f32x4 (&acc)[4][4], int m0, int n0, int wr, int wc, int fr, int fq, char* smem) const {
;     ...
;                 const int i0 = fq * 4;
;                 const u16x4 r1 = *(const u16x4*)(zb + (size_t)row * 800 + 768 + i0), r2 = *(const u16x4*)(zb + (size_t)row * 800 + 784 + i0);
;                 float x1[4], x2[4]; float sr = 0.f;
; #pragma unroll
;                 for (int j = 0; j < 4; ++j) { x1[j] = bf2f(r1[j]); x2[j] = bf2f(r2[j]); sr += x1[j] * x1[j] + x2[j] * x2[j]; }
;                 ss = ss * rstd * rstd + sr;
;                 ss += __shfl_xor(ss, 16); ss += __shfl_xor(ss, 32);
;                 const float sc = rsqrtf(ss * (1.f / 96.f) + 1e-6f);
;                 bf16_t* krow = Kb + ((size_t)(b * 8 + h) * TT + t) * 96;
;                 const float s1 = rstd * sc;
; #pragma unroll
;                 for (int n = 0; n < 4; ++n) {
;                     const int c = n * 16 + fq * 4;
;                     const f32x4 g = *(const f32x4*)(gk + c);
;                     const f32x4 v = acc[m][n];
;                     uint2 w; w.x = pack2bf(v[0] * s1 * g[0], v[1] * s1 * g[1]); w.y = pack2bf(v[2] * s1 * g[2], v[3] * s1 * g[3]);
;                     *(uint2*)(krow + c) = w;
;                 }
;                 const f32x4 g1 = *(const f32x4*)(gk + 64 + i0), g2 = *(const f32x4*)(gk + 80 + i0);
; #pragma unroll
;                 for (int j = 0; j < 4; ++j) { x1[j] *= sc * g1[j]; x2[j] *= sc * g2[j]; }
;                 if (t >= CTX) {
;                     const float* rp = rope + ((size_t)(t - CTX) * 16 + i0) * 2;
; #pragma unroll
;                     for (int j = 0; j < 4; ++j) { const float c = rp[2 * j], s = rp[2 * j + 1]; const float a = x1[j] * c - x2[j] * s, bb = x1[j] * s + x2[j] * c; x1[j] = a; x2[j] = bb; }
;                 }
	v_and_b32_e32 v73, 0xffff0000, v99
	v_lshlrev_b32_e32 v72, 16, v99
	v_lshlrev_b32_e32 v70, 16, v97
	v_pk_mul_f32 v[68:69], v[72:73], v[72:73]
	v_and_b32_e32 v97, 0xffff0000, v96
	v_pk_fma_f32 v[80:81], v[70:71], v[70:71], v[68:69]
	v_mul_f32_e32 v68, v61, v61
	v_pk_fma_f32 v[68:69], v[60:61], v[60:61], v[68:69] op_sel_hi:[1,1,0]
	v_mov_b32_e32 v75, v80
	v_pk_fma_f32 v[68:69], v[62:63], v[62:63], v[68:69]
	s_nop 0
	v_pk_add_f32 v[82:83], v[82:83], v[68:69] op_sel_hi:[0,1]
	v_and_b32_e32 v69, 64, v195
	v_xor_b32_e32 v68, 16, v195
	v_add_u32_e32 v69, 64, v69
	v_cmp_lt_i32_e64 s[0:1], v68, v69
	s_nop 1
	v_cndmask_b32_e64 v68, v195, v68, s[0:1]
	v_lshlrev_b32_e32 v111, 2, v68
	v_xor_b32_e32 v68, 32, v195
	v_cmp_lt_i32_e64 s[0:1], v68, v69
	s_nop 1
	v_cndmask_b32_e64 v68, v195, v68, s[0:1]
	v_lshlrev_b32_e32 v116, 2, v68
	v_lshl_add_u32 v68, v67, 3, s47
	v_ashrrev_i32_e32 v67, 31, v66
	s_movk_i32 s0, 0x1100
	v_mad_i64_i32 v[68:69], s[0:1], v68, s0, v[66:67]
	v_readlane_b32 s0, v251, 58
	v_readlane_b32 s1, v251, 59
	s_nop 1
	v_mov_b64_e32 v[92:93], s[0:1]
	v_mad_u64_u32 v[100:101], s[0:1], v68, s4, v[92:93]
	v_mov_b64_e32 v[92:93], v[224:225]
	v_mov_b64_e32 v[94:95], v[226:227]
	v_mad_i32_i24 v101, v69, s4, v101
	v_lshl_add_u64 v[68:69], v[100:101], 0, v[64:65]
	v_and_b32_e32 v101, 0xffff0000, v98
	v_lshlrev_b32_e32 v100, 16, v96
	v_lshlrev_b32_e32 v96, 16, v98
	v_pk_mul_f32 v[98:99], v[96:97], v[96:97]
	v_pk_mul_f32 v[102:103], v[100:101], v[100:101]
	v_pk_mov_b32 v[114:115], v[54:55], v[100:101] op_sel:[1,0]
	v_mov_b32_e32 v79, v98
	v_mov_b32_e32 v83, v99
	v_mov_b32_e32 v77, v103
	v_pk_fma_f32 v[78:79], v[114:115], v[114:115], v[78:79]
	v_pk_add_f32 v[76:77], v[82:83], v[76:77]
	s_mov_b32 s0, 0x800000
	v_pk_add_f32 v[76:77], v[78:79], v[76:77]
	s_nop 0
	v_pk_add_f32 v[74:75], v[74:75], v[76:77]
	s_nop 0
	v_mul_f32_e32 v65, v74, v91
	v_add_f32_e32 v67, v75, v81
	v_fmac_f32_e32 v67, v91, v65
	ds_bpermute_b32 v65, v111, v67
	s_waitcnt lgkmcnt(0)
	v_add_f32_e32 v65, v67, v65
	ds_bpermute_b32 v67, v116, v65
	s_waitcnt lgkmcnt(0)
	v_add_f32_e32 v65, v65, v67
	v_fmamk_f32 v65, v65, 0x3c2aaaab, v108
	v_cmp_gt_f32_e64 s[0:1], s0, v65
	v_mul_f32_e32 v67, 0x4b800000, v65
	s_nop 0
	v_cndmask_b32_e64 v65, v65, v67, s[0:1]
	v_rsq_f32_e32 v65, v65
	s_nop 0
	v_mul_f32_e32 v67, 0x45800000, v65
	v_cndmask_b32_e64 v74, v65, v67, s[0:1]
	v_mul_f32_e32 v76, v91, v74
	v_pk_mul_f32 v[60:61], v[60:61], v[76:77] op_sel_hi:[1,0]
	v_pk_mul_f32 v[62:63], v[62:63], v[76:77] op_sel_hi:[1,0]
	v_pk_mul_f32 v[56:57], v[56:57], v[76:77] op_sel_hi:[1,0]
	v_pk_mul_f32 v[58:59], v[58:59], v[76:77] op_sel_hi:[1,0]
	v_pk_mul_f32 v[52:53], v[52:53], v[76:77] op_sel_hi:[1,0]
	v_pk_mul_f32 v[54:55], v[54:55], v[76:77] op_sel_hi:[1,0]
	v_pk_mul_f32 v[48:49], v[48:49], v[76:77] op_sel_hi:[1,0]
	v_pk_mul_f32 v[50:51], v[50:51], v[76:77] op_sel_hi:[1,0]
	v_cmp_lt_i32_e64 s[0:1], s2, v66
	v_pk_mul_f32 v[60:61], v[92:93], v[60:61]
	v_pk_mul_f32 v[62:63], v[94:95], v[62:63]
	v_cvt_pk_bf16_f32 v60, v60, v61
	v_cvt_pk_bf16_f32 v61, v62, v63
	global_store_dwordx2 v[68:69], v[60:61], off
	v_mov_b64_e32 v[60:61], v[228:229]
	v_mov_b64_e32 v[62:63], v[230:231]
	v_pk_mul_f32 v[56:57], v[60:61], v[56:57]
	v_pk_mul_f32 v[58:59], v[62:63], v[58:59]
	v_cvt_pk_bf16_f32 v56, v56, v57
	v_cvt_pk_bf16_f32 v57, v58, v59
	global_store_dwordx2 v[68:69], v[56:57], off offset:32
	v_mov_b64_e32 v[56:57], v[232:233]
	v_mov_b64_e32 v[58:59], v[234:235]
	v_pk_mul_f32 v[52:53], v[56:57], v[52:53]
	v_pk_mul_f32 v[54:55], v[58:59], v[54:55]
	v_cvt_pk_bf16_f32 v52, v52, v53
	v_cvt_pk_bf16_f32 v53, v54, v55
	global_store_dwordx2 v[68:69], v[52:53], off offset:64
	v_mov_b64_e32 v[52:53], v[236:237]
	v_mov_b64_e32 v[54:55], v[238:239]
	v_pk_mul_f32 v[48:49], v[52:53], v[48:49]
	v_pk_mul_f32 v[50:51], v[54:55], v[50:51]
	v_cvt_pk_bf16_f32 v48, v48, v49
	v_cvt_pk_bf16_f32 v49, v50, v51
	global_store_dwordx2 v[68:69], v[48:49], off offset:96
	v_mov_b64_e32 v[54:55], v[240:241]
	v_mov_b64_e32 v[56:57], v[242:243]
	v_mov_b64_e32 v[58:59], v[244:245]
	v_mov_b64_e32 v[60:61], v[246:247]
	v_mov_b32_e32 v48, v54
	v_mov_b32_e32 v49, v59
	v_mov_b32_e32 v59, v55
	v_mul_f32_e32 v52, v56, v74
	v_mov_b32_e32 v56, v61
	v_pk_mul_f32 v[48:49], v[48:49], v[74:75] op_sel_hi:[1,0]
	v_pk_mul_f32 v[50:51], v[58:59], v[74:75] op_sel_hi:[1,0]
	v_mul_f32_e32 v52, v52, v70
	v_mul_f32_e32 v53, v60, v74
	v_pk_mul_f32 v[56:57], v[56:57], v[74:75] op_sel_hi:[1,0]
	v_mov_b32_e32 v70, v73
	v_pk_mul_f32 v[48:49], v[48:49], v[100:101]
	v_pk_mul_f32 v[50:51], v[50:51], v[96:97]
	v_mul_f32_e32 v54, v53, v72
	v_pk_mul_f32 v[56:57], v[56:57], v[70:71]
	s_and_saveexec_b64 s[42:43], s[0:1]
	s_cbranch_execz .LBB0_616
	v_add_u32_e32 v58, 0xffffff00, v66
	v_mov_b32_e32 v59, v105
	v_readlane_b32 s0, v252, 22
	v_lshlrev_b64 v[58:59], 7, v[58:59]
	v_readlane_b32 s1, v252, 23
	v_mov_b32_e32 v74, v50
	v_mov_b32_e32 v75, v49
	v_lshl_add_u64 v[58:59], s[0:1], 0, v[58:59]
	v_lshl_add_u64 v[62:63], v[58:59], 0, v[104:105]
	global_load_dwordx4 v[58:61], v[62:63], off offset:16
	s_mov_b64 s[100:101], 0x1000
	v_lshl_add_u64 v[210:211], v[62:63], 0, s[100:101]
	global_load_dwordx4 v[142:145], v[62:63], off offset:2064
	global_load_dwordx4 v[146:149], v[62:63], off offset:2048
	global_load_dwordx4 v[150:153], v[210:211], off offset:16
	global_load_dwordx4 v[154:157], v[210:211], off
	global_load_dwordx4 v[158:161], v[210:211], off offset:2064
	global_load_dwordx4 v[162:165], v[210:211], off offset:2048
	global_load_dwordx4 v[70:73], v[62:63], off
	s_waitcnt vmcnt(1)
	v_mul_f32_e32 v78, v52, v59
	s_waitcnt vmcnt(0)
	v_mov_b32_e32 v62, v71
	v_mov_b32_e32 v63, v72
	v_mov_b32_e32 v76, v71
	v_mov_b32_e32 v77, v73
	v_mov_b32_e32 v71, v72
	v_mul_f32_e32 v72, v52, v58
	v_pk_mul_f32 v[52:53], v[56:57], v[60:61] op_sel:[1,0] op_sel_hi:[0,1]
	v_mov_b32_e32 v66, v70
	v_mov_b32_e32 v67, v73
	v_pk_mul_f32 v[74:75], v[74:75], v[76:77]
	v_mov_b32_e32 v73, v52
	v_mov_b32_e32 v77, v53
	v_pk_mul_f32 v[52:53], v[56:57], v[60:61]
	v_pk_mul_f32 v[66:67], v[50:51], v[66:67]
	v_mov_b32_e32 v50, v48
	v_mul_f32_e32 v76, v54, v59
	v_mul_f32_e32 v54, v54, v58
	v_mov_b32_e32 v55, v52
	v_mov_b32_e32 v79, v53
	v_pk_fma_f32 v[58:59], v[50:51], v[70:71], v[74:75] neg_lo:[0,0,1] neg_hi:[0,0,1]
	v_pk_add_f32 v[52:53], v[72:73], v[76:77] neg_lo:[0,1] neg_hi:[0,1]
	v_pk_fma_f32 v[50:51], v[48:49], v[62:63], v[66:67]
	v_pk_add_f32 v[54:55], v[54:55], v[78:79]
	v_mov_b32_e32 v49, v51
	v_mov_b32_e32 v56, v55
	v_mov_b32_e32 v48, v58
	v_mov_b32_e32 v51, v59
	v_mov_b32_e32 v57, v53

;     __device__ __forceinline__ void operator()(const f32x4 (&acc)[4][4], int m0, int n0, int wr, int wc, int fr, int fq, char* smem) const {
;     ...
;             const int row = m0 + wr * 64 + m * 16 + fr;
;             const int b = row / TT, t = row - b * TT;
;             const float skv = stats[(size_t)row * 12 + 8] + stats[(size_t)row * 12 + 9] + stats[(size_t)row * 12 + 10] + stats[(size_t)row * 12 + 11];
;             const float rstd = rsqrtf(skv * (1.f / 256.f) + 1e-6f);
;             if (wc == 0) {
;                 float ss = 0.f;
; #pragma unroll
;                 for (int n = 0; n < 4; ++n) { const f32x4 v = acc[m][n]; ss += v[0] * v[0] + v[1] * v[1] + v[2] * v[2] + v[3] * v[3]; }
;                 const int i0 = fq * 4;
;                 const u16x4 r1 = *(const u16x4*)(zb + (size_t)row * 800 + 768 + i0), r2 = *(const u16x4*)(zb + (size_t)row * 800 + 784 + i0);
;                 float x1[4], x2[4]; float sr = 0.f;
; #pragma unroll
;                 for (int j = 0; j < 4; ++j) { x1[j] = bf2f(r1[j]); x2[j] = bf2f(r2[j]); sr += x1[j] * x1[j] + x2[j] * x2[j]; }
;                 ss = ss * rstd * rstd + sr;
;                 ss += __shfl_xor(ss, 16); ss += __shfl_xor(ss, 32);
;                 const float sc = rsqrtf(ss * (1.f / 96.f) + 1e-6f);
;                 bf16_t* krow = Kb + ((size_t)(b * 8 + h) * TT + t) * 96;
;                 const float s1 = rstd * sc;
; #pragma unroll
;                 for (int n = 0; n < 4; ++n) {
;                     const int c = n * 16 + fq * 4;
;                     const f32x4 g = *(const f32x4*)(gk + c);
;                     const f32x4 v = acc[m][n];
;                     uint2 w; w.x = pack2bf(v[0] * s1 * g[0], v[1] * s1 * g[1]); w.y = pack2bf(v[2] * s1 * g[2], v[3] * s1 * g[3]);
;                     *(uint2*)(krow + c) = w;
;                 }
;                 const f32x4 g1 = *(const f32x4*)(gk + 64 + i0), g2 = *(const f32x4*)(gk + 80 + i0);
; #pragma unroll
;                 for (int j = 0; j < 4; ++j) { x1[j] *= sc * g1[j]; x2[j] *= sc * g2[j]; }
;                 if (t >= CTX) {
;                     const float* rp = rope + ((size_t)(t - CTX) * 16 + i0) * 2;
; #pragma unroll
;                     for (int j = 0; j < 4; ++j) { const float c = rp[2 * j], s = rp[2 * j + 1]; const float a = x1[j] * c - x2[j] * s, bb = x1[j] * s + x2[j] * c; x1[j] = a; x2[j] = bb; }
;                 }
.LBB0_617:
	s_or_b64 exec, exec, s[34:35]
	v_readlane_b32 s0, v252, 20
	v_or_b32_e32 v49, 16, v90
	v_readlane_b32 s1, v252, 21
	s_nop 1
	v_mad_i64_i32 v[50:51], s[0:1], v49, 48, s[0:1]
	v_mov_b64_e32 v[50:51], v[118:119]
	v_mov_b64_e32 v[52:53], v[120:121]
	s_mov_b32 s0, 0x800000
	v_add_f32_e32 v48, v50, v51
	v_add_f32_e32 v48, v48, v52
	v_add_f32_e32 v48, v48, v53
	v_fmamk_f32 v48, v48, 0x3b800000, v108
	v_mul_f32_e32 v50, 0x4b800000, v48
	v_cmp_gt_f32_e64 s[0:1], s0, v48
	s_nop 1
	v_cndmask_b32_e64 v48, v48, v50, s[0:1]
	v_rsq_f32_e32 v48, v48
	s_nop 0
	v_mul_f32_e32 v50, 0x45800000, v48
	v_cndmask_b32_e64 v68, v48, v50, s[0:1]
	s_and_saveexec_b64 s[0:1], vcc
	s_xor_b64 s[0:1], exec, s[0:1]
	s_cbranch_execz .LBB0_619
	v_mul_f32_e32 v44, v44, v68
	v_bfe_u32 v48, v44, 16, 1
	s_movk_i32 s4, 0x7fff
	v_add3_u32 v44, v44, v48, s4
	ds_write_b16_d16_hi v89, v44 offset:32
	v_mul_f32_e32 v44, v45, v68
	v_bfe_u32 v45, v44, 16, 1
	v_add3_u32 v44, v44, v45, s4
	ds_write_b16_d16_hi v89, v44 offset:304
	v_mul_f32_e32 v44, v46, v68
	v_bfe_u32 v45, v44, 16, 1
	v_add3_u32 v44, v44, v45, s4
	ds_write_b16_d16_hi v89, v44 offset:576
	v_mul_f32_e32 v44, v47, v68
	v_bfe_u32 v45, v44, 16, 1
	v_add3_u32 v44, v44, v45, s4
	v_mul_f32_e32 v40, v40, v68
	ds_write_b16_d16_hi v89, v44 offset:848
	v_bfe_u32 v44, v40, 16, 1
	v_add3_u32 v40, v40, v44, s4
	ds_write_b16_d16_hi v89, v40 offset:4384
	v_mul_f32_e32 v40, v41, v68
	v_bfe_u32 v41, v40, 16, 1
	v_add3_u32 v40, v40, v41, s4
	ds_write_b16_d16_hi v89, v40 offset:4656
	v_mul_f32_e32 v40, v42, v68
	v_bfe_u32 v41, v40, 16, 1
	v_add3_u32 v40, v40, v41, s4
	ds_write_b16_d16_hi v89, v40 offset:4928
	v_mul_f32_e32 v40, v43, v68
	v_bfe_u32 v41, v40, 16, 1
	v_add3_u32 v40, v40, v41, s4
	v_mul_f32_e32 v36, v36, v68
	ds_write_b16_d16_hi v89, v40 offset:5200
	v_bfe_u32 v40, v36, 16, 1
	v_add3_u32 v36, v36, v40, s4
	ds_write_b16_d16_hi v89, v36 offset:8736
	v_mul_f32_e32 v36, v37, v68
	v_bfe_u32 v37, v36, 16, 1
	v_add3_u32 v36, v36, v37, s4
	ds_write_b16_d16_hi v89, v36 offset:9008
	v_mul_f32_e32 v36, v38, v68
	v_bfe_u32 v37, v36, 16, 1
	v_add3_u32 v36, v36, v37, s4
	ds_write_b16_d16_hi v89, v36 offset:9280
	v_mul_f32_e32 v36, v39, v68
	v_bfe_u32 v37, v36, 16, 1
	v_add3_u32 v36, v36, v37, s4
	v_mul_f32_e32 v32, v32, v68
	ds_write_b16_d16_hi v89, v36 offset:9552
	v_bfe_u32 v36, v32, 16, 1
	v_add3_u32 v32, v32, v36, s4
	ds_write_b16_d16_hi v89, v32 offset:13088
	v_mul_f32_e32 v32, v33, v68
	v_bfe_u32 v33, v32, 16, 1
	v_add3_u32 v32, v32, v33, s4
	ds_write_b16_d16_hi v89, v32 offset:13360
	v_mul_f32_e32 v32, v34, v68
	v_bfe_u32 v33, v32, 16, 1
	v_add3_u32 v32, v32, v33, s4
	ds_write_b16_d16_hi v89, v32 offset:13632
	v_mul_f32_e32 v32, v35, v68
	v_bfe_u32 v33, v32, 16, 1
	v_add3_u32 v32, v32, v33, s4
	ds_write_b16_d16_hi v89, v32 offset:13904
.LBB0_619:
	s_andn2_saveexec_b64 s[34:35], s[0:1]
	s_cbranch_execz .LBB0_623
	v_mul_hi_i32 v48, v49, s36
	v_lshrrev_b32_e32 v50, 31, v48
	v_ashrrev_i32_e32 v48, 11, v48
	v_add_u32_e32 v61, v48, v50
	v_mul_f32_e32 v50, v41, v41
	v_pk_fma_f32 v[50:51], v[40:41], v[40:41], v[50:51] op_sel_hi:[1,1,0]
	v_mul_f32_e32 v52, v43, v43
	v_pk_fma_f32 v[50:51], v[42:43], v[42:43], v[50:51]
	s_movk_i32 s0, 0xef00
	v_pk_add_f32 v[58:59], v[52:53], v[50:51] op_sel_hi:[0,1]
	v_pk_mul_f32 v[52:53], v[36:37], v[36:37]
	v_pk_mul_f32 v[50:51], v[38:39], v[38:39]
	v_fmac_f32_e32 v53, v36, v36
	v_add_f32_e32 v60, v50, v53
	v_mul_f32_e32 v50, v33, v33
	v_mad_i32_i24 v48, v61, s0, v49
	v_pk_fma_f32 v[50:51], v[32:33], v[32:33], v[50:51] op_sel_hi:[1,1,0]
	v_readlane_b32 s0, v252, 24
	v_pk_fma_f32 v[50:51], v[34:35], v[34:35], v[50:51]
	v_mul_f32_e32 v52, v35, v35
	v_readlane_b32 s1, v252, 25
	v_pk_add_f32 v[56:57], v[52:53], v[50:51] op_sel_hi:[0,1]
	v_mov_b32_e32 v65, v105
	v_mov_b64_e32 v[50:51], s[0:1]
	s_movk_i32 s0, 0x640
	v_mad_i64_i32 v[50:51], s[0:1], v49, s0, v[50:51]
	v_lshl_add_u64 v[50:51], v[50:51], 0, v[64:65]
	v_mov_b64_e32 v[74:75], v[130:131]
	v_mov_b64_e32 v[76:77], v[132:133]
	v_mul_f32_e32 v66, v47, v47
	v_xor_b32_e32 v49, 16, v195
	s_movk_i32 s4, 0xc0
	v_and_b32_e32 v53, 0xffff0000, v75
	v_and_b32_e32 v55, 0xffff0000, v77
	v_lshlrev_b32_e32 v54, 16, v77
	v_lshlrev_b32_e32 v52, 16, v75
	v_pk_mul_f32 v[50:51], v[54:55], v[54:55]
	v_and_b32_e32 v75, 0xffff0000, v74
	v_pk_fma_f32 v[62:63], v[52:53], v[52:53], v[50:51]
	v_mul_f32_e32 v50, v45, v45
	v_pk_fma_f32 v[50:51], v[44:45], v[44:45], v[50:51] op_sel_hi:[1,1,0]
	v_mov_b32_e32 v57, v62
	v_pk_fma_f32 v[50:51], v[46:47], v[46:47], v[50:51]
	s_nop 0
	v_pk_add_f32 v[66:67], v[66:67], v[50:51] op_sel_hi:[0,1]
	v_and_b32_e32 v50, 64, v195
	v_add_u32_e32 v50, 64, v50
	v_cmp_lt_i32_e64 s[0:1], v49, v50
	s_nop 1
	v_cndmask_b32_e64 v49, v195, v49, s[0:1]
	v_lshlrev_b32_e32 v69, 2, v49
	v_xor_b32_e32 v49, 32, v195
	v_cmp_lt_i32_e64 s[0:1], v49, v50
	v_lshl_add_u32 v50, v61, 3, s47
	s_nop 0
	v_cndmask_b32_e64 v49, v195, v49, s[0:1]
	v_lshlrev_b32_e32 v91, 2, v49
	v_ashrrev_i32_e32 v49, 31, v48
	s_movk_i32 s0, 0x1100
	v_mad_i64_i32 v[50:51], s[0:1], v50, s0, v[48:49]
	v_readlane_b32 s0, v251, 58
	v_readlane_b32 s1, v251, 59
	s_nop 1
	v_mov_b64_e32 v[70:71], s[0:1]
	v_mad_u64_u32 v[78:79], s[0:1], v50, s4, v[70:71]
	v_mov_b64_e32 v[70:71], v[224:225]
	v_mov_b64_e32 v[72:73], v[226:227]
	v_mad_i32_i24 v79, v51, s4, v79
	v_lshl_add_u64 v[50:51], v[78:79], 0, v[64:65]
	v_and_b32_e32 v79, 0xffff0000, v76
	v_lshlrev_b32_e32 v78, 16, v74
	v_lshlrev_b32_e32 v74, 16, v76
	v_pk_mul_f32 v[76:77], v[74:75], v[74:75]
	v_pk_mul_f32 v[80:81], v[78:79], v[78:79]
	v_pk_mov_b32 v[82:83], v[38:39], v[78:79] op_sel:[1,0]
	v_mov_b32_e32 v61, v76
	v_mov_b32_e32 v67, v77
	v_mov_b32_e32 v59, v81
	v_pk_fma_f32 v[60:61], v[82:83], v[82:83], v[60:61]
	v_pk_add_f32 v[58:59], v[66:67], v[58:59]
	s_mov_b32 s0, 0x800000
	v_pk_add_f32 v[58:59], v[60:61], v[58:59]
	s_nop 0
	v_pk_add_f32 v[56:57], v[56:57], v[58:59]
	s_nop 0
	v_mul_f32_e32 v49, v56, v68
	v_add_f32_e32 v56, v57, v63
	v_fmac_f32_e32 v56, v68, v49
	ds_bpermute_b32 v49, v69, v56
	s_waitcnt lgkmcnt(0)
; __device__ __forceinline__ unsigned pack2bf(float a, float b) { const f32x2 v = {a, b}; return __builtin_bit_cast(unsigned, __builtin_convertvector(v, bf2_t)); }
;     __device__ __forceinline__ void operator()(const f32x4 (&acc)[4][4], int m0, int n0, int wr, int wc, int fr, int fq, char* smem) const {
;     ...
;                 ss = ss * rstd * rstd + sr;
;                 ss += __shfl_xor(ss, 16); ss += __shfl_xor(ss, 32);
;                 const float sc = rsqrtf(ss * (1.f / 96.f) + 1e-6f);
;                 bf16_t* krow = Kb + ((size_t)(b * 8 + h) * TT + t) * 96;
;                 const float s1 = rstd * sc;
; #pragma unroll
;                 for (int n = 0; n < 4; ++n) {
;                     const int c = n * 16 + fq * 4;
;                     const f32x4 g = *(const f32x4*)(gk + c);
;                     const f32x4 v = acc[m][n];
;                     uint2 w; w.x = pack2bf(v[0] * s1 * g[0], v[1] * s1 * g[1]); w.y = pack2bf(v[2] * s1 * g[2], v[3] * s1 * g[3]);
;                     *(uint2*)(krow + c) = w;
;                 }
;                 const f32x4 g1 = *(const f32x4*)(gk + 64 + i0), g2 = *(const f32x4*)(gk + 80 + i0);
; #pragma unroll
;                 for (int j = 0; j < 4; ++j) { x1[j] *= sc * g1[j]; x2[j] *= sc * g2[j]; }
;                 if (t >= CTX) {
;                     const float* rp = rope + ((size_t)(t - CTX) * 16 + i0) * 2;
; #pragma unroll
;                     for (int j = 0; j < 4; ++j) { const float c = rp[2 * j], s = rp[2 * j + 1]; const float a = x1[j] * c - x2[j] * s, bb = x1[j] * s + x2[j] * c; x1[j] = a; x2[j] = bb; }
;                 }
;                 uint2 w; w.x = pack2bf(x1[0], x1[1]); w.y = pack2bf(x1[2], x1[3]); *(uint2*)(krow + 64 + i0) = w;
;                 w.x = pack2bf(x2[0], x2[1]); w.y = pack2bf(x2[2], x2[3]); *(uint2*)(krow + 80 + i0) = w;
	v_add_f32_e32 v49, v56, v49
	ds_bpermute_b32 v56, v91, v49
	s_waitcnt lgkmcnt(0)
	v_add_f32_e32 v49, v49, v56
	v_fmamk_f32 v49, v49, 0x3c2aaaab, v108
	v_cmp_gt_f32_e64 s[0:1], s0, v49
	v_mul_f32_e32 v56, 0x4b800000, v49
	s_nop 0
	v_cndmask_b32_e64 v49, v49, v56, s[0:1]
	v_rsq_f32_e32 v49, v49
	s_nop 0
	v_mul_f32_e32 v56, 0x45800000, v49
	v_cndmask_b32_e64 v56, v49, v56, s[0:1]
	v_mul_f32_e32 v58, v68, v56
	v_pk_mul_f32 v[44:45], v[44:45], v[58:59] op_sel_hi:[1,0]
	v_pk_mul_f32 v[46:47], v[46:47], v[58:59] op_sel_hi:[1,0]
	v_pk_mul_f32 v[40:41], v[40:41], v[58:59] op_sel_hi:[1,0]
	v_pk_mul_f32 v[42:43], v[42:43], v[58:59] op_sel_hi:[1,0]
	v_pk_mul_f32 v[36:37], v[36:37], v[58:59] op_sel_hi:[1,0]
	v_pk_mul_f32 v[38:39], v[38:39], v[58:59] op_sel_hi:[1,0]
	v_pk_mul_f32 v[32:33], v[32:33], v[58:59] op_sel_hi:[1,0]
	v_pk_mul_f32 v[34:35], v[34:35], v[58:59] op_sel_hi:[1,0]
	v_cmp_lt_i32_e64 s[0:1], s2, v48
	v_pk_mul_f32 v[44:45], v[70:71], v[44:45]
	v_pk_mul_f32 v[46:47], v[72:73], v[46:47]
	v_cvt_pk_bf16_f32 v44, v44, v45
	v_cvt_pk_bf16_f32 v45, v46, v47
	global_store_dwordx2 v[50:51], v[44:45], off
	v_mov_b64_e32 v[44:45], v[228:229]
	v_mov_b64_e32 v[46:47], v[230:231]
	v_pk_mul_f32 v[40:41], v[44:45], v[40:41]
	v_pk_mul_f32 v[42:43], v[46:47], v[42:43]
	v_cvt_pk_bf16_f32 v40, v40, v41
	v_cvt_pk_bf16_f32 v41, v42, v43
	global_store_dwordx2 v[50:51], v[40:41], off offset:32
	v_mov_b64_e32 v[40:41], v[232:233]
	v_mov_b64_e32 v[42:43], v[234:235]
	v_pk_mul_f32 v[36:37], v[40:41], v[36:37]
	v_pk_mul_f32 v[38:39], v[42:43], v[38:39]
	v_cvt_pk_bf16_f32 v36, v36, v37
	v_cvt_pk_bf16_f32 v37, v38, v39
	global_store_dwordx2 v[50:51], v[36:37], off offset:64
	v_mov_b64_e32 v[36:37], v[236:237]
	v_mov_b64_e32 v[38:39], v[238:239]
	v_pk_mul_f32 v[32:33], v[36:37], v[32:33]
	v_pk_mul_f32 v[34:35], v[38:39], v[34:35]
	v_cvt_pk_bf16_f32 v32, v32, v33
	v_cvt_pk_bf16_f32 v33, v34, v35
	global_store_dwordx2 v[50:51], v[32:33], off offset:96
	v_mov_b64_e32 v[38:39], v[240:241]
	v_mov_b64_e32 v[40:41], v[242:243]
	v_mov_b64_e32 v[42:43], v[244:245]
	v_mov_b64_e32 v[44:45], v[246:247]
	v_mov_b32_e32 v32, v38
	v_mov_b32_e32 v33, v43
	v_mov_b32_e32 v43, v39
	v_mul_f32_e32 v36, v40, v56
	v_mov_b32_e32 v40, v45
	v_pk_mul_f32 v[32:33], v[32:33], v[56:57] op_sel_hi:[1,0]
	v_pk_mul_f32 v[34:35], v[42:43], v[56:57] op_sel_hi:[1,0]
	v_mul_f32_e32 v36, v36, v52
	v_mul_f32_e32 v37, v44, v56
	v_pk_mul_f32 v[40:41], v[40:41], v[56:57] op_sel_hi:[1,0]
	v_mov_b32_e32 v52, v55
	v_pk_mul_f32 v[32:33], v[32:33], v[78:79]
	v_pk_mul_f32 v[34:35], v[34:35], v[74:75]
	v_mul_f32_e32 v38, v37, v54
	v_pk_mul_f32 v[40:41], v[40:41], v[52:53]
	s_and_saveexec_b64 s[42:43], s[0:1]
	s_cbranch_execz .LBB0_622
	v_add_u32_e32 v42, 0xffffff00, v48
	v_mov_b32_e32 v43, v105
	v_readlane_b32 s0, v252, 22
	v_lshlrev_b64 v[42:43], 7, v[42:43]
	v_readlane_b32 s1, v252, 23
	v_mov_b32_e32 v56, v34
	v_mov_b32_e32 v57, v33
	v_lshl_add_u64 v[42:43], s[0:1], 0, v[42:43]
	v_lshl_add_u64 v[46:47], v[42:43], 0, v[104:105]
	v_mov_b64_e32 v[42:43], v[142:143]
	v_mov_b64_e32 v[44:45], v[144:145]
	s_nop 0
	v_mov_b64_e32 v[46:47], v[146:147]
	v_mov_b64_e32 v[48:49], v[148:149]
	v_mul_f32_e32 v60, v36, v43
	v_mov_b32_e32 v52, v47
	v_mov_b32_e32 v53, v48
	v_mov_b32_e32 v58, v47
	v_mov_b32_e32 v59, v49
	v_mov_b32_e32 v47, v48
	v_mul_f32_e32 v48, v36, v42
	v_pk_mul_f32 v[36:37], v[40:41], v[44:45] op_sel:[1,0] op_sel_hi:[0,1]
	v_mov_b32_e32 v54, v46
	v_mov_b32_e32 v55, v49
	v_pk_mul_f32 v[56:57], v[56:57], v[58:59]
	v_mov_b32_e32 v49, v36
	v_mov_b32_e32 v59, v37
	v_pk_mul_f32 v[36:37], v[40:41], v[44:45]
	v_pk_mul_f32 v[54:55], v[34:35], v[54:55]
	v_mov_b32_e32 v34, v32
	v_mul_f32_e32 v58, v38, v43
	v_mul_f32_e32 v38, v38, v42
	v_mov_b32_e32 v39, v36
	v_mov_b32_e32 v61, v37
	v_pk_fma_f32 v[42:43], v[34:35], v[46:47], v[56:57] neg_lo:[0,0,1] neg_hi:[0,0,1]
	v_pk_add_f32 v[36:37], v[48:49], v[58:59] neg_lo:[0,1] neg_hi:[0,1]
	v_pk_fma_f32 v[34:35], v[32:33], v[52:53], v[54:55]
	v_pk_add_f32 v[38:39], v[38:39], v[60:61]
	v_mov_b32_e32 v33, v35
	v_mov_b32_e32 v40, v39
	v_mov_b32_e32 v32, v42
	v_mov_b32_e32 v35, v43
	v_mov_b32_e32 v41, v37

;     __device__ __forceinline__ void operator()(const f32x4 (&acc)[4][4], int m0, int n0, int wr, int wc, int fr, int fq, char* smem) const {
;     ...
;             const int row = m0 + wr * 64 + m * 16 + fr;
;             const int b = row / TT, t = row - b * TT;
;             const float skv = stats[(size_t)row * 12 + 8] + stats[(size_t)row * 12 + 9] + stats[(size_t)row * 12 + 10] + stats[(size_t)row * 12 + 11];
;             const float rstd = rsqrtf(skv * (1.f / 256.f) + 1e-6f);
;             if (wc == 0) {
;                 float ss = 0.f;
; #pragma unroll
;                 for (int n = 0; n < 4; ++n) { const f32x4 v = acc[m][n]; ss += v[0] * v[0] + v[1] * v[1] + v[2] * v[2] + v[3] * v[3]; }
;                 const int i0 = fq * 4;
;                 const u16x4 r1 = *(const u16x4*)(zb + (size_t)row * 800 + 768 + i0), r2 = *(const u16x4*)(zb + (size_t)row * 800 + 784 + i0);
;                 float x1[4], x2[4]; float sr = 0.f;
; #pragma unroll
;                 for (int j = 0; j < 4; ++j) { x1[j] = bf2f(r1[j]); x2[j] = bf2f(r2[j]); sr += x1[j] * x1[j] + x2[j] * x2[j]; }
;                 ss = ss * rstd * rstd + sr;
;                 ss += __shfl_xor(ss, 16); ss += __shfl_xor(ss, 32);
;                 const float sc = rsqrtf(ss * (1.f / 96.f) + 1e-6f);
;                 bf16_t* krow = Kb + ((size_t)(b * 8 + h) * TT + t) * 96;
;                 const float s1 = rstd * sc;
; #pragma unroll
;                 for (int n = 0; n < 4; ++n) {
;                     const int c = n * 16 + fq * 4;
;                     const f32x4 g = *(const f32x4*)(gk + c);
;                     const f32x4 v = acc[m][n];
;                     uint2 w; w.x = pack2bf(v[0] * s1 * g[0], v[1] * s1 * g[1]); w.y = pack2bf(v[2] * s1 * g[2], v[3] * s1 * g[3]);
;                     *(uint2*)(krow + c) = w;
;                 }
;                 const f32x4 g1 = *(const f32x4*)(gk + 64 + i0), g2 = *(const f32x4*)(gk + 80 + i0);
; #pragma unroll
;                 for (int j = 0; j < 4; ++j) { x1[j] *= sc * g1[j]; x2[j] *= sc * g2[j]; }
;                 if (t >= CTX) {
;                     const float* rp = rope + ((size_t)(t - CTX) * 16 + i0) * 2;
; #pragma unroll
;                     for (int j = 0; j < 4; ++j) { const float c = rp[2 * j], s = rp[2 * j + 1]; const float a = x1[j] * c - x2[j] * s, bb = x1[j] * s + x2[j] * c; x1[j] = a; x2[j] = bb; }
;                 }
.LBB0_623:
	s_or_b64 exec, exec, s[34:35]
	v_readlane_b32 s0, v252, 20
	v_or_b32_e32 v33, 32, v90
	v_readlane_b32 s1, v252, 21
	s_nop 1
	v_mad_i64_i32 v[34:35], s[0:1], v33, 48, s[0:1]
	v_mov_b64_e32 v[34:35], v[122:123]
	v_mov_b64_e32 v[36:37], v[124:125]
	s_mov_b32 s0, 0x800000
	v_add_f32_e32 v32, v34, v35
	v_add_f32_e32 v32, v32, v36
	v_add_f32_e32 v32, v32, v37
	v_fmamk_f32 v32, v32, 0x3b800000, v108
	v_mul_f32_e32 v34, 0x4b800000, v32
	v_cmp_gt_f32_e64 s[0:1], s0, v32
	s_nop 1
	v_cndmask_b32_e64 v32, v32, v34, s[0:1]
	v_rsq_f32_e32 v32, v32
	s_nop 0
	v_mul_f32_e32 v34, 0x45800000, v32
	v_cndmask_b32_e64 v50, v32, v34, s[0:1]
	s_and_saveexec_b64 s[0:1], vcc
	s_xor_b64 s[0:1], exec, s[0:1]
	s_cbranch_execz .LBB0_625
	v_mul_f32_e32 v28, v28, v50
	v_bfe_u32 v32, v28, 16, 1
	s_movk_i32 s4, 0x7fff
	v_add3_u32 v28, v28, v32, s4
	ds_write_b16_d16_hi v89, v28 offset:64
	v_mul_f32_e32 v28, v29, v50
	v_bfe_u32 v29, v28, 16, 1
	v_add3_u32 v28, v28, v29, s4
	ds_write_b16_d16_hi v89, v28 offset:336
	v_mul_f32_e32 v28, v30, v50
	v_bfe_u32 v29, v28, 16, 1
	v_add3_u32 v28, v28, v29, s4
	ds_write_b16_d16_hi v89, v28 offset:608
	v_mul_f32_e32 v28, v31, v50
	v_bfe_u32 v29, v28, 16, 1
	v_add3_u32 v28, v28, v29, s4
	v_mul_f32_e32 v24, v24, v50
	ds_write_b16_d16_hi v89, v28 offset:880
	v_bfe_u32 v28, v24, 16, 1
	v_add3_u32 v24, v24, v28, s4
	ds_write_b16_d16_hi v89, v24 offset:4416
	v_mul_f32_e32 v24, v25, v50
	v_bfe_u32 v25, v24, 16, 1
	v_add3_u32 v24, v24, v25, s4
	ds_write_b16_d16_hi v89, v24 offset:4688
	v_mul_f32_e32 v24, v26, v50
	v_bfe_u32 v25, v24, 16, 1
	v_add3_u32 v24, v24, v25, s4
	ds_write_b16_d16_hi v89, v24 offset:4960
	v_mul_f32_e32 v24, v27, v50
	v_bfe_u32 v25, v24, 16, 1
	v_add3_u32 v24, v24, v25, s4
	v_mul_f32_e32 v20, v20, v50
	ds_write_b16_d16_hi v89, v24 offset:5232
	v_bfe_u32 v24, v20, 16, 1
	v_add3_u32 v20, v20, v24, s4
	ds_write_b16_d16_hi v89, v20 offset:8768
	v_mul_f32_e32 v20, v21, v50
	v_bfe_u32 v21, v20, 16, 1
	v_add3_u32 v20, v20, v21, s4
	ds_write_b16_d16_hi v89, v20 offset:9040
	v_mul_f32_e32 v20, v22, v50
	v_bfe_u32 v21, v20, 16, 1
	v_add3_u32 v20, v20, v21, s4
	ds_write_b16_d16_hi v89, v20 offset:9312
	v_mul_f32_e32 v20, v23, v50
	v_bfe_u32 v21, v20, 16, 1
	v_add3_u32 v20, v20, v21, s4
	v_mul_f32_e32 v16, v16, v50
	ds_write_b16_d16_hi v89, v20 offset:9584
	v_bfe_u32 v20, v16, 16, 1
	v_add3_u32 v16, v16, v20, s4
	ds_write_b16_d16_hi v89, v16 offset:13120
	v_mul_f32_e32 v16, v17, v50
	v_bfe_u32 v17, v16, 16, 1
	v_add3_u32 v16, v16, v17, s4
	ds_write_b16_d16_hi v89, v16 offset:13392
	v_mul_f32_e32 v16, v18, v50
	v_bfe_u32 v17, v16, 16, 1
	v_add3_u32 v16, v16, v17, s4
	ds_write_b16_d16_hi v89, v16 offset:13664
	v_mul_f32_e32 v16, v19, v50
	v_bfe_u32 v17, v16, 16, 1
	v_add3_u32 v16, v16, v17, s4
	ds_write_b16_d16_hi v89, v16 offset:13936
.LBB0_625:
	s_andn2_saveexec_b64 s[34:35], s[0:1]
	s_cbranch_execz .LBB0_629
	v_mul_hi_i32 v32, v33, s36
	v_lshrrev_b32_e32 v34, 31, v32
	v_ashrrev_i32_e32 v32, 11, v32
	v_add_u32_e32 v45, v32, v34
	v_mul_f32_e32 v34, v25, v25
	v_pk_fma_f32 v[34:35], v[24:25], v[24:25], v[34:35] op_sel_hi:[1,1,0]
	v_mul_f32_e32 v36, v27, v27
	v_pk_fma_f32 v[34:35], v[26:27], v[26:27], v[34:35]
	s_movk_i32 s0, 0xef00
	v_pk_add_f32 v[42:43], v[36:37], v[34:35] op_sel_hi:[0,1]
	v_pk_mul_f32 v[36:37], v[20:21], v[20:21]
	v_pk_mul_f32 v[34:35], v[22:23], v[22:23]
	v_fmac_f32_e32 v37, v20, v20
	v_add_f32_e32 v44, v34, v37
	v_mul_f32_e32 v34, v17, v17
	v_mad_i32_i24 v32, v45, s0, v33
	v_pk_fma_f32 v[34:35], v[16:17], v[16:17], v[34:35] op_sel_hi:[1,1,0]
	v_readlane_b32 s0, v252, 24
	v_pk_fma_f32 v[34:35], v[18:19], v[18:19], v[34:35]
	v_mul_f32_e32 v36, v19, v19
	v_readlane_b32 s1, v252, 25
	v_pk_add_f32 v[40:41], v[36:37], v[34:35] op_sel_hi:[0,1]
	v_mov_b32_e32 v65, v105
	v_mov_b64_e32 v[34:35], s[0:1]
	s_movk_i32 s0, 0x640
	v_mad_i64_i32 v[34:35], s[0:1], v33, s0, v[34:35]
	v_lshl_add_u64 v[34:35], v[34:35], 0, v[64:65]
	v_mov_b64_e32 v[56:57], v[134:135]
	v_mov_b64_e32 v[58:59], v[136:137]
	v_mul_f32_e32 v48, v31, v31
	v_xor_b32_e32 v33, 16, v195
	s_movk_i32 s4, 0xc0
	v_and_b32_e32 v37, 0xffff0000, v57
	v_and_b32_e32 v39, 0xffff0000, v59
	v_lshlrev_b32_e32 v38, 16, v59
	v_lshlrev_b32_e32 v36, 16, v57
	v_pk_mul_f32 v[34:35], v[38:39], v[38:39]
	v_and_b32_e32 v57, 0xffff0000, v56
	v_pk_fma_f32 v[46:47], v[36:37], v[36:37], v[34:35]
	v_mul_f32_e32 v34, v29, v29
	v_pk_fma_f32 v[34:35], v[28:29], v[28:29], v[34:35] op_sel_hi:[1,1,0]
	v_mov_b32_e32 v41, v46
	v_pk_fma_f32 v[34:35], v[30:31], v[30:31], v[34:35]
	s_nop 0
	v_pk_add_f32 v[48:49], v[48:49], v[34:35] op_sel_hi:[0,1]
	v_and_b32_e32 v34, 64, v195
	v_add_u32_e32 v34, 64, v34
	v_cmp_lt_i32_e64 s[0:1], v33, v34
	s_nop 1
	v_cndmask_b32_e64 v33, v195, v33, s[0:1]
	v_lshlrev_b32_e32 v51, 2, v33
	v_xor_b32_e32 v33, 32, v195
	v_cmp_lt_i32_e64 s[0:1], v33, v34
	v_lshl_add_u32 v34, v45, 3, s47
	s_nop 0
	v_cndmask_b32_e64 v33, v195, v33, s[0:1]
	v_lshlrev_b32_e32 v68, 2, v33
	v_ashrrev_i32_e32 v33, 31, v32
	s_movk_i32 s0, 0x1100
	v_mad_i64_i32 v[34:35], s[0:1], v34, s0, v[32:33]
	v_readlane_b32 s0, v251, 58
	v_readlane_b32 s1, v251, 59
	s_nop 1
	v_mov_b64_e32 v[52:53], s[0:1]
	v_mad_u64_u32 v[60:61], s[0:1], v34, s4, v[52:53]
	v_mov_b64_e32 v[52:53], v[224:225]
	v_mov_b64_e32 v[54:55], v[226:227]
	v_mad_i32_i24 v61, v35, s4, v61
	v_lshl_add_u64 v[34:35], v[60:61], 0, v[64:65]
	v_and_b32_e32 v61, 0xffff0000, v58
	v_lshlrev_b32_e32 v60, 16, v56
	v_lshlrev_b32_e32 v56, 16, v58
	v_pk_mul_f32 v[58:59], v[56:57], v[56:57]
	v_pk_mul_f32 v[62:63], v[60:61], v[60:61]
	v_pk_mov_b32 v[66:67], v[22:23], v[60:61] op_sel:[1,0]
	v_mov_b32_e32 v45, v58
	v_mov_b32_e32 v49, v59
	v_mov_b32_e32 v43, v63
	v_pk_fma_f32 v[44:45], v[66:67], v[66:67], v[44:45]
	v_pk_add_f32 v[42:43], v[48:49], v[42:43]
	s_mov_b32 s0, 0x800000
	v_pk_add_f32 v[42:43], v[44:45], v[42:43]
	s_nop 0
	v_pk_add_f32 v[40:41], v[40:41], v[42:43]
	s_nop 0
	v_mul_f32_e32 v33, v40, v50
	v_add_f32_e32 v40, v41, v47
	v_fmac_f32_e32 v40, v50, v33
	ds_bpermute_b32 v33, v51, v40
	s_waitcnt lgkmcnt(0)
; __device__ __forceinline__ unsigned pack2bf(float a, float b) { const f32x2 v = {a, b}; return __builtin_bit_cast(unsigned, __builtin_convertvector(v, bf2_t)); }
;     __device__ __forceinline__ void operator()(const f32x4 (&acc)[4][4], int m0, int n0, int wr, int wc, int fr, int fq, char* smem) const {
;     ...
;                 ss = ss * rstd * rstd + sr;
;                 ss += __shfl_xor(ss, 16); ss += __shfl_xor(ss, 32);
;                 const float sc = rsqrtf(ss * (1.f / 96.f) + 1e-6f);
;                 bf16_t* krow = Kb + ((size_t)(b * 8 + h) * TT + t) * 96;
;                 const float s1 = rstd * sc;
; #pragma unroll
;                 for (int n = 0; n < 4; ++n) {
;                     const int c = n * 16 + fq * 4;
;                     const f32x4 g = *(const f32x4*)(gk + c);
;                     const f32x4 v = acc[m][n];
;                     uint2 w; w.x = pack2bf(v[0] * s1 * g[0], v[1] * s1 * g[1]); w.y = pack2bf(v[2] * s1 * g[2], v[3] * s1 * g[3]);
;                     *(uint2*)(krow + c) = w;
;                 }
;                 const f32x4 g1 = *(const f32x4*)(gk + 64 + i0), g2 = *(const f32x4*)(gk + 80 + i0);
; #pragma unroll
;                 for (int j = 0; j < 4; ++j) { x1[j] *= sc * g1[j]; x2[j] *= sc * g2[j]; }
;                 if (t >= CTX) {
;                     const float* rp = rope + ((size_t)(t - CTX) * 16 + i0) * 2;
; #pragma unroll
;                     for (int j = 0; j < 4; ++j) { const float c = rp[2 * j], s = rp[2 * j + 1]; const float a = x1[j] * c - x2[j] * s, bb = x1[j] * s + x2[j] * c; x1[j] = a; x2[j] = bb; }
;                 }
;                 uint2 w; w.x = pack2bf(x1[0], x1[1]); w.y = pack2bf(x1[2], x1[3]); *(uint2*)(krow + 64 + i0) = w;
;                 w.x = pack2bf(x2[0], x2[1]); w.y = pack2bf(x2[2], x2[3]); *(uint2*)(krow + 80 + i0) = w;
	v_add_f32_e32 v33, v40, v33
	ds_bpermute_b32 v40, v68, v33
	s_waitcnt lgkmcnt(0)
	v_add_f32_e32 v33, v33, v40
	v_fmamk_f32 v33, v33, 0x3c2aaaab, v108
	v_cmp_gt_f32_e64 s[0:1], s0, v33
	v_mul_f32_e32 v40, 0x4b800000, v33
	s_nop 0
	v_cndmask_b32_e64 v33, v33, v40, s[0:1]
	v_rsq_f32_e32 v33, v33
	s_nop 0
	v_mul_f32_e32 v40, 0x45800000, v33
	v_cndmask_b32_e64 v40, v33, v40, s[0:1]
	v_mul_f32_e32 v42, v50, v40
	v_pk_mul_f32 v[28:29], v[28:29], v[42:43] op_sel_hi:[1,0]
	v_pk_mul_f32 v[30:31], v[30:31], v[42:43] op_sel_hi:[1,0]
	v_pk_mul_f32 v[24:25], v[24:25], v[42:43] op_sel_hi:[1,0]
	v_pk_mul_f32 v[26:27], v[26:27], v[42:43] op_sel_hi:[1,0]
	v_pk_mul_f32 v[20:21], v[20:21], v[42:43] op_sel_hi:[1,0]
	v_pk_mul_f32 v[22:23], v[22:23], v[42:43] op_sel_hi:[1,0]
	v_pk_mul_f32 v[16:17], v[16:17], v[42:43] op_sel_hi:[1,0]
	v_pk_mul_f32 v[18:19], v[18:19], v[42:43] op_sel_hi:[1,0]
	v_cmp_lt_i32_e64 s[0:1], s2, v32
	v_pk_mul_f32 v[28:29], v[52:53], v[28:29]
	v_pk_mul_f32 v[30:31], v[54:55], v[30:31]
	v_cvt_pk_bf16_f32 v28, v28, v29
	v_cvt_pk_bf16_f32 v29, v30, v31
	global_store_dwordx2 v[34:35], v[28:29], off
	v_mov_b64_e32 v[28:29], v[228:229]
	v_mov_b64_e32 v[30:31], v[230:231]
	v_pk_mul_f32 v[24:25], v[28:29], v[24:25]
	v_pk_mul_f32 v[26:27], v[30:31], v[26:27]
	v_cvt_pk_bf16_f32 v24, v24, v25
	v_cvt_pk_bf16_f32 v25, v26, v27
	global_store_dwordx2 v[34:35], v[24:25], off offset:32
	v_mov_b64_e32 v[24:25], v[232:233]
	v_mov_b64_e32 v[26:27], v[234:235]
	v_pk_mul_f32 v[20:21], v[24:25], v[20:21]
	v_pk_mul_f32 v[22:23], v[26:27], v[22:23]
	v_cvt_pk_bf16_f32 v20, v20, v21
	v_cvt_pk_bf16_f32 v21, v22, v23
	global_store_dwordx2 v[34:35], v[20:21], off offset:64
	v_mov_b64_e32 v[20:21], v[236:237]
	v_mov_b64_e32 v[22:23], v[238:239]
	v_pk_mul_f32 v[16:17], v[20:21], v[16:17]
	v_pk_mul_f32 v[18:19], v[22:23], v[18:19]
	v_cvt_pk_bf16_f32 v16, v16, v17
	v_cvt_pk_bf16_f32 v17, v18, v19
	global_store_dwordx2 v[34:35], v[16:17], off offset:96
	v_mov_b64_e32 v[22:23], v[240:241]
	v_mov_b64_e32 v[24:25], v[242:243]
	v_mov_b64_e32 v[26:27], v[244:245]
	v_mov_b64_e32 v[28:29], v[246:247]
	v_mov_b32_e32 v16, v22
	v_mov_b32_e32 v17, v27
	v_mov_b32_e32 v27, v23
	v_mul_f32_e32 v20, v24, v40
	v_mov_b32_e32 v24, v29
	v_pk_mul_f32 v[16:17], v[16:17], v[40:41] op_sel_hi:[1,0]
	v_pk_mul_f32 v[18:19], v[26:27], v[40:41] op_sel_hi:[1,0]
	v_mul_f32_e32 v20, v20, v36
	v_mul_f32_e32 v21, v28, v40
	v_pk_mul_f32 v[24:25], v[24:25], v[40:41] op_sel_hi:[1,0]
	v_mov_b32_e32 v36, v39
	v_pk_mul_f32 v[16:17], v[16:17], v[60:61]
	v_pk_mul_f32 v[18:19], v[18:19], v[56:57]
	v_mul_f32_e32 v22, v21, v38
	v_pk_mul_f32 v[24:25], v[24:25], v[36:37]
	s_and_saveexec_b64 s[42:43], s[0:1]
	s_cbranch_execz .LBB0_628
	v_add_u32_e32 v26, 0xffffff00, v32
	v_mov_b32_e32 v27, v105
	v_readlane_b32 s0, v252, 22
	v_lshlrev_b64 v[26:27], 7, v[26:27]
	v_readlane_b32 s1, v252, 23
	v_mov_b32_e32 v40, v18
	v_mov_b32_e32 v41, v17
	v_lshl_add_u64 v[26:27], s[0:1], 0, v[26:27]
	v_lshl_add_u64 v[30:31], v[26:27], 0, v[104:105]
	v_mov_b64_e32 v[26:27], v[150:151]
	v_mov_b64_e32 v[28:29], v[152:153]
	s_nop 0
	v_mov_b64_e32 v[30:31], v[154:155]
	v_mov_b64_e32 v[32:33], v[156:157]
	v_mul_f32_e32 v44, v20, v27
	v_mov_b32_e32 v36, v31
	v_mov_b32_e32 v37, v32
	v_mov_b32_e32 v42, v31
	v_mov_b32_e32 v43, v33
	v_mov_b32_e32 v31, v32
	v_mul_f32_e32 v32, v20, v26
	v_pk_mul_f32 v[20:21], v[24:25], v[28:29] op_sel:[1,0] op_sel_hi:[0,1]
	v_mov_b32_e32 v38, v30
	v_mov_b32_e32 v39, v33
	v_pk_mul_f32 v[40:41], v[40:41], v[42:43]
	v_mov_b32_e32 v33, v20
	v_mov_b32_e32 v43, v21
	v_pk_mul_f32 v[20:21], v[24:25], v[28:29]
	v_pk_mul_f32 v[38:39], v[18:19], v[38:39]
	v_mov_b32_e32 v18, v16
	v_mul_f32_e32 v42, v22, v27
	v_mul_f32_e32 v22, v22, v26
	v_mov_b32_e32 v23, v20
	v_mov_b32_e32 v45, v21
	v_pk_fma_f32 v[26:27], v[18:19], v[30:31], v[40:41] neg_lo:[0,0,1] neg_hi:[0,0,1]
	v_pk_add_f32 v[20:21], v[32:33], v[42:43] neg_lo:[0,1] neg_hi:[0,1]
	v_pk_fma_f32 v[18:19], v[16:17], v[36:37], v[38:39]
	v_pk_add_f32 v[22:23], v[22:23], v[44:45]
	v_mov_b32_e32 v17, v19
	v_mov_b32_e32 v24, v23
	v_mov_b32_e32 v16, v26
	v_mov_b32_e32 v19, v27
	v_mov_b32_e32 v25, v21

;     __device__ __forceinline__ void operator()(const f32x4 (&acc)[4][4], int m0, int n0, int wr, int wc, int fr, int fq, char* smem) const {
;     ...
;             const int row = m0 + wr * 64 + m * 16 + fr;
;             const int b = row / TT, t = row - b * TT;
;             const float skv = stats[(size_t)row * 12 + 8] + stats[(size_t)row * 12 + 9] + stats[(size_t)row * 12 + 10] + stats[(size_t)row * 12 + 11];
;             const float rstd = rsqrtf(skv * (1.f / 256.f) + 1e-6f);
;             if (wc == 0) {
;                 float ss = 0.f;
; #pragma unroll
;                 for (int n = 0; n < 4; ++n) { const f32x4 v = acc[m][n]; ss += v[0] * v[0] + v[1] * v[1] + v[2] * v[2] + v[3] * v[3]; }
;                 const int i0 = fq * 4;
;                 const u16x4 r1 = *(const u16x4*)(zb + (size_t)row * 800 + 768 + i0), r2 = *(const u16x4*)(zb + (size_t)row * 800 + 784 + i0);
;                 float x1[4], x2[4]; float sr = 0.f;
; #pragma unroll
;                 for (int j = 0; j < 4; ++j) { x1[j] = bf2f(r1[j]); x2[j] = bf2f(r2[j]); sr += x1[j] * x1[j] + x2[j] * x2[j]; }
;                 ss = ss * rstd * rstd + sr;
;                 ss += __shfl_xor(ss, 16); ss += __shfl_xor(ss, 32);
;                 const float sc = rsqrtf(ss * (1.f / 96.f) + 1e-6f);
;                 bf16_t* krow = Kb + ((size_t)(b * 8 + h) * TT + t) * 96;
;                 const float s1 = rstd * sc;
; #pragma unroll
;                 for (int n = 0; n < 4; ++n) {
;                     const int c = n * 16 + fq * 4;
;                     const f32x4 g = *(const f32x4*)(gk + c);
;                     const f32x4 v = acc[m][n];
;                     uint2 w; w.x = pack2bf(v[0] * s1 * g[0], v[1] * s1 * g[1]); w.y = pack2bf(v[2] * s1 * g[2], v[3] * s1 * g[3]);
;                     *(uint2*)(krow + c) = w;
;                 }
;                 const f32x4 g1 = *(const f32x4*)(gk + 64 + i0), g2 = *(const f32x4*)(gk + 80 + i0);
; #pragma unroll
;                 for (int j = 0; j < 4; ++j) { x1[j] *= sc * g1[j]; x2[j] *= sc * g2[j]; }
;                 if (t >= CTX) {
;                     const float* rp = rope + ((size_t)(t - CTX) * 16 + i0) * 2;
; #pragma unroll
;                     for (int j = 0; j < 4; ++j) { const float c = rp[2 * j], s = rp[2 * j + 1]; const float a = x1[j] * c - x2[j] * s, bb = x1[j] * s + x2[j] * c; x1[j] = a; x2[j] = bb; }
;                 }
.LBB0_629:
	s_or_b64 exec, exec, s[34:35]
	v_readlane_b32 s0, v252, 20
	v_or_b32_e32 v17, 48, v90
	v_readlane_b32 s1, v252, 21
	s_nop 1
	v_mad_i64_i32 v[18:19], s[0:1], v17, 48, s[0:1]
	v_mov_b64_e32 v[18:19], v[126:127]
	v_mov_b64_e32 v[20:21], v[128:129]
	s_mov_b32 s0, 0x800000
	v_add_f32_e32 v16, v18, v19
	v_add_f32_e32 v16, v16, v20
	v_add_f32_e32 v16, v16, v21
	v_fmamk_f32 v16, v16, 0x3b800000, v108
	v_mul_f32_e32 v18, 0x4b800000, v16
	v_cmp_gt_f32_e64 s[0:1], s0, v16
	s_nop 1
	v_cndmask_b32_e64 v16, v16, v18, s[0:1]
	v_rsq_f32_e32 v16, v16
	s_nop 0
	v_mul_f32_e32 v18, 0x45800000, v16
	v_cndmask_b32_e64 v34, v16, v18, s[0:1]
	s_and_saveexec_b64 s[0:1], vcc
	s_xor_b64 s[0:1], exec, s[0:1]
	s_cbranch_execz .LBB0_631
	v_mul_f32_e32 v12, v12, v34
	v_bfe_u32 v16, v12, 16, 1
	s_movk_i32 s4, 0x7fff
	v_add3_u32 v12, v12, v16, s4
	ds_write_b16_d16_hi v89, v12 offset:96
	v_mul_f32_e32 v12, v13, v34
	v_bfe_u32 v13, v12, 16, 1
	v_add3_u32 v12, v12, v13, s4
	ds_write_b16_d16_hi v89, v12 offset:368
	v_mul_f32_e32 v12, v14, v34
	v_bfe_u32 v13, v12, 16, 1
	v_add3_u32 v12, v12, v13, s4
	ds_write_b16_d16_hi v89, v12 offset:640
	v_mul_f32_e32 v12, v15, v34
	v_bfe_u32 v13, v12, 16, 1
	v_add3_u32 v12, v12, v13, s4
	v_mul_f32_e32 v8, v8, v34
	ds_write_b16_d16_hi v89, v12 offset:912
	v_bfe_u32 v12, v8, 16, 1
	v_add3_u32 v8, v8, v12, s4
	ds_write_b16_d16_hi v89, v8 offset:4448
	v_mul_f32_e32 v8, v9, v34
	v_bfe_u32 v9, v8, 16, 1
	v_add3_u32 v8, v8, v9, s4
	ds_write_b16_d16_hi v89, v8 offset:4720
	v_mul_f32_e32 v8, v10, v34
	v_bfe_u32 v9, v8, 16, 1
	v_add3_u32 v8, v8, v9, s4
	ds_write_b16_d16_hi v89, v8 offset:4992
	v_mul_f32_e32 v8, v11, v34
	v_bfe_u32 v9, v8, 16, 1
	v_add3_u32 v8, v8, v9, s4
	v_mul_f32_e32 v4, v4, v34
	ds_write_b16_d16_hi v89, v8 offset:5264
	v_bfe_u32 v8, v4, 16, 1
	v_add3_u32 v4, v4, v8, s4
	ds_write_b16_d16_hi v89, v4 offset:8800
	v_mul_f32_e32 v4, v5, v34
	v_bfe_u32 v5, v4, 16, 1
	v_add3_u32 v4, v4, v5, s4
	ds_write_b16_d16_hi v89, v4 offset:9072
	v_mul_f32_e32 v4, v6, v34
	v_bfe_u32 v5, v4, 16, 1
	v_add3_u32 v4, v4, v5, s4
	ds_write_b16_d16_hi v89, v4 offset:9344
	v_mul_f32_e32 v4, v7, v34
	v_bfe_u32 v5, v4, 16, 1
	v_add3_u32 v4, v4, v5, s4
	v_mul_f32_e32 v0, v0, v34
	ds_write_b16_d16_hi v89, v4 offset:9616
	v_bfe_u32 v4, v0, 16, 1
	v_add3_u32 v0, v0, v4, s4
	ds_write_b16_d16_hi v89, v0 offset:13152
	v_mul_f32_e32 v0, v1, v34
	v_bfe_u32 v1, v0, 16, 1
	v_add3_u32 v0, v0, v1, s4
	ds_write_b16_d16_hi v89, v0 offset:13424
	v_mul_f32_e32 v0, v2, v34
	v_bfe_u32 v1, v0, 16, 1
	v_add3_u32 v0, v0, v1, s4
	ds_write_b16_d16_hi v89, v0 offset:13696
	v_mul_f32_e32 v0, v3, v34
	v_bfe_u32 v1, v0, 16, 1
	v_add3_u32 v0, v0, v1, s4
	ds_write_b16_d16_hi v89, v0 offset:13968
.LBB0_631:
	s_andn2_saveexec_b64 s[0:1], s[0:1]
	s_cbranch_execz .LBB0_606
	v_mul_hi_i32 v16, v17, s36
	v_lshrrev_b32_e32 v18, 31, v16
	v_ashrrev_i32_e32 v16, 11, v16
	v_add_u32_e32 v29, v16, v18
	v_mul_f32_e32 v18, v9, v9
	v_pk_fma_f32 v[18:19], v[8:9], v[8:9], v[18:19] op_sel_hi:[1,1,0]
	v_mul_f32_e32 v20, v11, v11
	v_pk_fma_f32 v[18:19], v[10:11], v[10:11], v[18:19]
	s_movk_i32 s4, 0xef00
	v_pk_add_f32 v[26:27], v[20:21], v[18:19] op_sel_hi:[0,1]
	v_pk_mul_f32 v[20:21], v[4:5], v[4:5]
	v_pk_mul_f32 v[18:19], v[6:7], v[6:7]
	v_fmac_f32_e32 v21, v4, v4
	v_add_f32_e32 v28, v18, v21
	v_mul_f32_e32 v18, v1, v1
	v_mad_i32_i24 v16, v29, s4, v17
	v_pk_fma_f32 v[18:19], v[0:1], v[0:1], v[18:19] op_sel_hi:[1,1,0]
	v_readlane_b32 s4, v252, 24
	v_pk_fma_f32 v[18:19], v[2:3], v[2:3], v[18:19]
	v_mul_f32_e32 v20, v3, v3
	v_readlane_b32 s5, v252, 25
	v_pk_add_f32 v[24:25], v[20:21], v[18:19] op_sel_hi:[0,1]
	v_mov_b32_e32 v65, v105
	v_mov_b64_e32 v[18:19], s[4:5]
	s_movk_i32 s4, 0x640
	v_mad_i64_i32 v[18:19], s[34:35], v17, s4, v[18:19]
	v_lshl_add_u64 v[18:19], v[18:19], 0, v[64:65]
	v_mov_b64_e32 v[40:41], v[138:139]
	v_mov_b64_e32 v[42:43], v[140:141]
	v_mul_f32_e32 v32, v15, v15
	v_xor_b32_e32 v17, 16, v195
	s_movk_i32 s4, 0x1100
	v_and_b32_e32 v21, 0xffff0000, v41
	v_and_b32_e32 v23, 0xffff0000, v43
	v_lshlrev_b32_e32 v22, 16, v43
	v_lshlrev_b32_e32 v20, 16, v41
	v_pk_mul_f32 v[18:19], v[22:23], v[22:23]
	v_and_b32_e32 v41, 0xffff0000, v40
	v_pk_fma_f32 v[30:31], v[20:21], v[20:21], v[18:19]
	v_mul_f32_e32 v18, v13, v13
	v_pk_fma_f32 v[18:19], v[12:13], v[12:13], v[18:19] op_sel_hi:[1,1,0]
	v_mov_b32_e32 v25, v30
	v_pk_fma_f32 v[18:19], v[14:15], v[14:15], v[18:19]
	s_nop 0
	v_pk_add_f32 v[32:33], v[32:33], v[18:19] op_sel_hi:[0,1]
	v_and_b32_e32 v18, 64, v195
	v_add_u32_e32 v18, 64, v18
	v_cmp_lt_i32_e32 vcc, v17, v18
	s_nop 1
	v_cndmask_b32_e32 v17, v195, v17, vcc
	v_lshlrev_b32_e32 v35, 2, v17
	v_xor_b32_e32 v17, 32, v195
	v_cmp_lt_i32_e32 vcc, v17, v18
	v_lshl_add_u32 v18, v29, 3, s47
	s_nop 0
	v_cndmask_b32_e32 v17, v195, v17, vcc
	v_lshlrev_b32_e32 v50, 2, v17
	v_ashrrev_i32_e32 v17, 31, v16
	v_mad_i64_i32 v[18:19], s[34:35], v18, s4, v[16:17]
	v_readlane_b32 s4, v251, 58
	v_readlane_b32 s5, v251, 59
	s_nop 1
	v_mov_b64_e32 v[36:37], s[4:5]
	s_movk_i32 s4, 0xc0
	v_mad_u64_u32 v[44:45], s[34:35], v18, s4, v[36:37]
	v_mov_b64_e32 v[36:37], v[224:225]
	v_mov_b64_e32 v[38:39], v[226:227]
	v_mad_i32_i24 v45, v19, s4, v45
	v_lshl_add_u64 v[18:19], v[44:45], 0, v[64:65]
	v_and_b32_e32 v45, 0xffff0000, v42
	v_lshlrev_b32_e32 v44, 16, v40
	v_lshlrev_b32_e32 v40, 16, v42
	v_pk_mul_f32 v[42:43], v[40:41], v[40:41]
	v_pk_mul_f32 v[46:47], v[44:45], v[44:45]
	v_pk_mov_b32 v[48:49], v[6:7], v[44:45] op_sel:[1,0]
	v_mov_b32_e32 v29, v42
	v_mov_b32_e32 v33, v43
	v_mov_b32_e32 v27, v47
	v_pk_fma_f32 v[28:29], v[48:49], v[48:49], v[28:29]
	v_pk_add_f32 v[26:27], v[32:33], v[26:27]
	s_mov_b32 s4, 0x800000
	v_pk_add_f32 v[26:27], v[28:29], v[26:27]
	s_nop 0
	v_pk_add_f32 v[24:25], v[24:25], v[26:27]
	s_nop 0
	v_mul_f32_e32 v17, v24, v34
	v_add_f32_e32 v24, v25, v31
	v_fmac_f32_e32 v24, v34, v17
	ds_bpermute_b32 v17, v35, v24
	s_waitcnt lgkmcnt(0)
; __device__ __forceinline__ unsigned pack2bf(float a, float b) { const f32x2 v = {a, b}; return __builtin_bit_cast(unsigned, __builtin_convertvector(v, bf2_t)); }
;     __device__ __forceinline__ void operator()(const f32x4 (&acc)[4][4], int m0, int n0, int wr, int wc, int fr, int fq, char* smem) const {
;     ...
;                 ss = ss * rstd * rstd + sr;
;                 ss += __shfl_xor(ss, 16); ss += __shfl_xor(ss, 32);
;                 const float sc = rsqrtf(ss * (1.f / 96.f) + 1e-6f);
;                 bf16_t* krow = Kb + ((size_t)(b * 8 + h) * TT + t) * 96;
;                 const float s1 = rstd * sc;
; #pragma unroll
;                 for (int n = 0; n < 4; ++n) {
;                     const int c = n * 16 + fq * 4;
;                     const f32x4 g = *(const f32x4*)(gk + c);
;                     const f32x4 v = acc[m][n];
;                     uint2 w; w.x = pack2bf(v[0] * s1 * g[0], v[1] * s1 * g[1]); w.y = pack2bf(v[2] * s1 * g[2], v[3] * s1 * g[3]);
;                     *(uint2*)(krow + c) = w;
;                 }
;                 const f32x4 g1 = *(const f32x4*)(gk + 64 + i0), g2 = *(const f32x4*)(gk + 80 + i0);
; #pragma unroll
;                 for (int j = 0; j < 4; ++j) { x1[j] *= sc * g1[j]; x2[j] *= sc * g2[j]; }
;                 if (t >= CTX) {
;                     const float* rp = rope + ((size_t)(t - CTX) * 16 + i0) * 2;
; #pragma unroll
;                     for (int j = 0; j < 4; ++j) { const float c = rp[2 * j], s = rp[2 * j + 1]; const float a = x1[j] * c - x2[j] * s, bb = x1[j] * s + x2[j] * c; x1[j] = a; x2[j] = bb; }
;                 }
;                 uint2 w; w.x = pack2bf(x1[0], x1[1]); w.y = pack2bf(x1[2], x1[3]); *(uint2*)(krow + 64 + i0) = w;
;                 w.x = pack2bf(x2[0], x2[1]); w.y = pack2bf(x2[2], x2[3]); *(uint2*)(krow + 80 + i0) = w;
	v_add_f32_e32 v17, v24, v17
	ds_bpermute_b32 v24, v50, v17
	s_waitcnt lgkmcnt(0)
	v_add_f32_e32 v17, v17, v24
	v_fmamk_f32 v17, v17, 0x3c2aaaab, v108
	v_cmp_gt_f32_e32 vcc, s4, v17
	v_mul_f32_e32 v24, 0x4b800000, v17
	s_nop 0
	v_cndmask_b32_e32 v17, v17, v24, vcc
	v_rsq_f32_e32 v17, v17
	s_nop 0
	v_mul_f32_e32 v24, 0x45800000, v17
	v_cndmask_b32_e32 v24, v17, v24, vcc
	v_mul_f32_e32 v26, v34, v24
	v_pk_mul_f32 v[12:13], v[12:13], v[26:27] op_sel_hi:[1,0]
	v_pk_mul_f32 v[14:15], v[14:15], v[26:27] op_sel_hi:[1,0]
	v_pk_mul_f32 v[8:9], v[8:9], v[26:27] op_sel_hi:[1,0]
	v_pk_mul_f32 v[10:11], v[10:11], v[26:27] op_sel_hi:[1,0]
	v_pk_mul_f32 v[4:5], v[4:5], v[26:27] op_sel_hi:[1,0]
	v_pk_mul_f32 v[6:7], v[6:7], v[26:27] op_sel_hi:[1,0]
	v_pk_mul_f32 v[0:1], v[0:1], v[26:27] op_sel_hi:[1,0]
	v_pk_mul_f32 v[2:3], v[2:3], v[26:27] op_sel_hi:[1,0]
	v_cmp_lt_i32_e32 vcc, s2, v16
	v_pk_mul_f32 v[12:13], v[36:37], v[12:13]
	v_pk_mul_f32 v[14:15], v[38:39], v[14:15]
	v_cvt_pk_bf16_f32 v12, v12, v13
	v_cvt_pk_bf16_f32 v13, v14, v15
	global_store_dwordx2 v[18:19], v[12:13], off
	v_mov_b64_e32 v[12:13], v[228:229]
	v_mov_b64_e32 v[14:15], v[230:231]
	v_pk_mul_f32 v[8:9], v[12:13], v[8:9]
	v_pk_mul_f32 v[10:11], v[14:15], v[10:11]
	v_cvt_pk_bf16_f32 v8, v8, v9
	v_cvt_pk_bf16_f32 v9, v10, v11
	global_store_dwordx2 v[18:19], v[8:9], off offset:32
	v_mov_b64_e32 v[8:9], v[232:233]
	v_mov_b64_e32 v[10:11], v[234:235]
	v_pk_mul_f32 v[4:5], v[8:9], v[4:5]
	v_pk_mul_f32 v[6:7], v[10:11], v[6:7]
	v_cvt_pk_bf16_f32 v4, v4, v5
	v_cvt_pk_bf16_f32 v5, v6, v7
	global_store_dwordx2 v[18:19], v[4:5], off offset:64
	v_mov_b64_e32 v[4:5], v[236:237]
	v_mov_b64_e32 v[6:7], v[238:239]
	v_pk_mul_f32 v[0:1], v[4:5], v[0:1]
	v_pk_mul_f32 v[2:3], v[6:7], v[2:3]
	v_cvt_pk_bf16_f32 v0, v0, v1
	v_cvt_pk_bf16_f32 v1, v2, v3
	global_store_dwordx2 v[18:19], v[0:1], off offset:96
	v_mov_b64_e32 v[6:7], v[240:241]
	v_mov_b64_e32 v[8:9], v[242:243]
	v_mov_b64_e32 v[10:11], v[244:245]
	v_mov_b64_e32 v[12:13], v[246:247]
	v_mov_b32_e32 v0, v6
	v_mov_b32_e32 v1, v11
	v_mov_b32_e32 v11, v7
	v_mul_f32_e32 v4, v8, v24
	v_mov_b32_e32 v8, v13
	v_pk_mul_f32 v[0:1], v[0:1], v[24:25] op_sel_hi:[1,0]
	v_pk_mul_f32 v[2:3], v[10:11], v[24:25] op_sel_hi:[1,0]
	v_mul_f32_e32 v4, v4, v20
	v_mul_f32_e32 v5, v12, v24
	v_pk_mul_f32 v[8:9], v[8:9], v[24:25] op_sel_hi:[1,0]
	v_mov_b32_e32 v20, v23
	v_pk_mul_f32 v[0:1], v[0:1], v[44:45]
	v_pk_mul_f32 v[2:3], v[2:3], v[40:41]
	v_mul_f32_e32 v6, v5, v22
	v_pk_mul_f32 v[8:9], v[8:9], v[20:21]
	s_and_saveexec_b64 s[34:35], vcc
	s_cbranch_execz .LBB0_605
	v_add_u32_e32 v10, 0xffffff00, v16
	v_mov_b32_e32 v11, v105
	v_readlane_b32 s4, v252, 22
	v_lshlrev_b64 v[10:11], 7, v[10:11]
	v_readlane_b32 s5, v252, 23
	v_mov_b32_e32 v24, v2
	v_mov_b32_e32 v25, v1
	v_lshl_add_u64 v[10:11], s[4:5], 0, v[10:11]
	v_lshl_add_u64 v[14:15], v[10:11], 0, v[104:105]
	v_mov_b64_e32 v[10:11], v[158:159]
	v_mov_b64_e32 v[12:13], v[160:161]
	s_nop 0
	v_mov_b64_e32 v[14:15], v[162:163]
	v_mov_b64_e32 v[16:17], v[164:165]
	v_mul_f32_e32 v28, v4, v11
	v_mov_b32_e32 v20, v15
	v_mov_b32_e32 v21, v16
	v_mov_b32_e32 v26, v15
	v_mov_b32_e32 v27, v17
	v_mov_b32_e32 v15, v16
	v_mul_f32_e32 v16, v4, v10
	v_pk_mul_f32 v[4:5], v[8:9], v[12:13] op_sel:[1,0] op_sel_hi:[0,1]
	v_mov_b32_e32 v22, v14
	v_mov_b32_e32 v23, v17
	v_pk_mul_f32 v[24:25], v[24:25], v[26:27]
	v_mov_b32_e32 v17, v4
	v_mov_b32_e32 v27, v5
	v_pk_mul_f32 v[4:5], v[8:9], v[12:13]
	v_pk_mul_f32 v[22:23], v[2:3], v[22:23]
	v_mov_b32_e32 v2, v0
	v_mul_f32_e32 v26, v6, v11
	v_mul_f32_e32 v6, v6, v10
	v_mov_b32_e32 v7, v4
	v_mov_b32_e32 v29, v5
	v_pk_fma_f32 v[10:11], v[2:3], v[14:15], v[24:25] neg_lo:[0,0,1] neg_hi:[0,0,1]
	v_pk_add_f32 v[4:5], v[16:17], v[26:27] neg_lo:[0,1] neg_hi:[0,1]
	v_pk_fma_f32 v[2:3], v[0:1], v[20:21], v[22:23]
	v_pk_add_f32 v[6:7], v[6:7], v[28:29]
	v_mov_b32_e32 v1, v3
	v_mov_b32_e32 v8, v7
	v_mov_b32_e32 v0, v10
	v_mov_b32_e32 v3, v11
	v_mov_b32_e32 v9, v5
	s_branch .LBB0_605

; __device__ __forceinline__ void phase_c(const Params& p, int layer, char* smem) {
;     ...
;     for (int run = blockIdx.x * 4 + wid; run < ROWS / 17; run += gridDim.x * 4) {
;       const int row0 = run * 17;
;       u16x4 pw[5], cu[5], nx[5];
; #pragma unroll
;       for (int sgi = 0; sgi < 5; ++sgi) {
;           const int c = sgi * 256 + lane * 4;
;           cu[sgi] = (u16x4){0, 0, 0, 0}; pw[sgi] = (u16x4){0, 0, 0, 0}; nx[sgi] = (u16x4){0, 0, 0, 0};
;           if (sgi < 4 || lane < 32) { cu[sgi] = *(const u16x4*)(za + (size_t)row0 * 1152 + c); if (row0 > 0) pw[sgi] = *(const u16x4*)(za + (size_t)(row0 - 1) * 1152 + c); }
.LBB0_639:
	v_lshl_add_u32 v35, v70, 4, v70
	s_movk_i32 s4, 0x900
	v_mad_i64_i32 v[50:51], s[0:1], v35, s4, v[30:31]
	v_lshl_add_u64 v[228:229], v[50:51], 0, v[104:105]
	s_mov_b64 s[100:101], 0x1000
	global_load_dwordx4 v[224:227], v[228:229], off offset:-2304
	global_load_dwordx4 v[224:227], v[228:229], off offset:-1280
	global_load_dwordx4 v[224:227], v[228:229], off offset:-256
	global_load_dwordx4 v[224:227], v[228:229], off offset:768
	v_add_co_u32_e32 v228, vcc, 0x700, v228
	s_nop 1
	v_addc_co_u32_e32 v229, vcc, 0, v229, vcc
	global_load_dwordx4 v[224:227], v[228:229], off offset:0
	global_load_dwordx4 v[224:227], v[228:229], off offset:1024
	global_load_dwordx4 v[224:227], v[228:229], off offset:2048
	global_load_dwordx4 v[224:227], v[228:229], off offset:3072
	v_lshl_add_u64 v[228:229], v[228:229], 0, s[100:101]
	global_load_dwordx4 v[224:227], v[228:229], off offset:0
	global_load_dwordx4 v[224:227], v[228:229], off offset:1024
	global_load_dwordx4 v[224:227], v[228:229], off offset:2048
	global_load_dwordx4 v[224:227], v[228:229], off offset:3072
	v_lshl_add_u64 v[228:229], v[228:229], 0, s[100:101]
	global_load_dwordx4 v[224:227], v[228:229], off offset:0
	global_load_dwordx4 v[224:227], v[228:229], off offset:1024
	global_load_dwordx4 v[224:227], v[228:229], off offset:2048
	global_load_dwordx4 v[224:227], v[228:229], off offset:3072
	v_lshl_add_u64 v[228:229], v[228:229], 0, s[100:101]
	global_load_dwordx4 v[224:227], v[228:229], off offset:0
	global_load_dwordx4 v[224:227], v[228:229], off offset:1024
	global_load_dwordx4 v[224:227], v[228:229], off offset:2048
	global_load_dwordx4 v[224:227], v[228:229], off offset:3072
	v_lshl_add_u64 v[228:229], v[228:229], 0, s[100:101]
	global_load_dwordx4 v[224:227], v[228:229], off offset:0
	global_load_dwordx4 v[224:227], v[228:229], off offset:1024
	global_load_dwordx4 v[224:227], v[228:229], off offset:2048
	global_load_dwordx4 v[224:227], v[228:229], off offset:3072
	v_lshl_add_u64 v[228:229], v[228:229], 0, s[100:101]
	global_load_dwordx4 v[224:227], v[228:229], off offset:0
	global_load_dwordx4 v[224:227], v[228:229], off offset:1024
	global_load_dwordx4 v[224:227], v[228:229], off offset:2048
	global_load_dwordx4 v[224:227], v[228:229], off offset:3072
	v_lshl_add_u64 v[228:229], v[228:229], 0, s[100:101]
	global_load_dwordx4 v[224:227], v[228:229], off offset:0
	global_load_dwordx4 v[224:227], v[228:229], off offset:1024
	global_load_dwordx4 v[224:227], v[228:229], off offset:2048
	global_load_dwordx4 v[224:227], v[228:229], off offset:3072
	v_lshl_add_u64 v[228:229], v[228:229], 0, s[100:101]
	global_load_dwordx4 v[224:227], v[228:229], off offset:0
	global_load_dwordx4 v[224:227], v[228:229], off offset:1024
	global_load_dwordx4 v[224:227], v[228:229], off offset:2048
	global_load_dwordx4 v[224:227], v[228:229], off offset:3072
	v_lshl_add_u64 v[228:229], v[228:229], 0, s[100:101]
	global_load_dwordx4 v[224:227], v[228:229], off offset:0
	global_load_dwordx4 v[224:227], v[228:229], off offset:1024
	global_load_dwordx4 v[224:227], v[228:229], off offset:2048
	global_load_dwordx4 v[224:227], v[228:229], off offset:3072
	v_lshl_add_u64 v[228:229], v[228:229], 0, s[100:101]
	global_load_dwordx4 v[224:227], v[228:229], off offset:0
	global_load_dwordx4 v[224:227], v[228:229], off offset:1024
	global_load_dwordx4 v[224:227], v[228:229], off offset:2048
	global_load_dwordx4 v[224:227], v[228:229], off offset:3072
	global_load_dwordx2 v[36:37], v[50:51], off
	v_cmp_lt_i32_e32 vcc, 0, v35
	v_add_u32_e32 v35, -1, v35
	v_mov_b64_e32 v[38:39], s[28:29]
	s_movk_i32 s33, 0x900
	v_mad_u64_u32 v[48:49], s[0:1], v35, s4, v[38:39]
	v_mov_b32_e32 v62, 0
	v_mov_b32_e32 v64, 0
	v_mov_b32_e32 v63, 0
	s_and_saveexec_b64 s[0:1], vcc
	s_cbranch_execz .LBB0_641
	v_lshl_add_u64 v[38:39], v[48:49], 0, v[104:105]
	global_load_dwordx2 v[62:63], v[38:39], off

; template <class Epi>
; __device__ __forceinline__ void gemm_tile(const bf16_t* A, int lda, const bf16_t* Bt, int ldb, int K, int m0, int n0, const Epi& epi, char* smem) {
;     ...
;     const int lr = lane >> 3;
;     const bf16_t* Ag[4]; const bf16_t* Bg[4];
; #pragma unroll
;     for (int i = 0; i < 4; ++i) {
;         const int r = (wid + 4 * i) * 8 + lr, lc = (lane & 7) ^ ((r >> 1) & 7);
;         Ag[i] = A + (size_t)(m0 + r) * lda + lc * 8; Bg[i] = Bt + (size_t)(n0 + r) * ldb + lc * 8;
;     }
;     const unsigned lds0 = (unsigned)(uintptr_t)smem;
;     const int rsw = (fr >> 1) & 7;
;     const int aofs = (wr * 64 + fr) * 128, bofs = 16384 + (wc * 64 + fr) * 128;
;     const int nk = K >> 6;
;     ...
;     G_ISSUE(0, 0)
;     asm volatile("s_waitcnt vmcnt(0)" ::: "memory");
.LBB0_696:
	v_mov_b32_e32 v16, v109
	s_lshl_b32 s30, s53, 7
	v_ashrrev_i32_e32 v17, 6, v16
	v_bfe_u32 v18, v16, 3, 3
	v_lshlrev_b32_e32 v19, 3, v17
	v_or_b32_e32 v12, v19, v18
	v_lshrrev_b32_e32 v20, 1, v12
	v_add_u32_e32 v0, s30, v12
	v_xor_b32_e32 v2, v20, v16
	s_waitcnt lgkmcnt(0)
	v_ashrrev_i32_e32 v1, 31, v0
	s_lshl_b32 s42, s52, 7
	v_lshlrev_b64 v[0:1], 11, v[0:1]
	v_lshlrev_b32_e32 v2, 4, v2
	v_lshlrev_b32_e32 v85, 10, v17
	v_lshl_add_u64 v[0:1], s[40:41], 0, v[0:1]
	v_and_b32_e32 v104, 0x70, v2
	v_add_u32_e32 v2, s42, v12
	v_add_u32_e32 v6, 32, v12
	v_readfirstlane_b32 s0, v85
	v_lshl_add_u64 v[0:1], v[0:1], 0, v[104:105]
	v_ashrrev_i32_e32 v3, 31, v2
	s_mov_b64 s[4:5], s[20:21]
	v_add_u32_e32 v4, s30, v6
	s_mov_b32 m0, s0
	v_lshlrev_b64 v[2:3], 11, v[2:3]
	s_mov_b64 s[10:11], s[26:27]
	v_ashrrev_i32_e32 v5, 31, v4
	v_add_u32_e32 v6, s42, v6
	v_add_u32_e32 v10, 64, v12
	global_load_lds_dwordx4 v[0:1], off
	v_add_u32_e32 v0, 0x4000, v85
	v_lshl_add_u64 v[2:3], s[10:11], 0, v[2:3]
	v_lshlrev_b64 v[4:5], 11, v[4:5]
	v_ashrrev_i32_e32 v7, 31, v6
	v_add_u32_e32 v8, s30, v10
	v_readfirstlane_b32 s0, v0
	v_add_u32_e32 v0, 0x1000, v85
	v_lshl_add_u64 v[2:3], v[2:3], 0, v[104:105]
	v_lshl_add_u64 v[4:5], s[40:41], 0, v[4:5]
	v_lshlrev_b64 v[6:7], 11, v[6:7]
	v_ashrrev_i32_e32 v9, 31, v8
	v_add_u32_e32 v10, s42, v10
	v_add_u32_e32 v14, 0x60, v12
	s_mov_b32 m0, s0
	v_readfirstlane_b32 s0, v0
	v_add_u32_e32 v0, 0x5000, v85
	v_lshl_add_u64 v[4:5], v[4:5], 0, v[104:105]
	v_lshl_add_u64 v[6:7], s[10:11], 0, v[6:7]
	v_lshlrev_b64 v[8:9], 11, v[8:9]
	v_ashrrev_i32_e32 v11, 31, v10
	v_add_u32_e32 v12, s30, v14
	global_load_lds_dwordx4 v[2:3], off
	s_mov_b32 m0, s0
	v_readfirstlane_b32 s0, v0
	v_add_u32_e32 v0, 0x2000, v85
	v_lshl_add_u64 v[6:7], v[6:7], 0, v[104:105]
	v_lshl_add_u64 v[8:9], s[40:41], 0, v[8:9]
	v_lshlrev_b64 v[10:11], 11, v[10:11]
	v_ashrrev_i32_e32 v13, 31, v12
	v_add_u32_e32 v14, s42, v14
	global_load_lds_dwordx4 v[4:5], off
	s_mov_b32 m0, s0
	v_readfirstlane_b32 s0, v0
	v_add_u32_e32 v0, 0x6000, v85
	v_lshl_add_u64 v[8:9], v[8:9], 0, v[104:105]
	v_lshl_add_u64 v[10:11], s[10:11], 0, v[10:11]
	v_lshlrev_b64 v[12:13], 11, v[12:13]
	v_ashrrev_i32_e32 v15, 31, v14
	global_load_lds_dwordx4 v[6:7], off
	s_mov_b32 m0, s0
	v_readfirstlane_b32 s0, v0
	v_add_u32_e32 v0, 0x3000, v85
	v_lshl_add_u64 v[10:11], v[10:11], 0, v[104:105]
	v_lshl_add_u64 v[12:13], s[40:41], 0, v[12:13]
	v_lshlrev_b64 v[14:15], 11, v[14:15]
	global_load_lds_dwordx4 v[8:9], off
	s_mov_b32 m0, s0
	v_readfirstlane_b32 s0, v0
	v_add_u32_e32 v0, 0x7000, v85
	v_lshl_add_u64 v[12:13], v[12:13], 0, v[104:105]
	v_lshl_add_u64 v[14:15], s[10:11], 0, v[14:15]
	global_load_lds_dwordx4 v[10:11], off
	s_mov_b32 m0, s0
	v_readfirstlane_b32 s0, v0
	v_lshl_add_u64 v[14:15], v[14:15], 0, v[104:105]
	global_load_lds_dwordx4 v[12:13], off
	s_mov_b32 m0, s0
	v_and_b32_e32 v83, 15, v16
	global_load_lds_dwordx4 v[14:15], off
	v_lshrrev_b32_e32 v21, 1, v16
	v_bfe_u32 v84, v16, 4, 2
	v_ashrrev_i32_e32 v82, 7, v16
	v_and_b32_e32 v80, 1, v17
	v_lshlrev_b32_e32 v23, 7, v83
	v_bitop3_b32 v0, v84, v21, 7 bitop3:0x78
	v_bfe_u32 v22, v16, 1, 3
	v_lshlrev_b32_e32 v0, 4, v0
	v_lshl_or_b32 v2, v82, 13, v23
	v_lshl_or_b32 v3, v80, 13, v23
	v_bitop3_b32 v1, v84, v22, 4 bitop3:0x36
	v_or_b32_e32 v88, v2, v0
	v_or_b32_e32 v89, v3, v0
	v_or_b32_e32 v0, s30, v18
	v_lshlrev_b32_e32 v1, 4, v1
	v_add_u32_e32 v0, v0, v19
	v_or_b32_e32 v87, v2, v1
	v_or_b32_e32 v86, v3, v1
	v_ashrrev_i32_e32 v1, 31, v0
	v_bitop3_b32 v2, v20, 7, v16 bitop3:0x48
	v_lshlrev_b64 v[0:1], 11, v[0:1]
	v_lshlrev_b32_e32 v2, 4, v2
	v_readlane_b32 s0, v252, 55
	v_or_b32_e32 v0, v0, v2
	v_readlane_b32 s1, v252, 56
	v_readlane_b32 s4, v253, 0
	v_readlane_b32 s5, v253, 1
	v_lshl_add_u64 v[64:65], s[0:1], 0, v[0:1]
	v_or_b32_e32 v0, s42, v18
	v_add_u32_e32 v0, v0, v19
	v_ashrrev_i32_e32 v1, 31, v0
	v_lshlrev_b64 v[0:1], 11, v[0:1]
	v_or_b32_e32 v0, v0, v2
	v_or_b32_e32 v3, 32, v18
	v_lshl_add_u64 v[66:67], s[4:5], 0, v[0:1]
	v_or_b32_e32 v0, s30, v3
	v_add_u32_e32 v0, v0, v19
	v_ashrrev_i32_e32 v1, 31, v0
	v_lshlrev_b64 v[0:1], 11, v[0:1]
	v_or_b32_e32 v0, v0, v2
	v_lshl_add_u64 v[68:69], s[0:1], 0, v[0:1]
	v_or_b32_e32 v0, s42, v3
	v_add_u32_e32 v0, v0, v19
	v_ashrrev_i32_e32 v1, 31, v0
	v_lshlrev_b64 v[0:1], 11, v[0:1]
	v_or_b32_e32 v0, v0, v2
	v_or_b32_e32 v3, 64, v18
	v_lshl_add_u64 v[70:71], s[4:5], 0, v[0:1]
	v_or_b32_e32 v0, s30, v3
	v_add_u32_e32 v0, v0, v19
	v_ashrrev_i32_e32 v1, 31, v0
	v_lshlrev_b64 v[0:1], 11, v[0:1]
	v_or_b32_e32 v0, v0, v2
	v_lshl_add_u64 v[72:73], s[0:1], 0, v[0:1]
	v_or_b32_e32 v0, s42, v3
	v_add_u32_e32 v0, v0, v19
	v_ashrrev_i32_e32 v1, 31, v0
	v_lshlrev_b64 v[0:1], 11, v[0:1]
	v_or_b32_e32 v0, v0, v2
	v_or_b32_e32 v3, 0x60, v18
	v_lshl_add_u64 v[74:75], s[4:5], 0, v[0:1]
	v_or_b32_e32 v0, s30, v3
	v_add_u32_e32 v0, v0, v19
	v_ashrrev_i32_e32 v1, 31, v0
	v_lshlrev_b64 v[0:1], 11, v[0:1]
	v_or_b32_e32 v0, v0, v2
	v_lshl_add_u64 v[76:77], s[0:1], 0, v[0:1]
	v_or_b32_e32 v0, s42, v3
	v_add_u32_e32 v0, v0, v19
	v_ashrrev_i32_e32 v1, 31, v0
	v_lshlrev_b64 v[0:1], 11, v[0:1]
	s_waitcnt vmcnt(0)
; template <class Epi>
; __device__ __forceinline__ void gemm_tile(const bf16_t* A, int lda, const bf16_t* Bt, int ldb, int K, int m0, int n0, const Epi& epi, char* smem) {
;     ...
;     f32x4 acc[4][4];
; #pragma unroll
;     for (int m = 0; m < 4; ++m)
; #pragma unroll
;         for (int n = 0; n < 4; ++n) acc[m][n] = (f32x4){0.f, 0.f, 0.f, 0.f};
;     const int lr = lane >> 3;
;     const bf16_t* Ag[4]; const bf16_t* Bg[4];
; #pragma unroll
;     for (int i = 0; i < 4; ++i) {
;         const int r = (wid + 4 * i) * 8 + lr, lc = (lane & 7) ^ ((r >> 1) & 7);
;         Ag[i] = A + (size_t)(m0 + r) * lda + lc * 8; Bg[i] = Bt + (size_t)(n0 + r) * ldb + lc * 8;
;     }
;     const unsigned lds0 = (unsigned)(uintptr_t)smem;
;     const int rsw = (fr >> 1) & 7;
;     const int aofs = (wr * 64 + fr) * 128, bofs = 16384 + (wc * 64 + fr) * 128;
;     const int nk = K >> 6;
;     ...
;     G_ISSUE(0, 0)
;     asm volatile("s_waitcnt vmcnt(0)" ::: "memory");
;     __syncthreads();
;     for (int kt = 0; kt < nk; ++kt) {
;         const int st = (kt & 1) * 32768;
;         if (kt + 1 < nk) G_ISSUE(((kt + 1) & 1) * 32768, (kt + 1) * 64)
;         {
;             bf16x8 a0[4], b0[4], a1[4], b1[4];
;             const int ch0 = ((0 + fq) ^ rsw) << 4, ch1 = ((4 + fq) ^ rsw) << 4;
; #pragma unroll
;             for (int m = 0; m < 4; ++m) a0[m] = *(const bf16x8*)(smem + st + aofs + m * 2048 + ch0);
; #pragma unroll
;             for (int n = 0; n < 4; ++n) b0[n] = *(const bf16x8*)(smem + st + bofs + n * 2048 + ch0);
;             __builtin_amdgcn_sched_barrier(0);
; #pragma unroll
;             for (int m = 0; m < 4; ++m) a1[m] = *(const bf16x8*)(smem + st + aofs + m * 2048 + ch1);
; #pragma unroll
;             for (int n = 0; n < 4; ++n) b1[n] = *(const bf16x8*)(smem + st + bofs + n * 2048 + ch1);
;             __builtin_amdgcn_sched_barrier(0);
;             __builtin_amdgcn_s_setprio(1);
; #pragma unroll
;             for (int m = 0; m < 4; ++m)
; #pragma unroll
;                 for (int n = 0; n < 4; ++n) acc[m][n] = __builtin_amdgcn_mfma_f32_16x16x32_bf16(b0[n], a0[m], acc[m][n], 0, 0, 0);
;             __builtin_amdgcn_sched_barrier(0);
; #pragma unroll
;             for (int m = 0; m < 4; ++m)
; #pragma unroll
;                 for (int n = 0; n < 4; ++n) acc[m][n] = __builtin_amdgcn_mfma_f32_16x16x32_bf16(b1[n], a1[m], acc[m][n], 0, 0, 0);
	v_or_b32_e32 v0, v0, v2
	v_lshl_add_u64 v[78:79], s[4:5], 0, v[0:1]
	v_mov_b32_e32 v0, 0
	v_and_b32_e32 v81, 63, v16
	s_mov_b64 s[0:1], 0
	s_mov_b32 s31, 0x8000
	v_mov_b32_e32 v1, v0
	v_mov_b32_e32 v2, v0
	v_mov_b32_e32 v3, v0
	v_mov_b32_e32 v4, v0
	v_mov_b32_e32 v5, v0
	v_mov_b32_e32 v6, v0
	v_mov_b32_e32 v7, v0
	v_mov_b32_e32 v8, v0
	v_mov_b32_e32 v9, v0
	v_mov_b32_e32 v10, v0
	v_mov_b32_e32 v11, v0
	v_mov_b32_e32 v12, v0
	v_mov_b32_e32 v13, v0
	v_mov_b32_e32 v14, v0
	v_mov_b32_e32 v15, v0
	v_mov_b32_e32 v16, v0
	v_mov_b32_e32 v17, v0
	v_mov_b32_e32 v18, v0
	v_mov_b32_e32 v19, v0
	v_mov_b32_e32 v20, v0
	v_mov_b32_e32 v21, v0
	v_mov_b32_e32 v22, v0
	v_mov_b32_e32 v23, v0
	v_mov_b32_e32 v24, v0
	v_mov_b32_e32 v25, v0
	v_mov_b32_e32 v26, v0
	v_mov_b32_e32 v27, v0
	v_mov_b32_e32 v36, v0
	v_mov_b32_e32 v37, v0
	v_mov_b32_e32 v38, v0
	v_mov_b32_e32 v39, v0
	v_mov_b32_e32 v28, v0
	v_mov_b32_e32 v29, v0
	v_mov_b32_e32 v30, v0
	v_mov_b32_e32 v31, v0
	v_mov_b32_e32 v32, v0
	v_mov_b32_e32 v33, v0
	v_mov_b32_e32 v34, v0
	v_mov_b32_e32 v35, v0
	v_mov_b32_e32 v40, v0
	v_mov_b32_e32 v41, v0
	v_mov_b32_e32 v42, v0
	v_mov_b32_e32 v43, v0
	v_mov_b32_e32 v44, v0
	v_mov_b32_e32 v45, v0
	v_mov_b32_e32 v46, v0
	v_mov_b32_e32 v47, v0
	v_mov_b32_e32 v48, v0
	v_mov_b32_e32 v49, v0
	v_mov_b32_e32 v50, v0
	v_mov_b32_e32 v51, v0
	v_mov_b32_e32 v52, v0
	v_mov_b32_e32 v53, v0
	v_mov_b32_e32 v54, v0
	v_mov_b32_e32 v55, v0
	v_mov_b32_e32 v56, v0
	v_mov_b32_e32 v57, v0
	v_mov_b32_e32 v58, v0
	v_mov_b32_e32 v59, v0
	v_mov_b32_e32 v60, v0
	v_mov_b32_e32 v61, v0
	v_mov_b32_e32 v62, v0
	v_mov_b32_e32 v63, v0
	s_mov_b64 s[6:7], s[22:23]
	s_mov_b64 s[8:9], s[24:25]
	v_readfirstlane_b32 s98, v85
	s_mov_b64 s[100:101], 0
	s_nop 3
	s_add_u32 s99, s98, 0x8000
	s_mov_b32 m0, s99
	v_lshl_add_u64 v[166:167], v[64:65], 0, s[100:101]
	global_load_lds_dwordx4 v[166:167], off
	s_add_u32 m0, s99, 0x4000
	v_lshl_add_u64 v[166:167], v[66:67], 0, s[100:101]
	global_load_lds_dwordx4 v[166:167], off
	s_add_u32 m0, s99, 0x1000
	v_lshl_add_u64 v[166:167], v[68:69], 0, s[100:101]
	global_load_lds_dwordx4 v[166:167], off
	s_add_u32 m0, s99, 0x5000
	v_lshl_add_u64 v[166:167], v[70:71], 0, s[100:101]
	global_load_lds_dwordx4 v[166:167], off
	s_add_u32 m0, s99, 0x2000
	v_lshl_add_u64 v[166:167], v[72:73], 0, s[100:101]
	global_load_lds_dwordx4 v[166:167], off
	s_add_u32 m0, s99, 0x6000
	v_lshl_add_u64 v[166:167], v[74:75], 0, s[100:101]
	global_load_lds_dwordx4 v[166:167], off
	s_add_u32 m0, s99, 0x3000
	v_lshl_add_u64 v[166:167], v[76:77], 0, s[100:101]
	global_load_lds_dwordx4 v[166:167], off
	s_add_u32 m0, s99, 0x7000
	v_lshl_add_u64 v[166:167], v[78:79], 0, s[100:101]
	global_load_lds_dwordx4 v[166:167], off
	s_waitcnt vmcnt(8) lgkmcnt(0)
	s_barrier
.LBB0_697:
	s_add_i32 s34, s31, 0xffff8000
	s_and_b32 s34, s34, 0x8000
	v_add_u32_e32 v102, s34, v88
	ds_read_b128 v[90:93], v102
	ds_read_b128 v[94:97], v102 offset:2048
	ds_read_b128 v[98:101], v102 offset:4096
	ds_read_b128 v[114:117], v102 offset:6144
	v_or_b32_e32 v102, s34, v89
	ds_read_b128 v[118:121], v102 offset:16384
	ds_read_b128 v[122:125], v102 offset:18432
	ds_read_b128 v[126:129], v102 offset:20480
	ds_read_b128 v[130:133], v102 offset:22528
	v_add_u32_e32 v102, s34, v87
	ds_read_b128 v[134:137], v102
	ds_read_b128 v[138:141], v102 offset:2048
	ds_read_b128 v[142:145], v102 offset:4096
	ds_read_b128 v[146:149], v102 offset:6144
	v_or_b32_e32 v102, s34, v86
	ds_read_b128 v[150:153], v102 offset:16384
	ds_read_b128 v[154:157], v102 offset:18432
	ds_read_b128 v[158:161], v102 offset:20480
	ds_read_b128 v[162:165], v102 offset:22528
	s_waitcnt lgkmcnt(0)
	s_barrier
	s_cmpk_eq_i32 s0, 0x700
	s_cbranch_scc1 .Lnodma_g697
	s_add_u32 s100, s0, 0x80
	s_addc_u32 s101, s1, 0
	s_add_u32 s99, s98, s34
	s_setprio 1
	v_mfma_f32_16x16x32_bf16 v[36:39], v[118:121], v[90:93], v[36:39]
	v_mfma_f32_16x16x32_bf16 v[24:27], v[122:125], v[90:93], v[24:27]
	v_mfma_f32_16x16x32_bf16 v[20:23], v[126:129], v[90:93], v[20:23]
	v_mfma_f32_16x16x32_bf16 v[16:19], v[130:133], v[90:93], v[16:19]
	s_mov_b32 m0, s99
	v_lshl_add_u64 v[166:167], v[64:65], 0, s[100:101]
	global_load_lds_dwordx4 v[166:167], off
	v_mfma_f32_16x16x32_bf16 v[12:15], v[118:121], v[94:97], v[12:15]
	v_mfma_f32_16x16x32_bf16 v[8:11], v[122:125], v[94:97], v[8:11]
	v_mfma_f32_16x16x32_bf16 v[4:7], v[126:129], v[94:97], v[4:7]
	v_mfma_f32_16x16x32_bf16 v[0:3], v[130:133], v[94:97], v[0:3]
	s_add_u32 m0, s99, 0x4000
	v_lshl_add_u64 v[166:167], v[66:67], 0, s[100:101]
	global_load_lds_dwordx4 v[166:167], off
	v_mfma_f32_16x16x32_bf16 v[28:31], v[118:121], v[98:101], v[28:31]
	v_mfma_f32_16x16x32_bf16 v[32:35], v[122:125], v[98:101], v[32:35]
	v_mfma_f32_16x16x32_bf16 v[40:43], v[126:129], v[98:101], v[40:43]
	v_mfma_f32_16x16x32_bf16 v[44:47], v[130:133], v[98:101], v[44:47]
	s_add_u32 m0, s99, 0x1000
	v_lshl_add_u64 v[166:167], v[68:69], 0, s[100:101]
	global_load_lds_dwordx4 v[166:167], off
	v_mfma_f32_16x16x32_bf16 v[48:51], v[118:121], v[114:117], v[48:51]
	v_mfma_f32_16x16x32_bf16 v[52:55], v[122:125], v[114:117], v[52:55]
	v_mfma_f32_16x16x32_bf16 v[56:59], v[126:129], v[114:117], v[56:59]
	v_mfma_f32_16x16x32_bf16 v[60:63], v[130:133], v[114:117], v[60:63]
	s_add_u32 m0, s99, 0x5000
	v_lshl_add_u64 v[166:167], v[70:71], 0, s[100:101]
	global_load_lds_dwordx4 v[166:167], off
	v_mfma_f32_16x16x32_bf16 v[36:39], v[150:153], v[134:137], v[36:39]
	v_mfma_f32_16x16x32_bf16 v[24:27], v[154:157], v[134:137], v[24:27]
	v_mfma_f32_16x16x32_bf16 v[20:23], v[158:161], v[134:137], v[20:23]
	v_mfma_f32_16x16x32_bf16 v[16:19], v[162:165], v[134:137], v[16:19]
	s_add_u32 m0, s99, 0x2000
	v_lshl_add_u64 v[166:167], v[72:73], 0, s[100:101]
	global_load_lds_dwordx4 v[166:167], off
	v_mfma_f32_16x16x32_bf16 v[12:15], v[150:153], v[138:141], v[12:15]
	v_mfma_f32_16x16x32_bf16 v[8:11], v[154:157], v[138:141], v[8:11]
	v_mfma_f32_16x16x32_bf16 v[4:7], v[158:161], v[138:141], v[4:7]
	v_mfma_f32_16x16x32_bf16 v[0:3], v[162:165], v[138:141], v[0:3]
	s_add_u32 m0, s99, 0x6000
	v_lshl_add_u64 v[166:167], v[74:75], 0, s[100:101]
	global_load_lds_dwordx4 v[166:167], off
	v_mfma_f32_16x16x32_bf16 v[28:31], v[150:153], v[142:145], v[28:31]
	v_mfma_f32_16x16x32_bf16 v[32:35], v[154:157], v[142:145], v[32:35]
	v_mfma_f32_16x16x32_bf16 v[40:43], v[158:161], v[142:145], v[40:43]
	v_mfma_f32_16x16x32_bf16 v[44:47], v[162:165], v[142:145], v[44:47]
	s_add_u32 m0, s99, 0x3000
	v_lshl_add_u64 v[166:167], v[76:77], 0, s[100:101]
	global_load_lds_dwordx4 v[166:167], off
	v_mfma_f32_16x16x32_bf16 v[48:51], v[150:153], v[146:149], v[48:51]
	v_mfma_f32_16x16x32_bf16 v[52:55], v[154:157], v[146:149], v[52:55]
	v_mfma_f32_16x16x32_bf16 v[56:59], v[158:161], v[146:149], v[56:59]
	v_mfma_f32_16x16x32_bf16 v[60:63], v[162:165], v[146:149], v[60:63]
	s_add_u32 m0, s99, 0x7000
	v_lshl_add_u64 v[166:167], v[78:79], 0, s[100:101]
	global_load_lds_dwordx4 v[166:167], off
	s_setprio 0
	s_branch .Ljoin_g697

; template <class Epi>
; __device__ __forceinline__ void gemm_tile(const bf16_t* A, int lda, const bf16_t* Bt, int ldb, int K, int m0, int n0, const Epi& epi, char* smem) {
;     ...
;         {
;             bf16x8 a0[4], b0[4], a1[4], b1[4];
;             const int ch0 = ((0 + fq) ^ rsw) << 4, ch1 = ((4 + fq) ^ rsw) << 4;
; #pragma unroll
;             for (int m = 0; m < 4; ++m) a0[m] = *(const bf16x8*)(smem + st + aofs + m * 2048 + ch0);
; #pragma unroll
;             for (int n = 0; n < 4; ++n) b0[n] = *(const bf16x8*)(smem + st + bofs + n * 2048 + ch0);
;             __builtin_amdgcn_sched_barrier(0);
; #pragma unroll
;             for (int m = 0; m < 4; ++m) a1[m] = *(const bf16x8*)(smem + st + aofs + m * 2048 + ch1);
; #pragma unroll
;             for (int n = 0; n < 4; ++n) b1[n] = *(const bf16x8*)(smem + st + bofs + n * 2048 + ch1);
;             __builtin_amdgcn_sched_barrier(0);
;             __builtin_amdgcn_s_setprio(1);
; #pragma unroll
;             for (int m = 0; m < 4; ++m)
; #pragma unroll
;                 for (int n = 0; n < 4; ++n) acc[m][n] = __builtin_amdgcn_mfma_f32_16x16x32_bf16(b0[n], a0[m], acc[m][n], 0, 0, 0);
;             __builtin_amdgcn_sched_barrier(0);
; #pragma unroll
;             for (int m = 0; m < 4; ++m)
; #pragma unroll
;                 for (int n = 0; n < 4; ++n) acc[m][n] = __builtin_amdgcn_mfma_f32_16x16x32_bf16(b1[n], a1[m], acc[m][n], 0, 0, 0);
;             __builtin_amdgcn_s_setprio(0);
;             __builtin_amdgcn_sched_barrier(0);
;         }
;         asm volatile("s_waitcnt vmcnt(0)" ::: "memory");
;         __syncthreads();
;     __device__ __forceinline__ void operator()(const f32x4 (&acc)[4][4], int m0, int n0, int wr, int wc, int fr, int fq, char*) const {
;     ...
;             const int row = m0 + wr * 64 + m * 16 + fr;
;             float ss = 0.f;
; #pragma unroll
;             for (int n = 0; n < 4; ++n) { const f32x4 v = acc[m][n]; ss += v[0] * v[0] + v[1] * v[1] + v[2] * v[2] + v[3] * v[3]; }
; #pragma unroll
;             for (int g = 0; g < 2; ++g) {
;                 const int col = n0 + wc * 64 + g * 32 + fq * 8;
;                 if (col < INC) {
;                     const f32x4 v0 = acc[m][2 * g], v1 = acc[m][2 * g + 1];
;                     uint4 w; w.x = pack2bf(v0[0], v0[1]); w.y = pack2bf(v0[2], v0[3]); w.z = pack2bf(v1[0], v1[1]); w.w = pack2bf(v1[2], v1[3]);
;                     bf16_t* dst;
.Ljoin_g697:
	s_add_u32 s0, s0, 0x80
	s_addc_u32 s1, s1, 0
	s_add_i32 s31, s31, 0x8000
	s_cmpk_eq_i32 s0, 0x780
	s_waitcnt vmcnt(8)
	s_barrier
	s_cbranch_scc0 .LBB0_697
	ds_read_b128 v[64:67], v89 offset:55296
	ds_read_b128 v[68:71], v89 offset:53248
	ds_read_b128 v[72:75], v89 offset:51200
	ds_read_b128 v[76:79], v89 offset:49152
	ds_read_b128 v[90:93], v88 offset:38912
	ds_read_b128 v[94:97], v88 offset:36864
	ds_read_b128 v[98:101], v88 offset:34816
	ds_read_b128 v[114:117], v88 offset:32768
	ds_read_b128 v[118:121], v87 offset:32768
	ds_read_b128 v[122:125], v87 offset:34816
	ds_read_b128 v[126:129], v87 offset:36864
	ds_read_b128 v[130:133], v87 offset:38912
	ds_read_b128 v[134:137], v86 offset:49152
	ds_read_b128 v[138:141], v86 offset:51200
	ds_read_b128 v[142:145], v86 offset:53248
	ds_read_b128 v[86:89], v86 offset:55296
	s_setprio 1
	s_waitcnt lgkmcnt(8)
	v_mfma_f32_16x16x32_bf16 v[36:39], v[76:79], v[114:117], v[36:39]
	v_mfma_f32_16x16x32_bf16 v[24:27], v[72:75], v[114:117], v[24:27]
	v_mfma_f32_16x16x32_bf16 v[20:23], v[68:71], v[114:117], v[20:23]
	v_mfma_f32_16x16x32_bf16 v[16:19], v[64:67], v[114:117], v[16:19]
	v_mfma_f32_16x16x32_bf16 v[12:15], v[76:79], v[98:101], v[12:15]
	v_mfma_f32_16x16x32_bf16 v[8:11], v[72:75], v[98:101], v[8:11]
	v_mfma_f32_16x16x32_bf16 v[4:7], v[68:71], v[98:101], v[4:7]
	v_mfma_f32_16x16x32_bf16 v[0:3], v[64:67], v[98:101], v[0:3]
	v_mfma_f32_16x16x32_bf16 v[28:31], v[76:79], v[94:97], v[28:31]
	v_mfma_f32_16x16x32_bf16 v[98:101], v[72:75], v[94:97], v[32:35]
	v_mfma_f32_16x16x32_bf16 v[114:117], v[68:71], v[94:97], v[40:43]
	v_mfma_f32_16x16x32_bf16 v[94:97], v[64:67], v[94:97], v[44:47]
	v_mfma_f32_16x16x32_bf16 v[72:75], v[72:75], v[90:93], v[52:55]
	v_mfma_f32_16x16x32_bf16 v[68:71], v[68:71], v[90:93], v[56:59]
	v_mfma_f32_16x16x32_bf16 v[64:67], v[64:67], v[90:93], v[60:63]
	v_mfma_f32_16x16x32_bf16 v[76:79], v[76:79], v[90:93], v[48:51]
	s_waitcnt lgkmcnt(3)
	v_mfma_f32_16x16x32_bf16 v[48:51], v[134:137], v[118:121], v[36:39]
	s_waitcnt lgkmcnt(2)
	v_mfma_f32_16x16x32_bf16 v[60:63], v[138:141], v[118:121], v[24:27]
	s_waitcnt lgkmcnt(1)
	v_mfma_f32_16x16x32_bf16 v[56:59], v[142:145], v[118:121], v[20:23]
	s_waitcnt lgkmcnt(0)
	v_mfma_f32_16x16x32_bf16 v[52:55], v[86:89], v[118:121], v[16:19]
	v_mfma_f32_16x16x32_bf16 v[32:35], v[134:137], v[122:125], v[12:15]
	v_mfma_f32_16x16x32_bf16 v[44:47], v[138:141], v[122:125], v[8:11]
	v_mfma_f32_16x16x32_bf16 v[40:43], v[142:145], v[122:125], v[4:7]
	v_mfma_f32_16x16x32_bf16 v[36:39], v[86:89], v[122:125], v[0:3]
	v_mfma_f32_16x16x32_bf16 v[16:19], v[134:137], v[126:129], v[28:31]
	v_mfma_f32_16x16x32_bf16 v[28:31], v[138:141], v[126:129], v[98:101]
	v_mfma_f32_16x16x32_bf16 v[24:27], v[142:145], v[126:129], v[114:117]
	v_mfma_f32_16x16x32_bf16 v[20:23], v[86:89], v[126:129], v[94:97]
	v_mfma_f32_16x16x32_bf16 v[0:3], v[134:137], v[130:133], v[76:79]
	v_mfma_f32_16x16x32_bf16 v[12:15], v[138:141], v[130:133], v[72:75]
	v_mfma_f32_16x16x32_bf16 v[8:11], v[142:145], v[130:133], v[68:71]
	v_mfma_f32_16x16x32_bf16 v[4:7], v[86:89], v[130:133], v[64:67]
	s_setprio 0
	s_nop 1
	v_or_b32_e32 v64, s30, v83
	v_lshl_add_u32 v73, v82, 6, v64
	s_movk_i32 s0, 0x620
	v_mad_i64_i32 v[66:67], s[0:1], v73, s0, 0
	v_lshlrev_b32_e32 v64, 6, v80
	v_lshlrev_b32_e32 v65, 3, v84
	s_movk_i32 s0, 0x640
	s_waitcnt vmcnt(0)
	v_or3_b32 v104, v64, v65, s42
	v_mad_i64_i32 v[64:65], s[0:1], v73, s0, 0
	v_mad_i64_i32 v[68:69], s[0:1], v73, s33, 0
	s_movk_i32 s0, 0xab0
	s_nop 0
	v_cmp_gt_i32_e64 s[44:45], s0, v104
	s_barrier
	s_and_saveexec_b64 s[0:1], s[44:45]
	s_movk_i32 s6, 0x47f
	s_cbranch_execz .LBB0_708
	v_cmp_lt_i32_e32 vcc, s6, v104
	s_and_saveexec_b64 s[30:31], vcc
	s_xor_b64 s[34:35], exec, s[30:31]
	s_cbranch_execz .LBB0_705
	s_movk_i32 s4, 0x79f
	v_cmp_lt_u32_e32 vcc, s4, v104
	s_and_saveexec_b64 s[30:31], vcc
	s_xor_b64 s[30:31], exec, s[30:31]
	s_cbranch_execz .LBB0_702
	v_readlane_b32 s4, v252, 2
	v_readlane_b32 s5, v252, 3
	s_nop 1
	v_lshl_add_u64 v[70:71], s[4:5], 0, v[66:67]
	s_movk_i32 s4, 0xf0c0
	v_lshl_add_u64 v[70:71], v[104:105], 1, v[70:71]
	s_mov_b32 s5, -1
	v_lshl_add_u64 v[70:71], v[70:71], 0, s[4:5]

; __global__ void __launch_bounds__(NTHR, 2) fwd_kernel(Params p, int ph_lo, int ph_hi) {
;     __shared__ __attribute__((aligned(16))) char smem[65536];
	.amdhsa_kernel _Z10fwd_kernel6Paramsii
		.amdhsa_group_segment_fixed_size 65556
		.amdhsa_private_segment_fixed_size 0
		.amdhsa_kernarg_size 552
		.amdhsa_user_sgpr_count 2
		.amdhsa_user_sgpr_dispatch_ptr 0
		.amdhsa_user_sgpr_queue_ptr 0
		.amdhsa_user_sgpr_kernarg_segment_ptr 1
		.amdhsa_user_sgpr_dispatch_id 0
		.amdhsa_user_sgpr_kernarg_preload_length 0
		.amdhsa_user_sgpr_kernarg_preload_offset 0
		.amdhsa_user_sgpr_private_segment_size 0
		.amdhsa_uses_dynamic_stack 0
		.amdhsa_enable_private_segment 0
		.amdhsa_system_sgpr_workgroup_id_x 1
		.amdhsa_system_sgpr_workgroup_id_y 0
		.amdhsa_system_sgpr_workgroup_id_z 0
		.amdhsa_system_sgpr_workgroup_info 0
		.amdhsa_system_vgpr_workitem_id 2
		.amdhsa_next_free_vgpr 256
		.amdhsa_next_free_sgpr 102
		.amdhsa_accum_offset 256
		.amdhsa_reserve_vcc 1
		.amdhsa_float_round_mode_32 0
		.amdhsa_float_round_mode_16_64 0
		.amdhsa_float_denorm_mode_32 3
		.amdhsa_float_denorm_mode_16_64 3
		.amdhsa_dx10_clamp 1
		.amdhsa_ieee_mode 1
		.amdhsa_fp16_overflow 0
		.amdhsa_tg_split 0
		.amdhsa_exception_fp_ieee_invalid_op 0
		.amdhsa_exception_fp_denorm_src 0
		.amdhsa_exception_fp_ieee_div_zero 0
		.amdhsa_exception_fp_ieee_overflow 0
		.amdhsa_exception_fp_ieee_underflow 0
		.amdhsa_exception_fp_ieee_inexact 0
		.amdhsa_exception_int_div_zero 0
	.end_amdhsa_kernel

; __global__ void __launch_bounds__(NTHR, 2) fwd_kernel(Params p, int ph_lo, int ph_hi) {
;     __shared__ __attribute__((aligned(16))) char smem[65536];
amdhsa.kernels:
  - .agpr_count:     0
    .args:
      - .offset:         0
        .size:           288
        .value_kind:     by_value
      - .offset:         288
        .size:           4
        .value_kind:     by_value
      - .offset:         292
        .size:           4
        .value_kind:     by_value
      - .offset:         296
        .size:           4
        .value_kind:     hidden_block_count_x
      - .offset:         300
        .size:           4
        .value_kind:     hidden_block_count_y
      - .offset:         304
        .size:           4
        .value_kind:     hidden_block_count_z
      - .offset:         308
        .size:           2
        .value_kind:     hidden_group_size_x
      - .offset:         310
        .size:           2
        .value_kind:     hidden_group_size_y
      - .offset:         312
        .size:           2
        .value_kind:     hidden_group_size_z
      - .offset:         314
        .size:           2
        .value_kind:     hidden_remainder_x
      - .offset:         316
        .size:           2
        .value_kind:     hidden_remainder_y
      - .offset:         318
        .size:           2
        .value_kind:     hidden_remainder_z
      - .offset:         336
        .size:           8
        .value_kind:     hidden_global_offset_x
      - .offset:         344
        .size:           8
        .value_kind:     hidden_global_offset_y
      - .offset:         352
        .size:           8
        .value_kind:     hidden_global_offset_z
      - .offset:         360
        .size:           2
        .value_kind:     hidden_grid_dims
      - .offset:         384
        .size:           8
        .value_kind:     hidden_multigrid_sync_arg
    .group_segment_fixed_size: 65556
    .kernarg_segment_align: 8
    .kernarg_segment_size: 552
    .language:       OpenCL C
    .language_version:
      - 2
      - 0
    .max_flat_workgroup_size: 256
    .name:           _Z10fwd_kernel6Paramsii
    .private_segment_fixed_size: 0
    .sgpr_count:     108
    .sgpr_spill_count: 351
    .symbol:         _Z10fwd_kernel6Paramsii.kd
    .uniform_work_group_size: 1
    .uses_dynamic_stack: false
    .vgpr_count:     256
    .vgpr_spill_count: 0
    .wavefront_size: 64
